# GEMM K-loops: duplicate lgkmcnt(0) after the template's own wait removed; M0 wait-state nop replaced by placing the address add between the M0 write and the LDS-DMA load
# speedup vs baseline: 1.0101x; 1.0044x over previous
.LBB0_122:
	v_mov_b64_e32 v[0:1], 0x180
	s_ashr_i32 s15, s14, 31
	v_cmp_lt_i64_e32 vcc, s[16:17], v[0:1]
	s_lshl_b64 s[16:17], s[14:15], 19
	s_add_u32 s16, s30, s16
	s_addc_u32 s17, s31, s17
	s_and_b64 s[18:19], vcc, exec
	s_cselect_b32 s7, s17, s21
	s_cselect_b32 s9, s16, s20
	s_ashr_i32 s13, s12, 31
	s_lshl_b64 s[18:19], s[12:13], 19
	s_add_u32 s18, s34, s18
	s_addc_u32 s19, s35, s19
	s_and_b64 s[22:23], vcc, exec
	s_cselect_b32 s13, s19, s3
	s_cselect_b32 s15, s18, s2
	s_add_u32 s20, s20, 0x40080
	s_addc_u32 s21, s21, 0
	s_add_u32 s50, s2, 0x100
	s_addc_u32 s51, s3, 0
	s_mov_b32 s52, -2
	s_add_u32 s2, s20, 0xfffc0080
	s_addc_u32 s3, s21, -1
	s_add_i32 s53, 0, 0x10000
	v_add_u32_e32 v36, s53, v164
	ds_read_b128 v[24:27], v36
	ds_read_b128 v[28:31], v36 offset:1024
	ds_read_b128 v[32:35], v36 offset:2048
	ds_read_b128 v[36:39], v36 offset:3072
	s_cmp_eq_u32 s52, 12
	s_cselect_b32 s23, s7, s3
	s_cselect_b32 s22, s9, s2
	s_cselect_b32 s3, s13, s51
	s_cselect_b32 s2, s15, s50
	v_lshl_add_u64 v[166:167], s[20:21], 0, v[150:151]
	s_add_i32 m0, s37, 0xc000
	ds_read_b128 v[154:157], v165
	ds_read_b128 v[158:161], v165 offset:1024
	ds_read_b128 v[180:183], v165 offset:2048
	ds_read_b128 v[184:187], v165 offset:3072
	ds_read_b128 v[188:191], v165 offset:4096
	ds_read_b128 v[192:195], v165 offset:5120
	ds_read_b128 v[196:199], v165 offset:6144
	ds_read_b128 v[200:203], v165 offset:7168
	global_load_lds_dwordx4 v[166:167], off
	s_add_i32 m0, s37, 0xe000
	v_lshl_add_u64 v[166:167], s[20:21], 0, v[152:153]
	global_load_lds_dwordx4 v[166:167], off
	s_waitcnt lgkmcnt(8)
	s_barrier
	s_waitcnt lgkmcnt(0)
	s_setprio 1
	v_mfma_f32_16x16x32_bf16 v[140:143], v[24:27], v[154:157], 0
	v_mfma_f32_16x16x32_bf16 v[136:139], v[32:35], v[154:157], 0
	v_mfma_f32_16x16x32_bf16 v[124:127], v[24:27], v[180:183], 0
	v_mfma_f32_16x16x32_bf16 v[120:123], v[32:35], v[180:183], 0
	v_mfma_f32_16x16x32_bf16 v[108:111], v[24:27], v[188:191], 0
	v_mfma_f32_16x16x32_bf16 v[104:107], v[32:35], v[188:191], 0
	v_mfma_f32_16x16x32_bf16 v[92:95], v[24:27], v[196:199], 0
	v_mfma_f32_16x16x32_bf16 v[88:91], v[32:35], v[196:199], 0
	v_mfma_f32_16x16x32_bf16 v[140:143], v[28:31], v[158:161], v[140:143]
	v_mfma_f32_16x16x32_bf16 v[136:139], v[36:39], v[158:161], v[136:139]
	v_mfma_f32_16x16x32_bf16 v[124:127], v[28:31], v[184:187], v[124:127]
	v_mfma_f32_16x16x32_bf16 v[120:123], v[36:39], v[184:187], v[120:123]
	v_mfma_f32_16x16x32_bf16 v[108:111], v[28:31], v[192:195], v[108:111]
	v_mfma_f32_16x16x32_bf16 v[104:107], v[36:39], v[192:195], v[104:107]
	v_mfma_f32_16x16x32_bf16 v[92:95], v[28:31], v[200:203], v[92:95]
	v_mfma_f32_16x16x32_bf16 v[88:91], v[36:39], v[200:203], v[88:91]
	s_setprio 0
	s_barrier
	s_add_i32 s56, 0, 0x14000
	v_add_u32_e32 v166, s56, v164
	s_add_i32 s53, s53, s36
	ds_read_b128 v[204:207], v166
	ds_read_b128 v[208:211], v166 offset:1024
	ds_read_b128 v[212:215], v166 offset:2048
	ds_read_b128 v[216:219], v166 offset:3072
	v_lshl_add_u64 v[166:167], s[2:3], 0, v[168:169]
	s_mov_b32 m0, s53
	v_lshl_add_u64 v[220:221], s[2:3], 0, v[148:149]
	global_load_lds_dwordx4 v[166:167], off
	s_add_i32 m0, s53, 0x2000
	s_nop 0
	global_load_lds_dwordx4 v[220:221], off
	s_barrier
	s_waitcnt lgkmcnt(0)
	s_setprio 1
	v_mfma_f32_16x16x32_bf16 v[132:135], v[204:207], v[154:157], 0
	v_mfma_f32_16x16x32_bf16 v[128:131], v[212:215], v[154:157], 0
	v_mfma_f32_16x16x32_bf16 v[116:119], v[204:207], v[180:183], 0
	v_mfma_f32_16x16x32_bf16 v[112:115], v[212:215], v[180:183], 0
	v_mfma_f32_16x16x32_bf16 v[100:103], v[204:207], v[188:191], 0
	v_mfma_f32_16x16x32_bf16 v[96:99], v[212:215], v[188:191], 0
	v_mfma_f32_16x16x32_bf16 v[84:87], v[204:207], v[196:199], 0
	v_mfma_f32_16x16x32_bf16 v[80:83], v[212:215], v[196:199], 0
	v_mfma_f32_16x16x32_bf16 v[132:135], v[208:211], v[158:161], v[132:135]
	v_mfma_f32_16x16x32_bf16 v[128:131], v[216:219], v[158:161], v[128:131]
	v_mfma_f32_16x16x32_bf16 v[116:119], v[208:211], v[184:187], v[116:119]
	v_mfma_f32_16x16x32_bf16 v[112:115], v[216:219], v[184:187], v[112:115]
	v_mfma_f32_16x16x32_bf16 v[100:103], v[208:211], v[192:195], v[100:103]
	v_mfma_f32_16x16x32_bf16 v[96:99], v[216:219], v[192:195], v[96:99]
	v_mfma_f32_16x16x32_bf16 v[84:87], v[208:211], v[200:203], v[84:87]
	v_mfma_f32_16x16x32_bf16 v[80:83], v[216:219], v[200:203], v[80:83]
	s_setprio 0
	s_mov_b32 m0, s37
	v_lshl_add_u64 v[222:223], s[22:23], 0, v[144:145]
	s_barrier
	ds_read_b128 v[154:157], v165 offset:16384
	ds_read_b128 v[158:161], v165 offset:17408
	ds_read_b128 v[180:183], v165 offset:18432
	ds_read_b128 v[184:187], v165 offset:19456
	ds_read_b128 v[188:191], v165 offset:20480
	ds_read_b128 v[192:195], v165 offset:21504
	ds_read_b128 v[196:199], v165 offset:22528
	ds_read_b128 v[200:203], v165 offset:23552
	global_load_lds_dwordx4 v[222:223], off
	s_mov_b32 m0, s38
	v_lshl_add_u64 v[236:237], s[22:23], 0, v[146:147]
	global_load_lds_dwordx4 v[236:237], off
	s_barrier
	s_waitcnt lgkmcnt(0)
	s_setprio 1
	v_mfma_f32_16x16x32_bf16 v[76:79], v[24:27], v[154:157], 0
	v_mfma_f32_16x16x32_bf16 v[72:75], v[32:35], v[154:157], 0
	v_mfma_f32_16x16x32_bf16 v[60:63], v[24:27], v[180:183], 0
	v_mfma_f32_16x16x32_bf16 v[56:59], v[32:35], v[180:183], 0
	v_mfma_f32_16x16x32_bf16 v[44:47], v[24:27], v[188:191], 0
	v_mfma_f32_16x16x32_bf16 v[40:43], v[32:35], v[188:191], 0
	v_mfma_f32_16x16x32_bf16 v[12:15], v[24:27], v[196:199], 0
	v_mfma_f32_16x16x32_bf16 v[8:11], v[32:35], v[196:199], 0
	v_mfma_f32_16x16x32_bf16 v[76:79], v[28:31], v[158:161], v[76:79]
	v_mfma_f32_16x16x32_bf16 v[72:75], v[36:39], v[158:161], v[72:75]
	v_mfma_f32_16x16x32_bf16 v[60:63], v[28:31], v[184:187], v[60:63]
	v_mfma_f32_16x16x32_bf16 v[56:59], v[36:39], v[184:187], v[56:59]
	v_mfma_f32_16x16x32_bf16 v[44:47], v[28:31], v[192:195], v[44:47]
	v_mfma_f32_16x16x32_bf16 v[40:43], v[36:39], v[192:195], v[40:43]
	v_mfma_f32_16x16x32_bf16 v[12:15], v[28:31], v[200:203], v[12:15]
	v_mfma_f32_16x16x32_bf16 v[8:11], v[36:39], v[200:203], v[8:11]
	s_setprio 0
	s_barrier
	s_add_u32 s54, s2, 0x40000
	s_addc_u32 s55, s3, 0
	s_add_i32 s53, s56, s36
	s_mov_b32 m0, s53
	v_lshl_add_u64 v[24:25], s[54:55], 0, v[168:169]
	global_load_lds_dwordx4 v[24:25], off
	s_add_i32 m0, s53, 0x2000
	v_lshl_add_u64 v[24:25], s[54:55], 0, v[148:149]
	global_load_lds_dwordx4 v[24:25], off
	s_waitcnt vmcnt(6)
	s_barrier
	s_setprio 1
	v_mfma_f32_16x16x32_bf16 v[20:23], v[204:207], v[188:191], 0
	v_mfma_f32_16x16x32_bf16 v[16:19], v[212:215], v[188:191], 0
	v_mfma_f32_16x16x32_bf16 v[4:7], v[204:207], v[196:199], 0
	v_mfma_f32_16x16x32_bf16 v[0:3], v[212:215], v[196:199], 0
	v_mfma_f32_16x16x32_bf16 v[24:27], v[204:207], v[154:157], 0
	v_mfma_f32_16x16x32_bf16 v[28:31], v[212:215], v[154:157], 0
	v_mfma_f32_16x16x32_bf16 v[32:35], v[204:207], v[180:183], 0
	v_mfma_f32_16x16x32_bf16 v[36:39], v[212:215], v[180:183], 0
	v_mfma_f32_16x16x32_bf16 v[20:23], v[208:211], v[192:195], v[20:23]
	v_mfma_f32_16x16x32_bf16 v[16:19], v[216:219], v[192:195], v[16:19]
	v_mfma_f32_16x16x32_bf16 v[4:7], v[208:211], v[200:203], v[4:7]
	v_mfma_f32_16x16x32_bf16 v[0:3], v[216:219], v[200:203], v[0:3]
	v_mfma_f32_16x16x32_bf16 v[24:27], v[208:211], v[158:161], v[24:27]
	v_mfma_f32_16x16x32_bf16 v[28:31], v[216:219], v[158:161], v[28:31]
	v_mfma_f32_16x16x32_bf16 v[32:35], v[208:211], v[184:187], v[32:35]
	v_mfma_f32_16x16x32_bf16 v[36:39], v[216:219], v[184:187], v[36:39]
	s_setprio 0
	s_add_i32 s53, 0, 0x18000
	v_add_u32_e32 v68, s53, v164
	s_barrier
	ds_read_b128 v[48:51], v68
	ds_read_b128 v[52:55], v68 offset:1024
	ds_read_b128 v[64:67], v68 offset:2048
	ds_read_b128 v[68:71], v68 offset:3072
	s_add_u32 s22, s22, 0x40000
	s_addc_u32 s23, s23, 0
	s_mov_b32 m0, s39
	v_lshl_add_u64 v[204:205], s[22:23], 0, v[144:145]
	ds_read_b128 v[154:157], v165 offset:32768
	ds_read_b128 v[158:161], v165 offset:33792
	ds_read_b128 v[180:183], v165 offset:34816
	ds_read_b128 v[184:187], v165 offset:35840
	ds_read_b128 v[188:191], v165 offset:36864
	ds_read_b128 v[192:195], v165 offset:37888
	ds_read_b128 v[196:199], v165 offset:38912
	ds_read_b128 v[200:203], v165 offset:39936
	global_load_lds_dwordx4 v[204:205], off
	s_mov_b32 m0, s40
	v_lshl_add_u64 v[204:205], s[22:23], 0, v[146:147]
	global_load_lds_dwordx4 v[204:205], off
	s_waitcnt lgkmcnt(8)
	s_barrier
	s_waitcnt lgkmcnt(0)
	s_setprio 1
	v_mfma_f32_16x16x32_bf16 v[140:143], v[48:51], v[154:157], v[140:143]
	v_mfma_f32_16x16x32_bf16 v[136:139], v[64:67], v[154:157], v[136:139]
	v_mfma_f32_16x16x32_bf16 v[124:127], v[48:51], v[180:183], v[124:127]
	v_mfma_f32_16x16x32_bf16 v[120:123], v[64:67], v[180:183], v[120:123]
	v_mfma_f32_16x16x32_bf16 v[108:111], v[48:51], v[188:191], v[108:111]
	v_mfma_f32_16x16x32_bf16 v[104:107], v[64:67], v[188:191], v[104:107]
	v_mfma_f32_16x16x32_bf16 v[92:95], v[48:51], v[196:199], v[92:95]
	v_mfma_f32_16x16x32_bf16 v[88:91], v[64:67], v[196:199], v[88:91]
	v_mfma_f32_16x16x32_bf16 v[140:143], v[52:55], v[158:161], v[140:143]
	v_mfma_f32_16x16x32_bf16 v[136:139], v[68:71], v[158:161], v[136:139]
	v_mfma_f32_16x16x32_bf16 v[124:127], v[52:55], v[184:187], v[124:127]
	v_mfma_f32_16x16x32_bf16 v[120:123], v[68:71], v[184:187], v[120:123]
	v_mfma_f32_16x16x32_bf16 v[108:111], v[52:55], v[192:195], v[108:111]
	v_mfma_f32_16x16x32_bf16 v[104:107], v[68:71], v[192:195], v[104:107]
	v_mfma_f32_16x16x32_bf16 v[92:95], v[52:55], v[200:203], v[92:95]
	v_mfma_f32_16x16x32_bf16 v[88:91], v[68:71], v[200:203], v[88:91]
	s_setprio 0
	s_barrier
	s_add_i32 s22, 0, 0x1c000
	s_add_i32 s23, s53, s36
	v_add_u32_e32 v216, s22, v164
	v_lshl_add_u64 v[166:167], v[166:167], 0, s[78:79]
	s_mov_b32 m0, s23
	ds_read_b128 v[204:207], v216
	ds_read_b128 v[208:211], v216 offset:1024
	ds_read_b128 v[212:215], v216 offset:2048
	ds_read_b128 v[216:219], v216 offset:3072
	global_load_lds_dwordx4 v[166:167], off
	s_add_i32 m0, s23, 0x2000
	v_lshl_add_u64 v[166:167], v[220:221], 0, s[78:79]
	global_load_lds_dwordx4 v[166:167], off
	s_barrier
	s_waitcnt lgkmcnt(0)
	s_setprio 1
	v_mfma_f32_16x16x32_bf16 v[132:135], v[204:207], v[154:157], v[132:135]
	v_mfma_f32_16x16x32_bf16 v[128:131], v[212:215], v[154:157], v[128:131]
	v_mfma_f32_16x16x32_bf16 v[116:119], v[204:207], v[180:183], v[116:119]
	v_mfma_f32_16x16x32_bf16 v[112:115], v[212:215], v[180:183], v[112:115]
	v_mfma_f32_16x16x32_bf16 v[100:103], v[204:207], v[188:191], v[100:103]
	v_mfma_f32_16x16x32_bf16 v[96:99], v[212:215], v[188:191], v[96:99]
	v_mfma_f32_16x16x32_bf16 v[84:87], v[204:207], v[196:199], v[84:87]
	v_mfma_f32_16x16x32_bf16 v[80:83], v[212:215], v[196:199], v[80:83]
	v_mfma_f32_16x16x32_bf16 v[132:135], v[208:211], v[158:161], v[132:135]
	v_mfma_f32_16x16x32_bf16 v[128:131], v[216:219], v[158:161], v[128:131]
	v_mfma_f32_16x16x32_bf16 v[116:119], v[208:211], v[184:187], v[116:119]
	v_mfma_f32_16x16x32_bf16 v[112:115], v[216:219], v[184:187], v[112:115]
	v_mfma_f32_16x16x32_bf16 v[100:103], v[208:211], v[192:195], v[100:103]
	v_mfma_f32_16x16x32_bf16 v[96:99], v[216:219], v[192:195], v[96:99]
	v_mfma_f32_16x16x32_bf16 v[84:87], v[208:211], v[200:203], v[84:87]
	v_mfma_f32_16x16x32_bf16 v[80:83], v[216:219], v[200:203], v[80:83]
	s_setprio 0
	s_mov_b32 m0, s45
	v_lshl_add_u64 v[166:167], v[222:223], 0, s[78:79]
	s_barrier
	ds_read_b128 v[154:157], v165 offset:49152
	ds_read_b128 v[158:161], v165 offset:50176
	ds_read_b128 v[180:183], v165 offset:51200
	ds_read_b128 v[184:187], v165 offset:52224
	ds_read_b128 v[188:191], v165 offset:53248
	ds_read_b128 v[192:195], v165 offset:54272
	ds_read_b128 v[196:199], v165 offset:55296
	ds_read_b128 v[200:203], v165 offset:56320
	global_load_lds_dwordx4 v[166:167], off
	s_mov_b32 m0, s46
	v_lshl_add_u64 v[166:167], v[236:237], 0, s[78:79]
	global_load_lds_dwordx4 v[166:167], off
	s_barrier
	s_waitcnt lgkmcnt(0)
	s_setprio 1
	v_mfma_f32_16x16x32_bf16 v[76:79], v[48:51], v[154:157], v[76:79]
	v_mfma_f32_16x16x32_bf16 v[72:75], v[64:67], v[154:157], v[72:75]
	v_mfma_f32_16x16x32_bf16 v[60:63], v[48:51], v[180:183], v[60:63]
	v_mfma_f32_16x16x32_bf16 v[56:59], v[64:67], v[180:183], v[56:59]
	v_mfma_f32_16x16x32_bf16 v[44:47], v[48:51], v[188:191], v[44:47]
	v_mfma_f32_16x16x32_bf16 v[40:43], v[64:67], v[188:191], v[40:43]
	v_mfma_f32_16x16x32_bf16 v[12:15], v[48:51], v[196:199], v[12:15]
	v_mfma_f32_16x16x32_bf16 v[8:11], v[64:67], v[196:199], v[8:11]
	v_mfma_f32_16x16x32_bf16 v[76:79], v[52:55], v[158:161], v[76:79]
	v_mfma_f32_16x16x32_bf16 v[72:75], v[68:71], v[158:161], v[72:75]
	v_mfma_f32_16x16x32_bf16 v[60:63], v[52:55], v[184:187], v[60:63]
	v_mfma_f32_16x16x32_bf16 v[56:59], v[68:71], v[184:187], v[56:59]
	v_mfma_f32_16x16x32_bf16 v[44:47], v[52:55], v[192:195], v[44:47]
	v_mfma_f32_16x16x32_bf16 v[40:43], v[68:71], v[192:195], v[40:43]
	v_mfma_f32_16x16x32_bf16 v[12:15], v[52:55], v[200:203], v[12:15]
	v_mfma_f32_16x16x32_bf16 v[8:11], v[68:71], v[200:203], v[8:11]
	s_setprio 0
	s_barrier
	s_add_u32 s2, s2, 0x40080
	s_addc_u32 s3, s3, 0
	s_add_i32 s22, s22, s36
	s_mov_b32 m0, s22
	v_lshl_add_u64 v[48:49], s[2:3], 0, v[168:169]
	global_load_lds_dwordx4 v[48:49], off
	s_add_i32 m0, s22, 0x2000
	v_lshl_add_u64 v[48:49], s[2:3], 0, v[148:149]
	global_load_lds_dwordx4 v[48:49], off
	s_waitcnt vmcnt(6)
	s_barrier
	s_setprio 1
	v_mfma_f32_16x16x32_bf16 v[24:27], v[204:207], v[154:157], v[24:27]
	v_mfma_f32_16x16x32_bf16 v[68:71], v[208:211], v[158:161], v[24:27]
	v_mfma_f32_16x16x32_bf16 v[24:27], v[212:215], v[154:157], v[28:31]
	v_mfma_f32_16x16x32_bf16 v[64:67], v[216:219], v[158:161], v[24:27]
	v_mfma_f32_16x16x32_bf16 v[24:27], v[204:207], v[180:183], v[32:35]
	v_mfma_f32_16x16x32_bf16 v[52:55], v[208:211], v[184:187], v[24:27]
	v_mfma_f32_16x16x32_bf16 v[24:27], v[212:215], v[180:183], v[36:39]
	v_mfma_f32_16x16x32_bf16 v[20:23], v[204:207], v[188:191], v[20:23]
	v_mfma_f32_16x16x32_bf16 v[16:19], v[212:215], v[188:191], v[16:19]
	v_mfma_f32_16x16x32_bf16 v[4:7], v[204:207], v[196:199], v[4:7]
	v_mfma_f32_16x16x32_bf16 v[0:3], v[212:215], v[196:199], v[0:3]
	v_mfma_f32_16x16x32_bf16 v[48:51], v[216:219], v[184:187], v[24:27]
	v_mfma_f32_16x16x32_bf16 v[20:23], v[208:211], v[192:195], v[20:23]
	v_mfma_f32_16x16x32_bf16 v[16:19], v[216:219], v[192:195], v[16:19]
	v_mfma_f32_16x16x32_bf16 v[4:7], v[208:211], v[200:203], v[4:7]
	v_mfma_f32_16x16x32_bf16 v[0:3], v[216:219], v[200:203], v[0:3]
	s_setprio 0
	s_add_i32 s52, s52, 2
	s_add_u32 s20, s20, 0x100
	s_addc_u32 s21, s21, 0
	s_add_u32 s50, s50, 0x100
	s_addc_u32 s51, s51, 0
	s_cmp_gt_u32 s52, 13
	s_barrier
.LBB0_123:
	s_add_u32 s2, s20, 0xfffc0080
	s_addc_u32 s3, s21, -1
	s_add_i32 s53, 0, 0x10000
	v_add_u32_e32 v36, s53, v164
	ds_read_b128 v[24:27], v36
	ds_read_b128 v[28:31], v36 offset:1024
	ds_read_b128 v[32:35], v36 offset:2048
	ds_read_b128 v[36:39], v36 offset:3072
	s_cmp_eq_u32 s52, 12
	s_cselect_b32 s23, s7, s3
	s_cselect_b32 s22, s9, s2
	s_cselect_b32 s3, s13, s51
	s_cselect_b32 s2, s15, s50
	v_lshl_add_u64 v[166:167], s[20:21], 0, v[150:151]
	s_add_i32 m0, s37, 0xc000
	ds_read_b128 v[154:157], v165
	ds_read_b128 v[158:161], v165 offset:1024
	ds_read_b128 v[180:183], v165 offset:2048
	ds_read_b128 v[184:187], v165 offset:3072
	ds_read_b128 v[188:191], v165 offset:4096
	ds_read_b128 v[192:195], v165 offset:5120
	ds_read_b128 v[196:199], v165 offset:6144
	ds_read_b128 v[200:203], v165 offset:7168
	global_load_lds_dwordx4 v[166:167], off
	s_add_i32 m0, s37, 0xe000
	v_lshl_add_u64 v[166:167], s[20:21], 0, v[152:153]
	global_load_lds_dwordx4 v[166:167], off
	s_waitcnt lgkmcnt(8)
	s_barrier
	s_waitcnt lgkmcnt(0)
	s_setprio 1
	v_mfma_f32_16x16x32_bf16 v[140:143], v[24:27], v[154:157], v[140:143]
	v_mfma_f32_16x16x32_bf16 v[136:139], v[32:35], v[154:157], v[136:139]
	v_mfma_f32_16x16x32_bf16 v[124:127], v[24:27], v[180:183], v[124:127]
	v_mfma_f32_16x16x32_bf16 v[120:123], v[32:35], v[180:183], v[120:123]
	v_mfma_f32_16x16x32_bf16 v[108:111], v[24:27], v[188:191], v[108:111]
	v_mfma_f32_16x16x32_bf16 v[104:107], v[32:35], v[188:191], v[104:107]
	v_mfma_f32_16x16x32_bf16 v[92:95], v[24:27], v[196:199], v[92:95]
	v_mfma_f32_16x16x32_bf16 v[88:91], v[32:35], v[196:199], v[88:91]
	v_mfma_f32_16x16x32_bf16 v[140:143], v[28:31], v[158:161], v[140:143]
	v_mfma_f32_16x16x32_bf16 v[136:139], v[36:39], v[158:161], v[136:139]
	v_mfma_f32_16x16x32_bf16 v[124:127], v[28:31], v[184:187], v[124:127]
	v_mfma_f32_16x16x32_bf16 v[120:123], v[36:39], v[184:187], v[120:123]
	v_mfma_f32_16x16x32_bf16 v[108:111], v[28:31], v[192:195], v[108:111]
	v_mfma_f32_16x16x32_bf16 v[104:107], v[36:39], v[192:195], v[104:107]
	v_mfma_f32_16x16x32_bf16 v[92:95], v[28:31], v[200:203], v[92:95]
	v_mfma_f32_16x16x32_bf16 v[88:91], v[36:39], v[200:203], v[88:91]
	s_setprio 0
	s_barrier
	s_add_i32 s56, 0, 0x14000
	v_add_u32_e32 v166, s56, v164
	s_add_i32 s53, s53, s36
	ds_read_b128 v[204:207], v166
	ds_read_b128 v[208:211], v166 offset:1024
	ds_read_b128 v[212:215], v166 offset:2048
	ds_read_b128 v[216:219], v166 offset:3072
	v_lshl_add_u64 v[166:167], s[2:3], 0, v[168:169]
	s_mov_b32 m0, s53
	v_lshl_add_u64 v[220:221], s[2:3], 0, v[148:149]
	global_load_lds_dwordx4 v[166:167], off
	s_add_i32 m0, s53, 0x2000
	s_nop 0
	global_load_lds_dwordx4 v[220:221], off
	s_barrier
	s_waitcnt lgkmcnt(0)
	s_setprio 1
	v_mfma_f32_16x16x32_bf16 v[132:135], v[204:207], v[154:157], v[132:135]
	v_mfma_f32_16x16x32_bf16 v[128:131], v[212:215], v[154:157], v[128:131]
	v_mfma_f32_16x16x32_bf16 v[116:119], v[204:207], v[180:183], v[116:119]
	v_mfma_f32_16x16x32_bf16 v[112:115], v[212:215], v[180:183], v[112:115]
	v_mfma_f32_16x16x32_bf16 v[100:103], v[204:207], v[188:191], v[100:103]
	v_mfma_f32_16x16x32_bf16 v[96:99], v[212:215], v[188:191], v[96:99]
	v_mfma_f32_16x16x32_bf16 v[84:87], v[204:207], v[196:199], v[84:87]
	v_mfma_f32_16x16x32_bf16 v[80:83], v[212:215], v[196:199], v[80:83]
	v_mfma_f32_16x16x32_bf16 v[132:135], v[208:211], v[158:161], v[132:135]
	v_mfma_f32_16x16x32_bf16 v[128:131], v[216:219], v[158:161], v[128:131]
	v_mfma_f32_16x16x32_bf16 v[116:119], v[208:211], v[184:187], v[116:119]
	v_mfma_f32_16x16x32_bf16 v[112:115], v[216:219], v[184:187], v[112:115]
	v_mfma_f32_16x16x32_bf16 v[100:103], v[208:211], v[192:195], v[100:103]
	v_mfma_f32_16x16x32_bf16 v[96:99], v[216:219], v[192:195], v[96:99]
	v_mfma_f32_16x16x32_bf16 v[84:87], v[208:211], v[200:203], v[84:87]
	v_mfma_f32_16x16x32_bf16 v[80:83], v[216:219], v[200:203], v[80:83]
	s_setprio 0
	s_mov_b32 m0, s37
	v_lshl_add_u64 v[222:223], s[22:23], 0, v[144:145]
	s_barrier
	ds_read_b128 v[154:157], v165 offset:16384
	ds_read_b128 v[158:161], v165 offset:17408
	ds_read_b128 v[180:183], v165 offset:18432
	ds_read_b128 v[184:187], v165 offset:19456
	ds_read_b128 v[188:191], v165 offset:20480
	ds_read_b128 v[192:195], v165 offset:21504
	ds_read_b128 v[196:199], v165 offset:22528
	ds_read_b128 v[200:203], v165 offset:23552
	global_load_lds_dwordx4 v[222:223], off
	s_mov_b32 m0, s38
	v_lshl_add_u64 v[236:237], s[22:23], 0, v[146:147]
	global_load_lds_dwordx4 v[236:237], off
	s_barrier
	s_waitcnt lgkmcnt(0)
	s_setprio 1
	v_mfma_f32_16x16x32_bf16 v[76:79], v[24:27], v[154:157], v[76:79]
	v_mfma_f32_16x16x32_bf16 v[72:75], v[32:35], v[154:157], v[72:75]
	v_mfma_f32_16x16x32_bf16 v[60:63], v[24:27], v[180:183], v[60:63]
	v_mfma_f32_16x16x32_bf16 v[56:59], v[32:35], v[180:183], v[56:59]
	v_mfma_f32_16x16x32_bf16 v[44:47], v[24:27], v[188:191], v[44:47]
	v_mfma_f32_16x16x32_bf16 v[40:43], v[32:35], v[188:191], v[40:43]
	v_mfma_f32_16x16x32_bf16 v[12:15], v[24:27], v[196:199], v[12:15]
	v_mfma_f32_16x16x32_bf16 v[8:11], v[32:35], v[196:199], v[8:11]
	v_mfma_f32_16x16x32_bf16 v[76:79], v[28:31], v[158:161], v[76:79]
	v_mfma_f32_16x16x32_bf16 v[72:75], v[36:39], v[158:161], v[72:75]
	v_mfma_f32_16x16x32_bf16 v[60:63], v[28:31], v[184:187], v[60:63]
	v_mfma_f32_16x16x32_bf16 v[56:59], v[36:39], v[184:187], v[56:59]
	v_mfma_f32_16x16x32_bf16 v[44:47], v[28:31], v[192:195], v[44:47]
	v_mfma_f32_16x16x32_bf16 v[40:43], v[36:39], v[192:195], v[40:43]
	v_mfma_f32_16x16x32_bf16 v[12:15], v[28:31], v[200:203], v[12:15]
	v_mfma_f32_16x16x32_bf16 v[8:11], v[36:39], v[200:203], v[8:11]
	s_setprio 0
	s_barrier
	s_add_u32 s54, s2, 0x40000
	s_addc_u32 s55, s3, 0
	s_add_i32 s53, s56, s36
	s_mov_b32 m0, s53
	v_lshl_add_u64 v[24:25], s[54:55], 0, v[168:169]
	global_load_lds_dwordx4 v[24:25], off
	s_add_i32 m0, s53, 0x2000
	v_lshl_add_u64 v[24:25], s[54:55], 0, v[148:149]
	global_load_lds_dwordx4 v[24:25], off
	s_waitcnt vmcnt(6)
	s_barrier
	s_setprio 1
	v_mfma_f32_16x16x32_bf16 v[20:23], v[204:207], v[188:191], v[20:23]
	v_mfma_f32_16x16x32_bf16 v[16:19], v[212:215], v[188:191], v[16:19]
	v_mfma_f32_16x16x32_bf16 v[4:7], v[204:207], v[196:199], v[4:7]
	v_mfma_f32_16x16x32_bf16 v[0:3], v[212:215], v[196:199], v[0:3]
	v_mfma_f32_16x16x32_bf16 v[24:27], v[204:207], v[154:157], v[68:71]
	v_mfma_f32_16x16x32_bf16 v[28:31], v[212:215], v[154:157], v[64:67]
	v_mfma_f32_16x16x32_bf16 v[32:35], v[204:207], v[180:183], v[52:55]
	v_mfma_f32_16x16x32_bf16 v[36:39], v[212:215], v[180:183], v[48:51]
	v_mfma_f32_16x16x32_bf16 v[20:23], v[208:211], v[192:195], v[20:23]
	v_mfma_f32_16x16x32_bf16 v[16:19], v[216:219], v[192:195], v[16:19]
	v_mfma_f32_16x16x32_bf16 v[4:7], v[208:211], v[200:203], v[4:7]
	v_mfma_f32_16x16x32_bf16 v[0:3], v[216:219], v[200:203], v[0:3]
	v_mfma_f32_16x16x32_bf16 v[24:27], v[208:211], v[158:161], v[24:27]
	v_mfma_f32_16x16x32_bf16 v[28:31], v[216:219], v[158:161], v[28:31]
	v_mfma_f32_16x16x32_bf16 v[32:35], v[208:211], v[184:187], v[32:35]
	v_mfma_f32_16x16x32_bf16 v[36:39], v[216:219], v[184:187], v[36:39]
	s_setprio 0
	s_add_i32 s53, 0, 0x18000
	v_add_u32_e32 v68, s53, v164
	s_barrier
	ds_read_b128 v[48:51], v68
	ds_read_b128 v[52:55], v68 offset:1024
	ds_read_b128 v[64:67], v68 offset:2048
	ds_read_b128 v[68:71], v68 offset:3072
	s_add_u32 s22, s22, 0x40000
	s_addc_u32 s23, s23, 0
	s_mov_b32 m0, s39
	v_lshl_add_u64 v[204:205], s[22:23], 0, v[144:145]
	ds_read_b128 v[154:157], v165 offset:32768
	ds_read_b128 v[158:161], v165 offset:33792
	ds_read_b128 v[180:183], v165 offset:34816
	ds_read_b128 v[184:187], v165 offset:35840
	ds_read_b128 v[188:191], v165 offset:36864
	ds_read_b128 v[192:195], v165 offset:37888
	ds_read_b128 v[196:199], v165 offset:38912
	ds_read_b128 v[200:203], v165 offset:39936
	global_load_lds_dwordx4 v[204:205], off
	s_mov_b32 m0, s40
	v_lshl_add_u64 v[204:205], s[22:23], 0, v[146:147]
	global_load_lds_dwordx4 v[204:205], off
	s_waitcnt lgkmcnt(8)
	s_barrier
	s_waitcnt lgkmcnt(0)
	s_setprio 1
	v_mfma_f32_16x16x32_bf16 v[140:143], v[48:51], v[154:157], v[140:143]
	v_mfma_f32_16x16x32_bf16 v[136:139], v[64:67], v[154:157], v[136:139]
	v_mfma_f32_16x16x32_bf16 v[124:127], v[48:51], v[180:183], v[124:127]
	v_mfma_f32_16x16x32_bf16 v[120:123], v[64:67], v[180:183], v[120:123]
	v_mfma_f32_16x16x32_bf16 v[108:111], v[48:51], v[188:191], v[108:111]
	v_mfma_f32_16x16x32_bf16 v[104:107], v[64:67], v[188:191], v[104:107]
	v_mfma_f32_16x16x32_bf16 v[92:95], v[48:51], v[196:199], v[92:95]
	v_mfma_f32_16x16x32_bf16 v[88:91], v[64:67], v[196:199], v[88:91]
	v_mfma_f32_16x16x32_bf16 v[140:143], v[52:55], v[158:161], v[140:143]
	v_mfma_f32_16x16x32_bf16 v[136:139], v[68:71], v[158:161], v[136:139]
	v_mfma_f32_16x16x32_bf16 v[124:127], v[52:55], v[184:187], v[124:127]
	v_mfma_f32_16x16x32_bf16 v[120:123], v[68:71], v[184:187], v[120:123]
	v_mfma_f32_16x16x32_bf16 v[108:111], v[52:55], v[192:195], v[108:111]
	v_mfma_f32_16x16x32_bf16 v[104:107], v[68:71], v[192:195], v[104:107]
	v_mfma_f32_16x16x32_bf16 v[92:95], v[52:55], v[200:203], v[92:95]
	v_mfma_f32_16x16x32_bf16 v[88:91], v[68:71], v[200:203], v[88:91]
	s_setprio 0
	s_barrier
	s_add_i32 s22, 0, 0x1c000
	s_add_i32 s23, s53, s36
	v_add_u32_e32 v216, s22, v164
	v_lshl_add_u64 v[166:167], v[166:167], 0, s[78:79]
	s_mov_b32 m0, s23
	ds_read_b128 v[204:207], v216
	ds_read_b128 v[208:211], v216 offset:1024
	ds_read_b128 v[212:215], v216 offset:2048
	ds_read_b128 v[216:219], v216 offset:3072
	global_load_lds_dwordx4 v[166:167], off
	s_add_i32 m0, s23, 0x2000
	v_lshl_add_u64 v[166:167], v[220:221], 0, s[78:79]
	global_load_lds_dwordx4 v[166:167], off
	s_barrier
	s_waitcnt lgkmcnt(0)
	s_setprio 1
	v_mfma_f32_16x16x32_bf16 v[132:135], v[204:207], v[154:157], v[132:135]
	v_mfma_f32_16x16x32_bf16 v[128:131], v[212:215], v[154:157], v[128:131]
	v_mfma_f32_16x16x32_bf16 v[116:119], v[204:207], v[180:183], v[116:119]
	v_mfma_f32_16x16x32_bf16 v[112:115], v[212:215], v[180:183], v[112:115]
	v_mfma_f32_16x16x32_bf16 v[100:103], v[204:207], v[188:191], v[100:103]
	v_mfma_f32_16x16x32_bf16 v[96:99], v[212:215], v[188:191], v[96:99]
	v_mfma_f32_16x16x32_bf16 v[84:87], v[204:207], v[196:199], v[84:87]
	v_mfma_f32_16x16x32_bf16 v[80:83], v[212:215], v[196:199], v[80:83]
	v_mfma_f32_16x16x32_bf16 v[132:135], v[208:211], v[158:161], v[132:135]
	v_mfma_f32_16x16x32_bf16 v[128:131], v[216:219], v[158:161], v[128:131]
	v_mfma_f32_16x16x32_bf16 v[116:119], v[208:211], v[184:187], v[116:119]
	v_mfma_f32_16x16x32_bf16 v[112:115], v[216:219], v[184:187], v[112:115]
	v_mfma_f32_16x16x32_bf16 v[100:103], v[208:211], v[192:195], v[100:103]
	v_mfma_f32_16x16x32_bf16 v[96:99], v[216:219], v[192:195], v[96:99]
	v_mfma_f32_16x16x32_bf16 v[84:87], v[208:211], v[200:203], v[84:87]
	v_mfma_f32_16x16x32_bf16 v[80:83], v[216:219], v[200:203], v[80:83]
	s_setprio 0
	s_mov_b32 m0, s45
	v_lshl_add_u64 v[166:167], v[222:223], 0, s[78:79]
	s_barrier
	ds_read_b128 v[154:157], v165 offset:49152
	ds_read_b128 v[158:161], v165 offset:50176
	ds_read_b128 v[180:183], v165 offset:51200
	ds_read_b128 v[184:187], v165 offset:52224
	ds_read_b128 v[188:191], v165 offset:53248
	ds_read_b128 v[192:195], v165 offset:54272
	ds_read_b128 v[196:199], v165 offset:55296
	ds_read_b128 v[200:203], v165 offset:56320
	global_load_lds_dwordx4 v[166:167], off
	s_mov_b32 m0, s46
	v_lshl_add_u64 v[166:167], v[236:237], 0, s[78:79]
	global_load_lds_dwordx4 v[166:167], off
	s_barrier
	s_waitcnt lgkmcnt(0)
	s_setprio 1
	v_mfma_f32_16x16x32_bf16 v[76:79], v[48:51], v[154:157], v[76:79]
	v_mfma_f32_16x16x32_bf16 v[72:75], v[64:67], v[154:157], v[72:75]
	v_mfma_f32_16x16x32_bf16 v[60:63], v[48:51], v[180:183], v[60:63]
	v_mfma_f32_16x16x32_bf16 v[56:59], v[64:67], v[180:183], v[56:59]
	v_mfma_f32_16x16x32_bf16 v[44:47], v[48:51], v[188:191], v[44:47]
	v_mfma_f32_16x16x32_bf16 v[40:43], v[64:67], v[188:191], v[40:43]
	v_mfma_f32_16x16x32_bf16 v[12:15], v[48:51], v[196:199], v[12:15]
	v_mfma_f32_16x16x32_bf16 v[8:11], v[64:67], v[196:199], v[8:11]
	v_mfma_f32_16x16x32_bf16 v[76:79], v[52:55], v[158:161], v[76:79]
	v_mfma_f32_16x16x32_bf16 v[72:75], v[68:71], v[158:161], v[72:75]
	v_mfma_f32_16x16x32_bf16 v[60:63], v[52:55], v[184:187], v[60:63]
	v_mfma_f32_16x16x32_bf16 v[56:59], v[68:71], v[184:187], v[56:59]
	v_mfma_f32_16x16x32_bf16 v[44:47], v[52:55], v[192:195], v[44:47]
	v_mfma_f32_16x16x32_bf16 v[40:43], v[68:71], v[192:195], v[40:43]
	v_mfma_f32_16x16x32_bf16 v[12:15], v[52:55], v[200:203], v[12:15]
	v_mfma_f32_16x16x32_bf16 v[8:11], v[68:71], v[200:203], v[8:11]
	s_setprio 0
	s_barrier
	s_add_u32 s2, s2, 0x40080
	s_addc_u32 s3, s3, 0
	s_add_i32 s22, s22, s36
	s_mov_b32 m0, s22
	v_lshl_add_u64 v[48:49], s[2:3], 0, v[168:169]
	global_load_lds_dwordx4 v[48:49], off
	s_add_i32 m0, s22, 0x2000
	v_lshl_add_u64 v[48:49], s[2:3], 0, v[148:149]
	global_load_lds_dwordx4 v[48:49], off
	s_waitcnt vmcnt(6)
	s_barrier
	s_setprio 1
	v_mfma_f32_16x16x32_bf16 v[24:27], v[204:207], v[154:157], v[24:27]
	v_mfma_f32_16x16x32_bf16 v[68:71], v[208:211], v[158:161], v[24:27]
	v_mfma_f32_16x16x32_bf16 v[24:27], v[212:215], v[154:157], v[28:31]
	v_mfma_f32_16x16x32_bf16 v[64:67], v[216:219], v[158:161], v[24:27]
	v_mfma_f32_16x16x32_bf16 v[24:27], v[204:207], v[180:183], v[32:35]
	v_mfma_f32_16x16x32_bf16 v[52:55], v[208:211], v[184:187], v[24:27]
	v_mfma_f32_16x16x32_bf16 v[24:27], v[212:215], v[180:183], v[36:39]
	v_mfma_f32_16x16x32_bf16 v[20:23], v[204:207], v[188:191], v[20:23]
	v_mfma_f32_16x16x32_bf16 v[16:19], v[212:215], v[188:191], v[16:19]
	v_mfma_f32_16x16x32_bf16 v[4:7], v[204:207], v[196:199], v[4:7]
	v_mfma_f32_16x16x32_bf16 v[0:3], v[212:215], v[196:199], v[0:3]
	v_mfma_f32_16x16x32_bf16 v[48:51], v[216:219], v[184:187], v[24:27]
	v_mfma_f32_16x16x32_bf16 v[20:23], v[208:211], v[192:195], v[20:23]
	v_mfma_f32_16x16x32_bf16 v[16:19], v[216:219], v[192:195], v[16:19]
	v_mfma_f32_16x16x32_bf16 v[4:7], v[208:211], v[200:203], v[4:7]
	v_mfma_f32_16x16x32_bf16 v[0:3], v[216:219], v[200:203], v[0:3]
	s_setprio 0
	s_add_i32 s52, s52, 2
	s_add_u32 s20, s20, 0x100
	s_addc_u32 s21, s21, 0
	s_add_u32 s50, s50, 0x100
	s_addc_u32 s51, s51, 0
	s_cmp_gt_u32 s52, 13
	s_barrier
	s_cbranch_scc0 .LBB0_123
	s_lshl_b32 s2, s6, 8
	s_add_i32 s3, s2, s43
	s_lshl_b32 s2, s8, 8
	s_cmp_gt_i32 s8, 3
	s_cselect_b64 s[20:21], -1, 0
	s_and_b64 s[22:23], s[20:21], exec
	s_mov_b32 s7, 0x8982000
	s_cselect_b32 s7, s7, 0x7182000
	s_add_u32 s22, s26, s7
	s_addc_u32 s23, s25, 0
	s_add_i32 s7, s6, -16
	v_mov_b32_e32 v160, v163
	v_mov_b32_e32 v24, v162
	s_lshr_b32 s7, s7, 3
	s_add_i32 s96, s7, 1
	v_add_u32_e32 v154, s3, v24
	s_lshl_b64 s[50:51], s[96:97], 11
	v_ashrrev_i32_e32 v155, 31, v154
	s_cmp_gt_i32 s6, 15
	v_lshl_add_u64 v[156:157], v[154:155], 2, s[10:11]
	s_cselect_b32 s7, s51, 0
	s_cselect_b32 s6, s50, 0
	global_load_dword v166, v[156:157], off
	global_load_dword v191, v[156:157], off offset:64
	global_load_dword v192, v[156:157], off offset:128
	global_load_dword v193, v[156:157], off offset:192
	global_load_dword v194, v[156:157], off offset:512
	global_load_dword v195, v[156:157], off offset:576
	global_load_dword v196, v[156:157], off offset:640
	global_load_dword v197, v[156:157], off offset:704
	s_lshl_b64 s[6:7], s[6:7], 2
	s_add_u32 s9, s41, s6
	s_addc_u32 s13, s42, s7
	s_ashr_i32 s3, s2, 31
	s_lshl_b64 s[6:7], s[2:3], 2
	s_add_u32 s3, s9, s6
	s_addc_u32 s7, s13, s7
	v_lshlrev_b32_e32 v158, 3, v160
	s_add_u32 s6, s3, s49
	s_addc_u32 s7, s7, 0
	v_ashrrev_i32_e32 v159, 31, v158
	v_lshl_add_u64 v[24:25], v[158:159], 2, s[6:7]
	global_load_dwordx4 v[36:39], v[24:25], off
	global_load_dwordx4 v[32:35], v[24:25], off offset:16
	global_load_dwordx4 v[28:31], v[24:25], off offset:512
	s_nop 0
	global_load_dwordx4 v[24:27], v[24:25], off offset:528
	s_and_b32 s2, s2, 0x300
	s_or_b32 s2, s2, s44
	v_add_u32_e32 v158, s2, v158
	v_cmp_eq_u32_e64 s[6:7], 0, v160
	v_lshlrev_b64 v[160:161], 11, v[154:155]
	s_cmp_lt_i32 s8, 4
	s_waitcnt vmcnt(0)
	v_ashrrev_i32_e32 v159, 31, v158
	v_lshl_add_u64 v[158:159], v[158:159], 1, s[22:23]
	v_lshl_add_u64 v[160:161], v[158:159], 0, v[160:161]
	v_lshl_add_u64 v[156:157], v[154:155], 2, s[0:1]
	s_and_b64 s[6:7], s[6:7], s[20:21]
	s_mov_b64 s[2:3], 0x8000
	s_mov_b64 s[50:51], 0x28000
	v_mov_b32_e32 v180, 0xc0135761
	v_mov_b32_e32 v181, 0xc0135761
	v_mov_b32_e32 v182, 0xbdd2d3e7
	v_mov_b32_e32 v183, 0xbdd2d3e7
	v_fmamk_f32 v166, v166, 0x3a800000, v225
	v_fmamk_f32 v190, v191, 0x3a800000, v225
	v_fmamk_f32 v192, v192, 0x3a800000, v225
	v_fmamk_f32 v188, v193, 0x3a800000, v225
	v_fmamk_f32 v194, v194, 0x3a800000, v225
	v_fmamk_f32 v186, v195, 0x3a800000, v225
	v_fmamk_f32 v196, v196, 0x3a800000, v225
	v_fmamk_f32 v184, v197, 0x3a800000, v225
	v_rsq_f32_e32 v166, v166
	v_rsq_f32_e32 v190, v190
	v_rsq_f32_e32 v192, v192
	v_rsq_f32_e32 v188, v188
	v_rsq_f32_e32 v194, v194
	v_rsq_f32_e32 v186, v186
	v_rsq_f32_e32 v196, v196
	v_rsq_f32_e32 v184, v184
	v_pk_fma_f32 v[140:141], v[140:141], v[166:167], v[36:37] op_sel_hi:[1,0,1]
	v_pk_fma_f32 v[142:143], v[142:143], v[166:167], v[38:39] op_sel_hi:[1,0,1]
	v_pk_fma_f32 v[136:137], v[136:137], v[166:167], v[32:33] op_sel_hi:[1,0,1]
	v_pk_fma_f32 v[138:139], v[138:139], v[166:167], v[34:35] op_sel_hi:[1,0,1]
	v_pk_fma_f32 v[132:133], v[132:133], v[166:167], v[28:29] op_sel_hi:[1,0,1]
	v_pk_fma_f32 v[134:135], v[134:135], v[166:167], v[30:31] op_sel_hi:[1,0,1]
	v_pk_fma_f32 v[128:129], v[128:129], v[166:167], v[24:25] op_sel_hi:[1,0,1]
	v_pk_fma_f32 v[130:131], v[130:131], v[166:167], v[26:27] op_sel_hi:[1,0,1]
	v_pk_fma_f32 v[124:125], v[124:125], v[190:191], v[36:37] op_sel_hi:[1,0,1]
	v_pk_fma_f32 v[126:127], v[126:127], v[190:191], v[38:39] op_sel_hi:[1,0,1]
	v_pk_fma_f32 v[120:121], v[120:121], v[190:191], v[32:33] op_sel_hi:[1,0,1]
	v_pk_fma_f32 v[122:123], v[122:123], v[190:191], v[34:35] op_sel_hi:[1,0,1]
	v_pk_fma_f32 v[116:117], v[116:117], v[190:191], v[28:29] op_sel_hi:[1,0,1]
	v_pk_fma_f32 v[118:119], v[118:119], v[190:191], v[30:31] op_sel_hi:[1,0,1]
	v_pk_fma_f32 v[112:113], v[112:113], v[190:191], v[24:25] op_sel_hi:[1,0,1]
	v_pk_fma_f32 v[114:115], v[114:115], v[190:191], v[26:27] op_sel_hi:[1,0,1]
	v_pk_fma_f32 v[108:109], v[108:109], v[192:193], v[36:37] op_sel_hi:[1,0,1]
	v_pk_fma_f32 v[110:111], v[110:111], v[192:193], v[38:39] op_sel_hi:[1,0,1]
	v_pk_fma_f32 v[104:105], v[104:105], v[192:193], v[32:33] op_sel_hi:[1,0,1]
	v_pk_fma_f32 v[106:107], v[106:107], v[192:193], v[34:35] op_sel_hi:[1,0,1]
	v_pk_fma_f32 v[100:101], v[100:101], v[192:193], v[28:29] op_sel_hi:[1,0,1]
	v_pk_fma_f32 v[102:103], v[102:103], v[192:193], v[30:31] op_sel_hi:[1,0,1]
	v_pk_fma_f32 v[96:97], v[96:97], v[192:193], v[24:25] op_sel_hi:[1,0,1]
	v_pk_fma_f32 v[98:99], v[98:99], v[192:193], v[26:27] op_sel_hi:[1,0,1]
	v_pk_fma_f32 v[92:93], v[92:93], v[188:189], v[36:37] op_sel_hi:[1,0,1]
	v_pk_fma_f32 v[94:95], v[94:95], v[188:189], v[38:39] op_sel_hi:[1,0,1]
	v_pk_fma_f32 v[88:89], v[88:89], v[188:189], v[32:33] op_sel_hi:[1,0,1]
	v_pk_fma_f32 v[90:91], v[90:91], v[188:189], v[34:35] op_sel_hi:[1,0,1]
	v_pk_fma_f32 v[84:85], v[84:85], v[188:189], v[28:29] op_sel_hi:[1,0,1]
	v_pk_fma_f32 v[86:87], v[86:87], v[188:189], v[30:31] op_sel_hi:[1,0,1]
	v_pk_fma_f32 v[80:81], v[80:81], v[188:189], v[24:25] op_sel_hi:[1,0,1]
	v_pk_fma_f32 v[82:83], v[82:83], v[188:189], v[26:27] op_sel_hi:[1,0,1]
	v_pk_fma_f32 v[76:77], v[76:77], v[194:195], v[36:37] op_sel_hi:[1,0,1]
	v_pk_fma_f32 v[78:79], v[78:79], v[194:195], v[38:39] op_sel_hi:[1,0,1]
	v_pk_fma_f32 v[72:73], v[72:73], v[194:195], v[32:33] op_sel_hi:[1,0,1]
	v_pk_fma_f32 v[74:75], v[74:75], v[194:195], v[34:35] op_sel_hi:[1,0,1]
	v_pk_fma_f32 v[68:69], v[68:69], v[194:195], v[28:29] op_sel_hi:[1,0,1]
	v_pk_fma_f32 v[70:71], v[70:71], v[194:195], v[30:31] op_sel_hi:[1,0,1]
	v_pk_fma_f32 v[64:65], v[64:65], v[194:195], v[24:25] op_sel_hi:[1,0,1]
	v_pk_fma_f32 v[66:67], v[66:67], v[194:195], v[26:27] op_sel_hi:[1,0,1]
	v_pk_fma_f32 v[60:61], v[60:61], v[186:187], v[36:37] op_sel_hi:[1,0,1]
	v_pk_fma_f32 v[62:63], v[62:63], v[186:187], v[38:39] op_sel_hi:[1,0,1]
	v_pk_fma_f32 v[56:57], v[56:57], v[186:187], v[32:33] op_sel_hi:[1,0,1]
	v_pk_fma_f32 v[58:59], v[58:59], v[186:187], v[34:35] op_sel_hi:[1,0,1]
	v_pk_fma_f32 v[52:53], v[52:53], v[186:187], v[28:29] op_sel_hi:[1,0,1]
	v_pk_fma_f32 v[54:55], v[54:55], v[186:187], v[30:31] op_sel_hi:[1,0,1]
	v_pk_fma_f32 v[48:49], v[48:49], v[186:187], v[24:25] op_sel_hi:[1,0,1]
	v_pk_fma_f32 v[50:51], v[50:51], v[186:187], v[26:27] op_sel_hi:[1,0,1]
	v_pk_fma_f32 v[44:45], v[44:45], v[196:197], v[36:37] op_sel_hi:[1,0,1]
	v_pk_fma_f32 v[46:47], v[46:47], v[196:197], v[38:39] op_sel_hi:[1,0,1]
	v_pk_fma_f32 v[40:41], v[40:41], v[196:197], v[32:33] op_sel_hi:[1,0,1]
	v_pk_fma_f32 v[42:43], v[42:43], v[196:197], v[34:35] op_sel_hi:[1,0,1]
	v_pk_fma_f32 v[20:21], v[20:21], v[196:197], v[28:29] op_sel_hi:[1,0,1]
	v_pk_fma_f32 v[22:23], v[22:23], v[196:197], v[30:31] op_sel_hi:[1,0,1]
	v_pk_fma_f32 v[16:17], v[16:17], v[196:197], v[24:25] op_sel_hi:[1,0,1]
	v_pk_fma_f32 v[18:19], v[18:19], v[196:197], v[26:27] op_sel_hi:[1,0,1]
	v_pk_fma_f32 v[12:13], v[12:13], v[184:185], v[36:37] op_sel_hi:[1,0,1]
	v_pk_fma_f32 v[14:15], v[14:15], v[184:185], v[38:39] op_sel_hi:[1,0,1]
	v_pk_fma_f32 v[8:9], v[8:9], v[184:185], v[32:33] op_sel_hi:[1,0,1]
	v_pk_fma_f32 v[10:11], v[10:11], v[184:185], v[34:35] op_sel_hi:[1,0,1]
	v_pk_fma_f32 v[4:5], v[4:5], v[184:185], v[28:29] op_sel_hi:[1,0,1]
	v_pk_fma_f32 v[6:7], v[6:7], v[184:185], v[30:31] op_sel_hi:[1,0,1]
	v_pk_fma_f32 v[0:1], v[0:1], v[184:185], v[24:25] op_sel_hi:[1,0,1]
	v_pk_fma_f32 v[2:3], v[2:3], v[184:185], v[26:27] op_sel_hi:[1,0,1]
	v_pk_mul_f32 v[24:25], v[140:141], v[140:141]
	v_pk_mul_f32 v[26:27], v[142:143], v[142:143]
	v_pk_mul_f32 v[28:29], v[136:137], v[136:137]
	v_pk_mul_f32 v[30:31], v[138:139], v[138:139]
	v_pk_mul_f32 v[32:33], v[132:133], v[132:133]
	v_pk_mul_f32 v[34:35], v[134:135], v[134:135]
	v_pk_mul_f32 v[36:37], v[128:129], v[128:129]
	v_pk_mul_f32 v[38:39], v[130:131], v[130:131]
	v_pk_fma_f32 v[24:25], v[24:25], v[182:183], v[180:181]
	v_pk_fma_f32 v[26:27], v[26:27], v[182:183], v[180:181]
	v_pk_fma_f32 v[28:29], v[28:29], v[182:183], v[180:181]
	v_pk_fma_f32 v[30:31], v[30:31], v[182:183], v[180:181]
	v_pk_fma_f32 v[32:33], v[32:33], v[182:183], v[180:181]
	v_pk_fma_f32 v[34:35], v[34:35], v[182:183], v[180:181]
	v_pk_fma_f32 v[36:37], v[36:37], v[182:183], v[180:181]
	v_pk_fma_f32 v[38:39], v[38:39], v[182:183], v[180:181]
	v_pk_mul_f32 v[24:25], v[24:25], v[140:141]
	v_pk_mul_f32 v[26:27], v[26:27], v[142:143]
	v_pk_mul_f32 v[28:29], v[28:29], v[136:137]
	v_pk_mul_f32 v[30:31], v[30:31], v[138:139]
	v_pk_mul_f32 v[32:33], v[32:33], v[132:133]
	v_pk_mul_f32 v[34:35], v[34:35], v[134:135]
	v_pk_mul_f32 v[36:37], v[36:37], v[128:129]
	v_pk_mul_f32 v[38:39], v[38:39], v[130:131]
	v_exp_f32_e32 v24, v24
	v_exp_f32_e32 v25, v25
	v_exp_f32_e32 v26, v26
	v_exp_f32_e32 v27, v27
	v_exp_f32_e32 v28, v28
	v_exp_f32_e32 v29, v29
	v_exp_f32_e32 v30, v30
	v_exp_f32_e32 v31, v31
	v_exp_f32_e32 v32, v32
	v_exp_f32_e32 v33, v33
	v_exp_f32_e32 v34, v34
	v_exp_f32_e32 v35, v35
	v_exp_f32_e32 v36, v36
	v_exp_f32_e32 v37, v37
	v_exp_f32_e32 v38, v38
	v_exp_f32_e32 v39, v39
	v_pk_add_f32 v[24:25], v[24:25], 1.0 op_sel_hi:[1,0]
	v_pk_add_f32 v[26:27], v[26:27], 1.0 op_sel_hi:[1,0]
	v_pk_add_f32 v[28:29], v[28:29], 1.0 op_sel_hi:[1,0]
	v_pk_add_f32 v[30:31], v[30:31], 1.0 op_sel_hi:[1,0]
	v_pk_add_f32 v[32:33], v[32:33], 1.0 op_sel_hi:[1,0]
	v_pk_add_f32 v[34:35], v[34:35], 1.0 op_sel_hi:[1,0]
	v_pk_add_f32 v[36:37], v[36:37], 1.0 op_sel_hi:[1,0]
	v_pk_add_f32 v[38:39], v[38:39], 1.0 op_sel_hi:[1,0]
	v_rcp_f32_e32 v24, v24
	v_rcp_f32_e32 v25, v25
	v_rcp_f32_e32 v26, v26
	v_rcp_f32_e32 v27, v27
	v_rcp_f32_e32 v28, v28
	v_rcp_f32_e32 v29, v29
	v_rcp_f32_e32 v30, v30
	v_rcp_f32_e32 v31, v31
	v_rcp_f32_e32 v32, v32
	v_rcp_f32_e32 v33, v33
	v_rcp_f32_e32 v34, v34
	v_rcp_f32_e32 v35, v35
	v_rcp_f32_e32 v36, v36
	v_rcp_f32_e32 v37, v37
	v_rcp_f32_e32 v38, v38
	v_rcp_f32_e32 v39, v39
	v_pk_mul_f32 v[140:141], v[140:141], v[24:25]
	v_pk_mul_f32 v[142:143], v[142:143], v[26:27]
	v_pk_mul_f32 v[136:137], v[136:137], v[28:29]
	v_pk_mul_f32 v[138:139], v[138:139], v[30:31]
	v_pk_mul_f32 v[132:133], v[132:133], v[32:33]
	v_pk_mul_f32 v[134:135], v[134:135], v[34:35]
	v_pk_mul_f32 v[128:129], v[128:129], v[36:37]
	v_pk_mul_f32 v[130:131], v[130:131], v[38:39]
	v_cvt_pk_bf16_f32 v24, v140, v141
	v_cvt_pk_bf16_f32 v25, v142, v143
	v_cvt_pk_bf16_f32 v26, v136, v137
	v_cvt_pk_bf16_f32 v27, v138, v139
	v_cvt_pk_bf16_f32 v28, v132, v133
	v_cvt_pk_bf16_f32 v29, v134, v135
	v_cvt_pk_bf16_f32 v30, v128, v129
	v_cvt_pk_bf16_f32 v31, v130, v131
	global_store_dwordx4 v[160:161], v[24:27], off
	global_store_dwordx4 v[160:161], v[28:31], off offset:256
	s_and_b64 vcc, exec, s[20:21]
	s_cbranch_vccz .Lio_skip_0
	v_pk_mul_f32 v[32:33], v[140:141], v[140:141]
	v_pk_fma_f32 v[32:33], v[142:143], v[142:143], v[32:33]
	v_pk_fma_f32 v[32:33], v[136:137], v[136:137], v[32:33]
	v_pk_fma_f32 v[32:33], v[138:139], v[138:139], v[32:33]
	v_pk_fma_f32 v[32:33], v[132:133], v[132:133], v[32:33]
	v_pk_fma_f32 v[32:33], v[134:135], v[134:135], v[32:33]
	v_pk_fma_f32 v[32:33], v[128:129], v[128:129], v[32:33]
	v_pk_fma_f32 v[32:33], v[130:131], v[130:131], v[32:33]
	s_nop 0
	v_add_f32_e32 v32, v32, v33
	v_mov_b32_e32 v33, v32
	s_nop 1
	v_permlane16_swap_b32_e32 v32, v33
	v_add_f32_e32 v32, v32, v33
	v_mov_b32_e32 v33, v32
	s_nop 1
	v_permlane32_swap_b32_e32 v32, v33
	s_and_saveexec_b64 vcc, s[6:7]
	v_add_f32_e32 v32, v32, v33
	global_atomic_add_f32 v[156:157], v32, off
	s_mov_b64 exec, vcc

.Lie_done_b:
.LBB0_354:
	s_ashr_i32 s31, s30, 31
	v_cmp_lt_i64_e32 vcc, s[8:9], v[170:171]
	s_lshl_b64 s[8:9], s[30:31], 19
	s_add_u32 s34, s52, s8
	s_addc_u32 s35, s53, s9
	s_and_b64 s[8:9], vcc, exec
	s_cselect_b32 s1, s35, s7
	s_cselect_b32 s31, s34, s6
	s_ashr_i32 s29, s28, 31
	s_lshl_b64 s[8:9], s[28:29], 19
	s_add_u32 s36, s43, s8
	s_addc_u32 s37, s42, s9
	s_and_b64 s[8:9], vcc, exec
	s_cselect_b32 s29, s37, s3
	s_cselect_b32 s38, s36, s2
	s_add_u32 s6, s6, 0x40080
	s_addc_u32 s7, s7, 0
	s_add_u32 s39, s2, 0x100
	s_addc_u32 s40, s3, 0
	s_mov_b32 s41, -2
	s_add_u32 s2, s6, 0xfffc0080
	s_addc_u32 s3, s7, -1
	s_add_i32 s64, 0, 0x10000
	v_add_u32_e32 v140, s64, v208
	ds_read_b128 v[128:131], v140
	ds_read_b128 v[132:135], v140 offset:1024
	ds_read_b128 v[136:139], v140 offset:2048
	ds_read_b128 v[140:143], v140 offset:3072
	s_cmp_eq_u32 s41, 12
	s_cselect_b32 s9, s1, s3
	s_cselect_b32 s8, s31, s2
	s_cselect_b32 s3, s29, s40
	s_cselect_b32 s2, s38, s39
	v_lshl_add_u64 v[196:197], s[6:7], 0, v[164:165]
	s_add_i32 m0, s21, 0xc000
	ds_read_b128 v[144:147], v209
	ds_read_b128 v[148:151], v209 offset:1024
	ds_read_b128 v[152:155], v209 offset:2048
	ds_read_b128 v[156:159], v209 offset:3072
	ds_read_b128 v[180:183], v209 offset:4096
	ds_read_b128 v[184:187], v209 offset:5120
	ds_read_b128 v[188:191], v209 offset:6144
	ds_read_b128 v[192:195], v209 offset:7168
	global_load_lds_dwordx4 v[196:197], off
	s_add_i32 m0, s21, 0xe000
	v_lshl_add_u64 v[196:197], s[6:7], 0, v[166:167]
	global_load_lds_dwordx4 v[196:197], off
	s_waitcnt lgkmcnt(8)
	s_barrier
	s_waitcnt lgkmcnt(0)
	s_setprio 1
	v_mfma_f32_16x16x32_bf16 v[124:127], v[128:131], v[144:147], 0
	v_mfma_f32_16x16x32_bf16 v[120:123], v[136:139], v[144:147], 0
	v_mfma_f32_16x16x32_bf16 v[116:119], v[128:131], v[152:155], 0
	v_mfma_f32_16x16x32_bf16 v[112:115], v[136:139], v[152:155], 0
	v_mfma_f32_16x16x32_bf16 v[100:103], v[128:131], v[180:183], 0
	v_mfma_f32_16x16x32_bf16 v[96:99], v[136:139], v[180:183], 0
	v_mfma_f32_16x16x32_bf16 v[84:87], v[128:131], v[188:191], 0
	v_mfma_f32_16x16x32_bf16 v[80:83], v[136:139], v[188:191], 0
	v_mfma_f32_16x16x32_bf16 v[124:127], v[132:135], v[148:151], v[124:127]
	v_mfma_f32_16x16x32_bf16 v[120:123], v[140:143], v[148:151], v[120:123]
	v_mfma_f32_16x16x32_bf16 v[116:119], v[132:135], v[156:159], v[116:119]
	v_mfma_f32_16x16x32_bf16 v[112:115], v[140:143], v[156:159], v[112:115]
	v_mfma_f32_16x16x32_bf16 v[100:103], v[132:135], v[184:187], v[100:103]
	v_mfma_f32_16x16x32_bf16 v[96:99], v[140:143], v[184:187], v[96:99]
	v_mfma_f32_16x16x32_bf16 v[84:87], v[132:135], v[192:195], v[84:87]
	v_mfma_f32_16x16x32_bf16 v[80:83], v[140:143], v[192:195], v[80:83]
	s_setprio 0
	s_barrier
	s_add_i32 s66, 0, 0x14000
	s_add_i32 s64, s64, s54
	v_add_u32_e32 v168, s66, v208
	v_lshl_add_u64 v[204:205], s[2:3], 0, v[160:161]
	s_mov_b32 m0, s64
	ds_read_b128 v[196:199], v168
	ds_read_b128 v[200:203], v168 offset:1024
	ds_read_b128 v[210:213], v168 offset:2048
	ds_read_b128 v[214:217], v168 offset:3072
	global_load_lds_dwordx4 v[204:205], off
	s_add_i32 m0, s64, 0x2000
	v_lshl_add_u64 v[218:219], s[2:3], 0, v[162:163]
	global_load_lds_dwordx4 v[218:219], off
	s_barrier
	s_waitcnt lgkmcnt(0)
	s_setprio 1
	v_mfma_f32_16x16x32_bf16 v[108:111], v[196:199], v[144:147], 0
	v_mfma_f32_16x16x32_bf16 v[104:107], v[210:213], v[144:147], 0
	v_mfma_f32_16x16x32_bf16 v[92:95], v[196:199], v[152:155], 0
	v_mfma_f32_16x16x32_bf16 v[88:91], v[210:213], v[152:155], 0
	v_mfma_f32_16x16x32_bf16 v[76:79], v[196:199], v[180:183], 0
	v_mfma_f32_16x16x32_bf16 v[72:75], v[210:213], v[180:183], 0
	v_mfma_f32_16x16x32_bf16 v[68:71], v[196:199], v[188:191], 0
	v_mfma_f32_16x16x32_bf16 v[64:67], v[210:213], v[188:191], 0
	v_mfma_f32_16x16x32_bf16 v[108:111], v[200:203], v[148:151], v[108:111]
	v_mfma_f32_16x16x32_bf16 v[104:107], v[214:217], v[148:151], v[104:107]
	v_mfma_f32_16x16x32_bf16 v[92:95], v[200:203], v[156:159], v[92:95]
	v_mfma_f32_16x16x32_bf16 v[88:91], v[214:217], v[156:159], v[88:91]
	v_mfma_f32_16x16x32_bf16 v[76:79], v[200:203], v[184:187], v[76:79]
	v_mfma_f32_16x16x32_bf16 v[72:75], v[214:217], v[184:187], v[72:75]
	v_mfma_f32_16x16x32_bf16 v[68:71], v[200:203], v[192:195], v[68:71]
	v_mfma_f32_16x16x32_bf16 v[64:67], v[214:217], v[192:195], v[64:67]
	s_setprio 0
	s_mov_b32 m0, s21
	v_lshl_add_u64 v[220:221], s[8:9], 0, v[160:161]
	s_barrier
	ds_read_b128 v[144:147], v209 offset:16384
	ds_read_b128 v[148:151], v209 offset:17408
	ds_read_b128 v[152:155], v209 offset:18432
	ds_read_b128 v[156:159], v209 offset:19456
	ds_read_b128 v[180:183], v209 offset:20480
	ds_read_b128 v[184:187], v209 offset:21504
	ds_read_b128 v[188:191], v209 offset:22528
	ds_read_b128 v[192:195], v209 offset:23552
	global_load_lds_dwordx4 v[220:221], off
	s_mov_b32 m0, s55
	v_lshl_add_u64 v[222:223], s[8:9], 0, v[162:163]
	global_load_lds_dwordx4 v[222:223], off
	s_barrier
	s_waitcnt lgkmcnt(0)
	s_setprio 1
	v_mfma_f32_16x16x32_bf16 v[60:63], v[128:131], v[144:147], 0
	v_mfma_f32_16x16x32_bf16 v[56:59], v[136:139], v[144:147], 0
	v_mfma_f32_16x16x32_bf16 v[52:55], v[128:131], v[152:155], 0
	v_mfma_f32_16x16x32_bf16 v[48:51], v[136:139], v[152:155], 0
	v_mfma_f32_16x16x32_bf16 v[36:39], v[128:131], v[180:183], 0
	v_mfma_f32_16x16x32_bf16 v[32:35], v[136:139], v[180:183], 0
	v_mfma_f32_16x16x32_bf16 v[20:23], v[128:131], v[188:191], 0
	v_mfma_f32_16x16x32_bf16 v[16:19], v[136:139], v[188:191], 0
	v_mfma_f32_16x16x32_bf16 v[60:63], v[132:135], v[148:151], v[60:63]
	v_mfma_f32_16x16x32_bf16 v[56:59], v[140:143], v[148:151], v[56:59]
	v_mfma_f32_16x16x32_bf16 v[52:55], v[132:135], v[156:159], v[52:55]
	v_mfma_f32_16x16x32_bf16 v[48:51], v[140:143], v[156:159], v[48:51]
	v_mfma_f32_16x16x32_bf16 v[36:39], v[132:135], v[184:187], v[36:39]
	v_mfma_f32_16x16x32_bf16 v[32:35], v[140:143], v[184:187], v[32:35]
	v_mfma_f32_16x16x32_bf16 v[20:23], v[132:135], v[192:195], v[20:23]
	v_mfma_f32_16x16x32_bf16 v[16:19], v[140:143], v[192:195], v[16:19]
	s_setprio 0
	s_barrier
	s_add_u32 s64, s2, 0x40000
	s_addc_u32 s65, s3, 0
	s_add_i32 s66, s66, s54
	s_mov_b32 m0, s66
	v_lshl_add_u64 v[128:129], s[64:65], 0, v[160:161]
	global_load_lds_dwordx4 v[128:129], off
	s_add_i32 m0, s66, 0x2000
	v_lshl_add_u64 v[128:129], s[64:65], 0, v[162:163]
	global_load_lds_dwordx4 v[128:129], off
	s_waitcnt vmcnt(6)
	s_barrier
	s_setprio 1
	v_mfma_f32_16x16x32_bf16 v[44:47], v[196:199], v[144:147], 0
	v_mfma_f32_16x16x32_bf16 v[40:43], v[210:213], v[144:147], 0
	v_mfma_f32_16x16x32_bf16 v[28:31], v[196:199], v[152:155], 0
	v_mfma_f32_16x16x32_bf16 v[24:27], v[210:213], v[152:155], 0
	v_mfma_f32_16x16x32_bf16 v[12:15], v[196:199], v[180:183], 0
	v_mfma_f32_16x16x32_bf16 v[8:11], v[210:213], v[180:183], 0
	v_mfma_f32_16x16x32_bf16 v[4:7], v[196:199], v[188:191], 0
	v_mfma_f32_16x16x32_bf16 v[0:3], v[210:213], v[188:191], 0
	v_mfma_f32_16x16x32_bf16 v[44:47], v[200:203], v[148:151], v[44:47]
	v_mfma_f32_16x16x32_bf16 v[40:43], v[214:217], v[148:151], v[40:43]
	v_mfma_f32_16x16x32_bf16 v[28:31], v[200:203], v[156:159], v[28:31]
	v_mfma_f32_16x16x32_bf16 v[24:27], v[214:217], v[156:159], v[24:27]
	v_mfma_f32_16x16x32_bf16 v[12:15], v[200:203], v[184:187], v[12:15]
	v_mfma_f32_16x16x32_bf16 v[8:11], v[214:217], v[184:187], v[8:11]
	v_mfma_f32_16x16x32_bf16 v[4:7], v[200:203], v[192:195], v[4:7]
	v_mfma_f32_16x16x32_bf16 v[0:3], v[214:217], v[192:195], v[0:3]
	s_setprio 0
	s_add_i32 s64, 0, 0x18000
	v_add_u32_e32 v140, s64, v208
	s_barrier
	ds_read_b128 v[128:131], v140
	ds_read_b128 v[132:135], v140 offset:1024
	ds_read_b128 v[136:139], v140 offset:2048
	ds_read_b128 v[140:143], v140 offset:3072
	s_add_u32 s8, s8, 0x40000
	s_addc_u32 s9, s9, 0
	s_mov_b32 m0, s56
	v_lshl_add_u64 v[196:197], s[8:9], 0, v[160:161]
	ds_read_b128 v[144:147], v209 offset:32768
	ds_read_b128 v[148:151], v209 offset:33792
	ds_read_b128 v[152:155], v209 offset:34816
	ds_read_b128 v[156:159], v209 offset:35840
	ds_read_b128 v[180:183], v209 offset:36864
	ds_read_b128 v[184:187], v209 offset:37888
	ds_read_b128 v[188:191], v209 offset:38912
	ds_read_b128 v[192:195], v209 offset:39936
	global_load_lds_dwordx4 v[196:197], off
	s_mov_b32 m0, s57
	v_lshl_add_u64 v[196:197], s[8:9], 0, v[162:163]
	global_load_lds_dwordx4 v[196:197], off
	s_waitcnt lgkmcnt(8)
	s_barrier
	s_waitcnt lgkmcnt(0)
	s_setprio 1
	v_mfma_f32_16x16x32_bf16 v[124:127], v[128:131], v[144:147], v[124:127]
	v_mfma_f32_16x16x32_bf16 v[120:123], v[136:139], v[144:147], v[120:123]
	v_mfma_f32_16x16x32_bf16 v[116:119], v[128:131], v[152:155], v[116:119]
	v_mfma_f32_16x16x32_bf16 v[112:115], v[136:139], v[152:155], v[112:115]
	v_mfma_f32_16x16x32_bf16 v[100:103], v[128:131], v[180:183], v[100:103]
	v_mfma_f32_16x16x32_bf16 v[96:99], v[136:139], v[180:183], v[96:99]
	v_mfma_f32_16x16x32_bf16 v[84:87], v[128:131], v[188:191], v[84:87]
	v_mfma_f32_16x16x32_bf16 v[80:83], v[136:139], v[188:191], v[80:83]
	v_mfma_f32_16x16x32_bf16 v[124:127], v[132:135], v[148:151], v[124:127]
	v_mfma_f32_16x16x32_bf16 v[120:123], v[140:143], v[148:151], v[120:123]
	v_mfma_f32_16x16x32_bf16 v[116:119], v[132:135], v[156:159], v[116:119]
	v_mfma_f32_16x16x32_bf16 v[112:115], v[140:143], v[156:159], v[112:115]
	v_mfma_f32_16x16x32_bf16 v[100:103], v[132:135], v[184:187], v[100:103]
	v_mfma_f32_16x16x32_bf16 v[96:99], v[140:143], v[184:187], v[96:99]
	v_mfma_f32_16x16x32_bf16 v[84:87], v[132:135], v[192:195], v[84:87]
	v_mfma_f32_16x16x32_bf16 v[80:83], v[140:143], v[192:195], v[80:83]
	s_setprio 0
	s_barrier
	s_add_i32 s8, 0, 0x1c000
	s_add_i32 s9, s64, s54
	v_add_u32_e32 v168, s8, v208
	v_lshl_add_u64 v[204:205], v[204:205], 0, s[78:79]
	s_mov_b32 m0, s9
	ds_read_b128 v[196:199], v168
	ds_read_b128 v[200:203], v168 offset:1024
	ds_read_b128 v[210:213], v168 offset:2048
	ds_read_b128 v[214:217], v168 offset:3072
	global_load_lds_dwordx4 v[204:205], off
	s_add_i32 m0, s9, 0x2000
	v_lshl_add_u64 v[204:205], v[218:219], 0, s[78:79]
	global_load_lds_dwordx4 v[204:205], off
	s_barrier
	s_waitcnt lgkmcnt(0)
	s_setprio 1
	v_mfma_f32_16x16x32_bf16 v[108:111], v[196:199], v[144:147], v[108:111]
	v_mfma_f32_16x16x32_bf16 v[104:107], v[210:213], v[144:147], v[104:107]
	v_mfma_f32_16x16x32_bf16 v[92:95], v[196:199], v[152:155], v[92:95]
	v_mfma_f32_16x16x32_bf16 v[88:91], v[210:213], v[152:155], v[88:91]
	v_mfma_f32_16x16x32_bf16 v[76:79], v[196:199], v[180:183], v[76:79]
	v_mfma_f32_16x16x32_bf16 v[72:75], v[210:213], v[180:183], v[72:75]
	v_mfma_f32_16x16x32_bf16 v[68:71], v[196:199], v[188:191], v[68:71]
	v_mfma_f32_16x16x32_bf16 v[64:67], v[210:213], v[188:191], v[64:67]
	v_mfma_f32_16x16x32_bf16 v[108:111], v[200:203], v[148:151], v[108:111]
	v_mfma_f32_16x16x32_bf16 v[104:107], v[214:217], v[148:151], v[104:107]
	v_mfma_f32_16x16x32_bf16 v[92:95], v[200:203], v[156:159], v[92:95]
	v_mfma_f32_16x16x32_bf16 v[88:91], v[214:217], v[156:159], v[88:91]
	v_mfma_f32_16x16x32_bf16 v[76:79], v[200:203], v[184:187], v[76:79]
	v_mfma_f32_16x16x32_bf16 v[72:75], v[214:217], v[184:187], v[72:75]
	v_mfma_f32_16x16x32_bf16 v[68:71], v[200:203], v[192:195], v[68:71]
	v_mfma_f32_16x16x32_bf16 v[64:67], v[214:217], v[192:195], v[64:67]
	s_setprio 0
	s_mov_b32 m0, s60
	v_lshl_add_u64 v[204:205], v[220:221], 0, s[78:79]
	s_barrier
	ds_read_b128 v[144:147], v209 offset:49152
	ds_read_b128 v[148:151], v209 offset:50176
	ds_read_b128 v[152:155], v209 offset:51200
	ds_read_b128 v[156:159], v209 offset:52224
	ds_read_b128 v[180:183], v209 offset:53248
	ds_read_b128 v[184:187], v209 offset:54272
	ds_read_b128 v[188:191], v209 offset:55296
	ds_read_b128 v[192:195], v209 offset:56320
	global_load_lds_dwordx4 v[204:205], off
	s_mov_b32 m0, s61
	v_lshl_add_u64 v[204:205], v[222:223], 0, s[78:79]
	global_load_lds_dwordx4 v[204:205], off
	s_barrier
	s_waitcnt lgkmcnt(0)
	s_setprio 1
	v_mfma_f32_16x16x32_bf16 v[60:63], v[128:131], v[144:147], v[60:63]
	v_mfma_f32_16x16x32_bf16 v[56:59], v[136:139], v[144:147], v[56:59]
	v_mfma_f32_16x16x32_bf16 v[52:55], v[128:131], v[152:155], v[52:55]
	v_mfma_f32_16x16x32_bf16 v[48:51], v[136:139], v[152:155], v[48:51]
	v_mfma_f32_16x16x32_bf16 v[36:39], v[128:131], v[180:183], v[36:39]
	v_mfma_f32_16x16x32_bf16 v[32:35], v[136:139], v[180:183], v[32:35]
	v_mfma_f32_16x16x32_bf16 v[20:23], v[128:131], v[188:191], v[20:23]
	v_mfma_f32_16x16x32_bf16 v[16:19], v[136:139], v[188:191], v[16:19]
	v_mfma_f32_16x16x32_bf16 v[60:63], v[132:135], v[148:151], v[60:63]
	v_mfma_f32_16x16x32_bf16 v[56:59], v[140:143], v[148:151], v[56:59]
	v_mfma_f32_16x16x32_bf16 v[52:55], v[132:135], v[156:159], v[52:55]
	v_mfma_f32_16x16x32_bf16 v[48:51], v[140:143], v[156:159], v[48:51]
	v_mfma_f32_16x16x32_bf16 v[36:39], v[132:135], v[184:187], v[36:39]
	v_mfma_f32_16x16x32_bf16 v[32:35], v[140:143], v[184:187], v[32:35]
	v_mfma_f32_16x16x32_bf16 v[20:23], v[132:135], v[192:195], v[20:23]
	v_mfma_f32_16x16x32_bf16 v[16:19], v[140:143], v[192:195], v[16:19]
	s_setprio 0
	s_barrier
	s_add_u32 s2, s2, 0x40080
	s_addc_u32 s3, s3, 0
	s_add_i32 s8, s8, s54
	s_mov_b32 m0, s8
	v_lshl_add_u64 v[128:129], s[2:3], 0, v[160:161]
	global_load_lds_dwordx4 v[128:129], off
	s_add_i32 m0, s8, 0x2000
	v_lshl_add_u64 v[128:129], s[2:3], 0, v[162:163]
	global_load_lds_dwordx4 v[128:129], off
	s_waitcnt vmcnt(6)
	s_barrier
	s_setprio 1
	v_mfma_f32_16x16x32_bf16 v[44:47], v[196:199], v[144:147], v[44:47]
	v_mfma_f32_16x16x32_bf16 v[40:43], v[210:213], v[144:147], v[40:43]
	v_mfma_f32_16x16x32_bf16 v[28:31], v[196:199], v[152:155], v[28:31]
	v_mfma_f32_16x16x32_bf16 v[24:27], v[210:213], v[152:155], v[24:27]
	v_mfma_f32_16x16x32_bf16 v[12:15], v[196:199], v[180:183], v[12:15]
	v_mfma_f32_16x16x32_bf16 v[8:11], v[210:213], v[180:183], v[8:11]
	v_mfma_f32_16x16x32_bf16 v[4:7], v[196:199], v[188:191], v[4:7]
	v_mfma_f32_16x16x32_bf16 v[0:3], v[210:213], v[188:191], v[0:3]
	v_mfma_f32_16x16x32_bf16 v[44:47], v[200:203], v[148:151], v[44:47]
	v_mfma_f32_16x16x32_bf16 v[40:43], v[214:217], v[148:151], v[40:43]
	v_mfma_f32_16x16x32_bf16 v[28:31], v[200:203], v[156:159], v[28:31]
	v_mfma_f32_16x16x32_bf16 v[24:27], v[214:217], v[156:159], v[24:27]
	v_mfma_f32_16x16x32_bf16 v[12:15], v[200:203], v[184:187], v[12:15]
	v_mfma_f32_16x16x32_bf16 v[8:11], v[214:217], v[184:187], v[8:11]
	v_mfma_f32_16x16x32_bf16 v[4:7], v[200:203], v[192:195], v[4:7]
	v_mfma_f32_16x16x32_bf16 v[0:3], v[214:217], v[192:195], v[0:3]
	s_setprio 0
	s_add_i32 s41, s41, 2
	s_add_u32 s6, s6, 0x100
	s_addc_u32 s7, s7, 0
	s_add_u32 s39, s39, 0x100
	s_addc_u32 s40, s40, 0
	s_cmp_gt_u32 s41, 13
	s_barrier
.LBB0_355:
	s_add_u32 s2, s6, 0xfffc0080
	s_addc_u32 s3, s7, -1
	s_add_i32 s64, 0, 0x10000
	v_add_u32_e32 v140, s64, v208
	ds_read_b128 v[128:131], v140
	ds_read_b128 v[132:135], v140 offset:1024
	ds_read_b128 v[136:139], v140 offset:2048
	ds_read_b128 v[140:143], v140 offset:3072
	s_cmp_eq_u32 s41, 12
	s_cselect_b32 s9, s1, s3
	s_cselect_b32 s8, s31, s2
	s_cselect_b32 s3, s29, s40
	s_cselect_b32 s2, s38, s39
	v_lshl_add_u64 v[196:197], s[6:7], 0, v[164:165]
	s_add_i32 m0, s21, 0xc000
	ds_read_b128 v[144:147], v209
	ds_read_b128 v[148:151], v209 offset:1024
	ds_read_b128 v[152:155], v209 offset:2048
	ds_read_b128 v[156:159], v209 offset:3072
	ds_read_b128 v[180:183], v209 offset:4096
	ds_read_b128 v[184:187], v209 offset:5120
	ds_read_b128 v[188:191], v209 offset:6144
	ds_read_b128 v[192:195], v209 offset:7168
	global_load_lds_dwordx4 v[196:197], off
	s_add_i32 m0, s21, 0xe000
	v_lshl_add_u64 v[196:197], s[6:7], 0, v[166:167]
	global_load_lds_dwordx4 v[196:197], off
	s_waitcnt lgkmcnt(8)
	s_barrier
	s_waitcnt lgkmcnt(0)
	s_setprio 1
	v_mfma_f32_16x16x32_bf16 v[124:127], v[128:131], v[144:147], v[124:127]
	v_mfma_f32_16x16x32_bf16 v[120:123], v[136:139], v[144:147], v[120:123]
	v_mfma_f32_16x16x32_bf16 v[116:119], v[128:131], v[152:155], v[116:119]
	v_mfma_f32_16x16x32_bf16 v[112:115], v[136:139], v[152:155], v[112:115]
	v_mfma_f32_16x16x32_bf16 v[100:103], v[128:131], v[180:183], v[100:103]
	v_mfma_f32_16x16x32_bf16 v[96:99], v[136:139], v[180:183], v[96:99]
	v_mfma_f32_16x16x32_bf16 v[84:87], v[128:131], v[188:191], v[84:87]
	v_mfma_f32_16x16x32_bf16 v[80:83], v[136:139], v[188:191], v[80:83]
	v_mfma_f32_16x16x32_bf16 v[124:127], v[132:135], v[148:151], v[124:127]
	v_mfma_f32_16x16x32_bf16 v[120:123], v[140:143], v[148:151], v[120:123]
	v_mfma_f32_16x16x32_bf16 v[116:119], v[132:135], v[156:159], v[116:119]
	v_mfma_f32_16x16x32_bf16 v[112:115], v[140:143], v[156:159], v[112:115]
	v_mfma_f32_16x16x32_bf16 v[100:103], v[132:135], v[184:187], v[100:103]
	v_mfma_f32_16x16x32_bf16 v[96:99], v[140:143], v[184:187], v[96:99]
	v_mfma_f32_16x16x32_bf16 v[84:87], v[132:135], v[192:195], v[84:87]
	v_mfma_f32_16x16x32_bf16 v[80:83], v[140:143], v[192:195], v[80:83]
	s_setprio 0
	s_barrier
	s_add_i32 s66, 0, 0x14000
	s_add_i32 s64, s64, s54
	v_add_u32_e32 v168, s66, v208
	v_lshl_add_u64 v[204:205], s[2:3], 0, v[160:161]
	s_mov_b32 m0, s64
	ds_read_b128 v[196:199], v168
	ds_read_b128 v[200:203], v168 offset:1024
	ds_read_b128 v[210:213], v168 offset:2048
	ds_read_b128 v[214:217], v168 offset:3072
	global_load_lds_dwordx4 v[204:205], off
	s_add_i32 m0, s64, 0x2000
	v_lshl_add_u64 v[218:219], s[2:3], 0, v[162:163]
	global_load_lds_dwordx4 v[218:219], off
	s_barrier
	s_waitcnt lgkmcnt(0)
	s_setprio 1
	v_mfma_f32_16x16x32_bf16 v[108:111], v[196:199], v[144:147], v[108:111]
	v_mfma_f32_16x16x32_bf16 v[104:107], v[210:213], v[144:147], v[104:107]
	v_mfma_f32_16x16x32_bf16 v[92:95], v[196:199], v[152:155], v[92:95]
	v_mfma_f32_16x16x32_bf16 v[88:91], v[210:213], v[152:155], v[88:91]
	v_mfma_f32_16x16x32_bf16 v[76:79], v[196:199], v[180:183], v[76:79]
	v_mfma_f32_16x16x32_bf16 v[72:75], v[210:213], v[180:183], v[72:75]
	v_mfma_f32_16x16x32_bf16 v[68:71], v[196:199], v[188:191], v[68:71]
	v_mfma_f32_16x16x32_bf16 v[64:67], v[210:213], v[188:191], v[64:67]
	v_mfma_f32_16x16x32_bf16 v[108:111], v[200:203], v[148:151], v[108:111]
	v_mfma_f32_16x16x32_bf16 v[104:107], v[214:217], v[148:151], v[104:107]
	v_mfma_f32_16x16x32_bf16 v[92:95], v[200:203], v[156:159], v[92:95]
	v_mfma_f32_16x16x32_bf16 v[88:91], v[214:217], v[156:159], v[88:91]
	v_mfma_f32_16x16x32_bf16 v[76:79], v[200:203], v[184:187], v[76:79]
	v_mfma_f32_16x16x32_bf16 v[72:75], v[214:217], v[184:187], v[72:75]
	v_mfma_f32_16x16x32_bf16 v[68:71], v[200:203], v[192:195], v[68:71]
	v_mfma_f32_16x16x32_bf16 v[64:67], v[214:217], v[192:195], v[64:67]
	s_setprio 0
	s_mov_b32 m0, s21
	v_lshl_add_u64 v[220:221], s[8:9], 0, v[160:161]
	s_barrier
	ds_read_b128 v[144:147], v209 offset:16384
	ds_read_b128 v[148:151], v209 offset:17408
	ds_read_b128 v[152:155], v209 offset:18432
	ds_read_b128 v[156:159], v209 offset:19456
	ds_read_b128 v[180:183], v209 offset:20480
	ds_read_b128 v[184:187], v209 offset:21504
	ds_read_b128 v[188:191], v209 offset:22528
	ds_read_b128 v[192:195], v209 offset:23552
	global_load_lds_dwordx4 v[220:221], off
	s_mov_b32 m0, s55
	v_lshl_add_u64 v[222:223], s[8:9], 0, v[162:163]
	global_load_lds_dwordx4 v[222:223], off
	s_barrier
	s_waitcnt lgkmcnt(0)
	s_setprio 1
	v_mfma_f32_16x16x32_bf16 v[60:63], v[128:131], v[144:147], v[60:63]
	v_mfma_f32_16x16x32_bf16 v[56:59], v[136:139], v[144:147], v[56:59]
	v_mfma_f32_16x16x32_bf16 v[52:55], v[128:131], v[152:155], v[52:55]
	v_mfma_f32_16x16x32_bf16 v[48:51], v[136:139], v[152:155], v[48:51]
	v_mfma_f32_16x16x32_bf16 v[36:39], v[128:131], v[180:183], v[36:39]
	v_mfma_f32_16x16x32_bf16 v[32:35], v[136:139], v[180:183], v[32:35]
	v_mfma_f32_16x16x32_bf16 v[20:23], v[128:131], v[188:191], v[20:23]
	v_mfma_f32_16x16x32_bf16 v[16:19], v[136:139], v[188:191], v[16:19]
	v_mfma_f32_16x16x32_bf16 v[60:63], v[132:135], v[148:151], v[60:63]
	v_mfma_f32_16x16x32_bf16 v[56:59], v[140:143], v[148:151], v[56:59]
	v_mfma_f32_16x16x32_bf16 v[52:55], v[132:135], v[156:159], v[52:55]
	v_mfma_f32_16x16x32_bf16 v[48:51], v[140:143], v[156:159], v[48:51]
	v_mfma_f32_16x16x32_bf16 v[36:39], v[132:135], v[184:187], v[36:39]
	v_mfma_f32_16x16x32_bf16 v[32:35], v[140:143], v[184:187], v[32:35]
	v_mfma_f32_16x16x32_bf16 v[20:23], v[132:135], v[192:195], v[20:23]
	v_mfma_f32_16x16x32_bf16 v[16:19], v[140:143], v[192:195], v[16:19]
	s_setprio 0
	s_barrier
	s_add_u32 s64, s2, 0x40000
	s_addc_u32 s65, s3, 0
	s_add_i32 s66, s66, s54
	s_mov_b32 m0, s66
	v_lshl_add_u64 v[128:129], s[64:65], 0, v[160:161]
	global_load_lds_dwordx4 v[128:129], off
	s_add_i32 m0, s66, 0x2000
	v_lshl_add_u64 v[128:129], s[64:65], 0, v[162:163]
	global_load_lds_dwordx4 v[128:129], off
	s_waitcnt vmcnt(6)
	s_barrier
	s_setprio 1
	v_mfma_f32_16x16x32_bf16 v[44:47], v[196:199], v[144:147], v[44:47]
	v_mfma_f32_16x16x32_bf16 v[40:43], v[210:213], v[144:147], v[40:43]
	v_mfma_f32_16x16x32_bf16 v[28:31], v[196:199], v[152:155], v[28:31]
	v_mfma_f32_16x16x32_bf16 v[24:27], v[210:213], v[152:155], v[24:27]
	v_mfma_f32_16x16x32_bf16 v[12:15], v[196:199], v[180:183], v[12:15]
	v_mfma_f32_16x16x32_bf16 v[8:11], v[210:213], v[180:183], v[8:11]
	v_mfma_f32_16x16x32_bf16 v[4:7], v[196:199], v[188:191], v[4:7]
	v_mfma_f32_16x16x32_bf16 v[0:3], v[210:213], v[188:191], v[0:3]
	v_mfma_f32_16x16x32_bf16 v[44:47], v[200:203], v[148:151], v[44:47]
	v_mfma_f32_16x16x32_bf16 v[40:43], v[214:217], v[148:151], v[40:43]
	v_mfma_f32_16x16x32_bf16 v[28:31], v[200:203], v[156:159], v[28:31]
	v_mfma_f32_16x16x32_bf16 v[24:27], v[214:217], v[156:159], v[24:27]
	v_mfma_f32_16x16x32_bf16 v[12:15], v[200:203], v[184:187], v[12:15]
	v_mfma_f32_16x16x32_bf16 v[8:11], v[214:217], v[184:187], v[8:11]
	v_mfma_f32_16x16x32_bf16 v[4:7], v[200:203], v[192:195], v[4:7]
	v_mfma_f32_16x16x32_bf16 v[0:3], v[214:217], v[192:195], v[0:3]
	s_setprio 0
	s_add_i32 s64, 0, 0x18000
	v_add_u32_e32 v140, s64, v208
	s_barrier
	ds_read_b128 v[128:131], v140
	ds_read_b128 v[132:135], v140 offset:1024
	ds_read_b128 v[136:139], v140 offset:2048
	ds_read_b128 v[140:143], v140 offset:3072
	s_add_u32 s8, s8, 0x40000
	s_addc_u32 s9, s9, 0
	s_mov_b32 m0, s56
	v_lshl_add_u64 v[196:197], s[8:9], 0, v[160:161]
	ds_read_b128 v[144:147], v209 offset:32768
	ds_read_b128 v[148:151], v209 offset:33792
	ds_read_b128 v[152:155], v209 offset:34816
	ds_read_b128 v[156:159], v209 offset:35840
	ds_read_b128 v[180:183], v209 offset:36864
	ds_read_b128 v[184:187], v209 offset:37888
	ds_read_b128 v[188:191], v209 offset:38912
	ds_read_b128 v[192:195], v209 offset:39936
	global_load_lds_dwordx4 v[196:197], off
	s_mov_b32 m0, s57
	v_lshl_add_u64 v[196:197], s[8:9], 0, v[162:163]
	global_load_lds_dwordx4 v[196:197], off
	s_waitcnt lgkmcnt(8)
	s_barrier
	s_waitcnt lgkmcnt(0)
	s_setprio 1
	v_mfma_f32_16x16x32_bf16 v[124:127], v[128:131], v[144:147], v[124:127]
	v_mfma_f32_16x16x32_bf16 v[120:123], v[136:139], v[144:147], v[120:123]
	v_mfma_f32_16x16x32_bf16 v[116:119], v[128:131], v[152:155], v[116:119]
	v_mfma_f32_16x16x32_bf16 v[112:115], v[136:139], v[152:155], v[112:115]
	v_mfma_f32_16x16x32_bf16 v[100:103], v[128:131], v[180:183], v[100:103]
	v_mfma_f32_16x16x32_bf16 v[96:99], v[136:139], v[180:183], v[96:99]
	v_mfma_f32_16x16x32_bf16 v[84:87], v[128:131], v[188:191], v[84:87]
	v_mfma_f32_16x16x32_bf16 v[80:83], v[136:139], v[188:191], v[80:83]
	v_mfma_f32_16x16x32_bf16 v[124:127], v[132:135], v[148:151], v[124:127]
	v_mfma_f32_16x16x32_bf16 v[120:123], v[140:143], v[148:151], v[120:123]
	v_mfma_f32_16x16x32_bf16 v[116:119], v[132:135], v[156:159], v[116:119]
	v_mfma_f32_16x16x32_bf16 v[112:115], v[140:143], v[156:159], v[112:115]
	v_mfma_f32_16x16x32_bf16 v[100:103], v[132:135], v[184:187], v[100:103]
	v_mfma_f32_16x16x32_bf16 v[96:99], v[140:143], v[184:187], v[96:99]
	v_mfma_f32_16x16x32_bf16 v[84:87], v[132:135], v[192:195], v[84:87]
	v_mfma_f32_16x16x32_bf16 v[80:83], v[140:143], v[192:195], v[80:83]
	s_setprio 0
	s_barrier
	s_add_i32 s8, 0, 0x1c000
	s_add_i32 s9, s64, s54
	v_add_u32_e32 v168, s8, v208
	v_lshl_add_u64 v[204:205], v[204:205], 0, s[78:79]
	s_mov_b32 m0, s9
	ds_read_b128 v[196:199], v168
	ds_read_b128 v[200:203], v168 offset:1024
	ds_read_b128 v[210:213], v168 offset:2048
	ds_read_b128 v[214:217], v168 offset:3072
	global_load_lds_dwordx4 v[204:205], off
	s_add_i32 m0, s9, 0x2000
	v_lshl_add_u64 v[204:205], v[218:219], 0, s[78:79]
	global_load_lds_dwordx4 v[204:205], off
	s_barrier
	s_waitcnt lgkmcnt(0)
	s_setprio 1
	v_mfma_f32_16x16x32_bf16 v[108:111], v[196:199], v[144:147], v[108:111]
	v_mfma_f32_16x16x32_bf16 v[104:107], v[210:213], v[144:147], v[104:107]
	v_mfma_f32_16x16x32_bf16 v[92:95], v[196:199], v[152:155], v[92:95]
	v_mfma_f32_16x16x32_bf16 v[88:91], v[210:213], v[152:155], v[88:91]
	v_mfma_f32_16x16x32_bf16 v[76:79], v[196:199], v[180:183], v[76:79]
	v_mfma_f32_16x16x32_bf16 v[72:75], v[210:213], v[180:183], v[72:75]
	v_mfma_f32_16x16x32_bf16 v[68:71], v[196:199], v[188:191], v[68:71]
	v_mfma_f32_16x16x32_bf16 v[64:67], v[210:213], v[188:191], v[64:67]
	v_mfma_f32_16x16x32_bf16 v[108:111], v[200:203], v[148:151], v[108:111]
	v_mfma_f32_16x16x32_bf16 v[104:107], v[214:217], v[148:151], v[104:107]
	v_mfma_f32_16x16x32_bf16 v[92:95], v[200:203], v[156:159], v[92:95]
	v_mfma_f32_16x16x32_bf16 v[88:91], v[214:217], v[156:159], v[88:91]
	v_mfma_f32_16x16x32_bf16 v[76:79], v[200:203], v[184:187], v[76:79]
	v_mfma_f32_16x16x32_bf16 v[72:75], v[214:217], v[184:187], v[72:75]
	v_mfma_f32_16x16x32_bf16 v[68:71], v[200:203], v[192:195], v[68:71]
	v_mfma_f32_16x16x32_bf16 v[64:67], v[214:217], v[192:195], v[64:67]
	s_setprio 0
	s_mov_b32 m0, s60
	v_lshl_add_u64 v[204:205], v[220:221], 0, s[78:79]
	s_barrier
	ds_read_b128 v[144:147], v209 offset:49152
	ds_read_b128 v[148:151], v209 offset:50176
	ds_read_b128 v[152:155], v209 offset:51200
	ds_read_b128 v[156:159], v209 offset:52224
	ds_read_b128 v[180:183], v209 offset:53248
	ds_read_b128 v[184:187], v209 offset:54272
	ds_read_b128 v[188:191], v209 offset:55296
	ds_read_b128 v[192:195], v209 offset:56320
	global_load_lds_dwordx4 v[204:205], off
	s_mov_b32 m0, s61
	v_lshl_add_u64 v[204:205], v[222:223], 0, s[78:79]
	global_load_lds_dwordx4 v[204:205], off
	s_barrier
	s_waitcnt lgkmcnt(0)
	s_setprio 1
	v_mfma_f32_16x16x32_bf16 v[60:63], v[128:131], v[144:147], v[60:63]
	v_mfma_f32_16x16x32_bf16 v[56:59], v[136:139], v[144:147], v[56:59]
	v_mfma_f32_16x16x32_bf16 v[52:55], v[128:131], v[152:155], v[52:55]
	v_mfma_f32_16x16x32_bf16 v[48:51], v[136:139], v[152:155], v[48:51]
	v_mfma_f32_16x16x32_bf16 v[36:39], v[128:131], v[180:183], v[36:39]
	v_mfma_f32_16x16x32_bf16 v[32:35], v[136:139], v[180:183], v[32:35]
	v_mfma_f32_16x16x32_bf16 v[20:23], v[128:131], v[188:191], v[20:23]
	v_mfma_f32_16x16x32_bf16 v[16:19], v[136:139], v[188:191], v[16:19]
	v_mfma_f32_16x16x32_bf16 v[60:63], v[132:135], v[148:151], v[60:63]
	v_mfma_f32_16x16x32_bf16 v[56:59], v[140:143], v[148:151], v[56:59]
	v_mfma_f32_16x16x32_bf16 v[52:55], v[132:135], v[156:159], v[52:55]
	v_mfma_f32_16x16x32_bf16 v[48:51], v[140:143], v[156:159], v[48:51]
	v_mfma_f32_16x16x32_bf16 v[36:39], v[132:135], v[184:187], v[36:39]
	v_mfma_f32_16x16x32_bf16 v[32:35], v[140:143], v[184:187], v[32:35]
	v_mfma_f32_16x16x32_bf16 v[20:23], v[132:135], v[192:195], v[20:23]
	v_mfma_f32_16x16x32_bf16 v[16:19], v[140:143], v[192:195], v[16:19]
	s_setprio 0
	s_barrier
	s_add_u32 s2, s2, 0x40080
	s_addc_u32 s3, s3, 0
	s_add_i32 s8, s8, s54
	s_mov_b32 m0, s8
	v_lshl_add_u64 v[128:129], s[2:3], 0, v[160:161]
	global_load_lds_dwordx4 v[128:129], off
	s_add_i32 m0, s8, 0x2000
	v_lshl_add_u64 v[128:129], s[2:3], 0, v[162:163]
	global_load_lds_dwordx4 v[128:129], off
	s_waitcnt vmcnt(6)
	s_barrier
	s_setprio 1
	v_mfma_f32_16x16x32_bf16 v[44:47], v[196:199], v[144:147], v[44:47]
	v_mfma_f32_16x16x32_bf16 v[40:43], v[210:213], v[144:147], v[40:43]
	v_mfma_f32_16x16x32_bf16 v[28:31], v[196:199], v[152:155], v[28:31]
	v_mfma_f32_16x16x32_bf16 v[24:27], v[210:213], v[152:155], v[24:27]
	v_mfma_f32_16x16x32_bf16 v[12:15], v[196:199], v[180:183], v[12:15]
	v_mfma_f32_16x16x32_bf16 v[8:11], v[210:213], v[180:183], v[8:11]
	v_mfma_f32_16x16x32_bf16 v[4:7], v[196:199], v[188:191], v[4:7]
	v_mfma_f32_16x16x32_bf16 v[0:3], v[210:213], v[188:191], v[0:3]
	v_mfma_f32_16x16x32_bf16 v[44:47], v[200:203], v[148:151], v[44:47]
	v_mfma_f32_16x16x32_bf16 v[40:43], v[214:217], v[148:151], v[40:43]
	v_mfma_f32_16x16x32_bf16 v[28:31], v[200:203], v[156:159], v[28:31]
	v_mfma_f32_16x16x32_bf16 v[24:27], v[214:217], v[156:159], v[24:27]
	v_mfma_f32_16x16x32_bf16 v[12:15], v[200:203], v[184:187], v[12:15]
	v_mfma_f32_16x16x32_bf16 v[8:11], v[214:217], v[184:187], v[8:11]
	v_mfma_f32_16x16x32_bf16 v[4:7], v[200:203], v[192:195], v[4:7]
	v_mfma_f32_16x16x32_bf16 v[0:3], v[214:217], v[192:195], v[0:3]
	s_setprio 0
	s_add_i32 s41, s41, 2
	s_add_u32 s6, s6, 0x100
	s_addc_u32 s7, s7, 0
	s_add_u32 s39, s39, 0x100
	s_addc_u32 s40, s40, 0
	s_cmp_gt_u32 s41, 13
	s_barrier
	s_cbranch_scc0 .LBB0_355
	s_lshl_b32 s1, s0, 8
	v_mov_b32_e32 v211, v206
	v_mov_b32_e32 v210, v207
	s_add_i32 s1, s1, s59
	s_cmp_lt_i32 s20, 3
	v_add_u32_e32 v180, s1, v211
	s_mov_b64 s[2:3], -1
	s_cbranch_scc0 .LBB0_490
	s_cmp_gt_i32 s0, 15
	s_cselect_b64 s[2:3], -1, 0
	s_cmp_lt_i32 s0, 16
	s_cselect_b64 s[38:39], -1, 0
	s_cmp_eq_u32 s20, 2
	s_cselect_b64 s[8:9], -1, 0
	s_cmp_lg_u32 s20, 2
	s_cselect_b64 s[0:1], -1, 0
	s_and_b64 s[40:41], s[8:9], s[22:23]
	v_lshlrev_b32_e32 v182, 2, v210
	s_mov_b64 s[6:7], -1
	s_and_b64 vcc, exec, s[40:41]
	v_ashrrev_i32_e32 v183, 31, v182
	s_cbranch_vccnz .LBB0_447
	s_and_b64 s[6:7], s[8:9], exec
	s_cselect_b32 s6, s46, s44
	s_cselect_b32 s7, s47, s45
	v_mov_b32_e32 v128, s7
	v_mov_b32_e32 v129, s6
	v_lshl_add_u64 v[128:129], v[182:183], 2, v[128:129]
	global_load_dwordx4 v[140:143], v[128:129], off
	global_load_dwordx4 v[136:139], v[128:129], off offset:64
	global_load_dwordx4 v[132:135], v[128:129], off offset:128
	s_nop 0
	global_load_dwordx4 v[128:131], v[128:129], off offset:192
	v_mul_f32_e32 v144, v125, v125
	v_mul_f32_e32 v145, v127, v127
	v_fmac_f32_e32 v144, v124, v124
	v_fmac_f32_e32 v145, v126, v126
	v_add_f32_e32 v144, v144, v145
	v_mul_f32_e32 v145, v121, v121
	v_mul_f32_e32 v146, v123, v123
	v_fmac_f32_e32 v145, v120, v120
	v_fmac_f32_e32 v146, v122, v122
	v_add_f32_e32 v145, v145, v146
	v_add_f32_e32 v144, v144, v145
	v_mul_f32_e32 v145, v109, v109
	v_mul_f32_e32 v146, v111, v111
	v_fmac_f32_e32 v145, v108, v108
	v_fmac_f32_e32 v146, v110, v110
	v_add_f32_e32 v145, v145, v146
	v_add_f32_e32 v144, v144, v145
	v_mul_f32_e32 v145, v105, v105
	v_mul_f32_e32 v146, v107, v107
	v_fmac_f32_e32 v145, v104, v104
	v_fmac_f32_e32 v146, v106, v106
	v_add_f32_e32 v145, v145, v146
	v_add_f32_e32 v144, v144, v145
	v_mov_b32_e32 v145, v144
	s_nop 1
	v_permlane16_swap_b32_e32 v144, v145
	v_add_f32_e32 v144, v144, v145
	v_mov_b32_e32 v145, v144
	s_nop 1
	v_permlane32_swap_b32_e32 v144, v145
	v_add_f32_e32 v144, v144, v145
	v_fmamk_f32 v144, v144, 0x3c800000, v225
	v_cmp_gt_f32_e32 vcc, s93, v144
	v_mul_f32_e32 v145, 0x4b800000, v144
	v_and_b32_e32 v202, 63, v211
	v_cndmask_b32_e32 v144, v144, v145, vcc
	v_rsq_f32_e32 v144, v144
	v_cndmask_b32_e64 v168, 0, 1, s[2:3]
	v_cmp_ne_u32_e64 s[6:7], 1, v168
	v_lshlrev_b32_e32 v186, 7, v202
	v_mul_f32_e32 v145, 0x45800000, v144
	v_cndmask_b32_e32 v152, v144, v145, vcc
	v_pk_mul_f32 v[144:145], v[124:125], v[152:153] op_sel_hi:[1,0]
	v_pk_mul_f32 v[146:147], v[126:127], v[152:153] op_sel_hi:[1,0]
	v_pk_mul_f32 v[148:149], v[108:109], v[152:153] op_sel_hi:[1,0]
	v_pk_mul_f32 v[150:151], v[110:111], v[152:153] op_sel_hi:[1,0]
	v_pk_mul_f32 v[184:185], v[104:105], v[152:153] op_sel_hi:[1,0]
	s_andn2_b64 vcc, exec, s[2:3]
	s_waitcnt vmcnt(0)
	v_pk_mul_f32 v[158:159], v[142:143], v[146:147]
	v_pk_mul_f32 v[156:157], v[140:141], v[144:145]
	v_pk_mul_f32 v[144:145], v[120:121], v[152:153] op_sel_hi:[1,0]
	v_pk_mul_f32 v[146:147], v[122:123], v[152:153] op_sel_hi:[1,0]
	v_pk_mul_f32 v[152:153], v[106:107], v[152:153] op_sel_hi:[1,0]
	v_pk_mul_f32 v[146:147], v[138:139], v[146:147]
	v_pk_mul_f32 v[144:145], v[136:137], v[144:145]
	v_pk_mul_f32 v[150:151], v[134:135], v[150:151]
	v_pk_mul_f32 v[148:149], v[132:133], v[148:149]
	v_pk_mul_f32 v[154:155], v[130:131], v[152:153]
	v_pk_mul_f32 v[152:153], v[128:129], v[184:185]
	v_lshl_add_u64 v[184:185], v[182:183], 3, s[18:19]
	s_cbranch_vccnz .LBB0_360
	v_lshlrev_b32_e32 v168, 1, v180
	v_and_b32_e32 v168, 0xf80, v168
	v_lshl_add_u64 v[188:189], v[184:185], 0, v[168:169]
	global_load_dwordx4 v[190:193], v[188:189], off offset:16
	global_load_dwordx4 v[194:197], v[188:189], off
	v_mov_b32_e32 v187, v169
	s_waitcnt vmcnt(0)
	v_mul_f32_e32 v198, v158, v190
	v_mov_b32_e32 v188, v194
	v_mov_b32_e32 v189, v196
	v_mov_b32_e32 v196, v195
	v_mul_f32_e32 v200, v146, v191
	v_mul_f32_e32 v204, v146, v190
	v_mul_f32_e32 v212, v158, v191
	v_mov_b32_e32 v146, v159
	v_mov_b32_e32 v158, v147
	v_pk_mul_f32 v[194:195], v[144:145], v[196:197]
	v_pk_mul_f32 v[144:145], v[144:145], v[188:189]
	v_pk_mul_f32 v[190:191], v[146:147], v[192:193]
	v_pk_mul_f32 v[146:147], v[158:159], v[192:193]
	v_lshl_add_u64 v[192:193], v[184:185], 0, v[186:187]
	v_mov_b32_e32 v199, v190
	v_mov_b32_e32 v201, v191
	v_pk_fma_f32 v[190:191], v[156:157], v[188:189], v[194:195] neg_lo:[0,0,1] neg_hi:[0,0,1]
	v_pk_fma_f32 v[144:145], v[156:157], v[196:197], v[144:145]
	global_load_dwordx4 v[156:159], v[192:193], off offset:16
	s_nop 0
	global_load_dwordx4 v[192:195], v[192:193], off
	v_pk_add_f32 v[188:189], v[198:199], v[200:201] neg_lo:[0,1] neg_hi:[0,1]
	v_mov_b32_e32 v213, v147
	v_mov_b32_e32 v205, v146
	v_pk_add_f32 v[146:147], v[212:213], v[204:205]
	s_waitcnt vmcnt(0)
	v_mul_f32_e32 v198, v150, v156
	v_mul_f32_e32 v200, v154, v157
	v_mul_f32_e32 v156, v154, v156
	v_mov_b32_e32 v154, v151
	v_mov_b32_e32 v197, v194
	v_mov_b32_e32 v194, v193
	v_mul_f32_e32 v204, v150, v157
	v_pk_mul_f32 v[212:213], v[154:155], v[158:159]
	v_mov_b32_e32 v150, v155
	v_mov_b32_e32 v196, v192
	v_pk_mul_f32 v[192:193], v[152:153], v[194:195]
	v_mov_b32_e32 v199, v212
	v_mov_b32_e32 v201, v213
	v_pk_mul_f32 v[150:151], v[150:151], v[158:159]
	v_pk_mul_f32 v[152:153], v[152:153], v[196:197]
	v_pk_fma_f32 v[192:193], v[148:149], v[196:197], v[192:193] neg_lo:[0,0,1] neg_hi:[0,0,1]
	v_pk_add_f32 v[196:197], v[198:199], v[200:201] neg_lo:[0,1] neg_hi:[0,1]
	v_mov_b32_e32 v205, v151
	v_mov_b32_e32 v157, v150
	v_pk_fma_f32 v[152:153], v[148:149], v[194:195], v[152:153]
	v_pk_add_f32 v[154:155], v[204:205], v[156:157]
	v_mov_b32_e32 v148, v192
	v_mov_b32_e32 v149, v193
	v_mov_b32_e32 v150, v196
	v_mov_b32_e32 v151, v197
	v_mov_b32_e32 v156, v190
	v_mov_b32_e32 v157, v191
	v_mov_b32_e32 v158, v188
	v_mov_b32_e32 v159, v189

.LBB0_677:
	s_ashr_i32 s23, s22, 31
	v_cmp_lt_i64_e32 vcc, s[24:25], v[174:175]
	s_lshl_b64 s[24:25], s[22:23], 19
	s_add_u32 s24, s36, s24
	s_addc_u32 s25, s37, s25
	s_and_b64 s[26:27], vcc, exec
	s_cselect_b32 s1, s25, s9
	s_cselect_b32 s7, s24, s8
	s_ashr_i32 s21, s20, 31
	s_lshl_b64 s[26:27], s[20:21], 19
	s_add_u32 s26, s38, s26
	s_addc_u32 s27, s39, s27
	s_and_b64 s[28:29], vcc, exec
	s_cselect_b32 s21, s27, s3
	s_cselect_b32 s23, s26, s2
	s_add_u32 s8, s8, 0x40080
	s_addc_u32 s9, s9, 0
	s_add_u32 s56, s2, 0x100
	s_addc_u32 s57, s3, 0
	s_mov_b32 s58, -2
	s_add_u32 s2, s8, 0xfffc0080
	s_addc_u32 s3, s9, -1
	s_add_i32 s59, 0, 0x10000
	v_add_u32_e32 v68, s59, v206
	ds_read_b128 v[48:51], v68
	ds_read_b128 v[52:55], v68 offset:1024
	ds_read_b128 v[60:63], v68 offset:2048
	ds_read_b128 v[68:71], v68 offset:3072
	s_cmp_eq_u32 s58, 12
	s_cselect_b32 s29, s1, s3
	s_cselect_b32 s28, s7, s2
	s_cselect_b32 s3, s21, s57
	s_cselect_b32 s2, s23, s56
	v_lshl_add_u64 v[200:201], s[8:9], 0, v[188:189]
	s_add_i32 m0, s41, 0xc000
	ds_read_b128 v[72:75], v207
	ds_read_b128 v[76:79], v207 offset:1024
	ds_read_b128 v[80:83], v207 offset:2048
	ds_read_b128 v[84:87], v207 offset:3072
	ds_read_b128 v[160:163], v207 offset:4096
	ds_read_b128 v[164:167], v207 offset:5120
	ds_read_b128 v[192:195], v207 offset:6144
	ds_read_b128 v[196:199], v207 offset:7168
	global_load_lds_dwordx4 v[200:201], off
	s_add_i32 m0, s41, 0xe000
	v_lshl_add_u64 v[200:201], s[8:9], 0, v[190:191]
	global_load_lds_dwordx4 v[200:201], off
	s_waitcnt lgkmcnt(8)
	s_barrier
	s_waitcnt lgkmcnt(0)
	s_setprio 1
	v_mfma_f32_16x16x32_bf16 v[156:159], v[48:51], v[72:75], 0
	v_mfma_f32_16x16x32_bf16 v[152:155], v[60:63], v[72:75], 0
	v_mfma_f32_16x16x32_bf16 v[140:143], v[48:51], v[80:83], 0
	v_mfma_f32_16x16x32_bf16 v[136:139], v[60:63], v[80:83], 0
	v_mfma_f32_16x16x32_bf16 v[124:127], v[48:51], v[160:163], 0
	v_mfma_f32_16x16x32_bf16 v[120:123], v[60:63], v[160:163], 0
	v_mfma_f32_16x16x32_bf16 v[108:111], v[48:51], v[192:195], 0
	v_mfma_f32_16x16x32_bf16 v[104:107], v[60:63], v[192:195], 0
	v_mfma_f32_16x16x32_bf16 v[156:159], v[52:55], v[76:79], v[156:159]
	v_mfma_f32_16x16x32_bf16 v[152:155], v[68:71], v[76:79], v[152:155]
	v_mfma_f32_16x16x32_bf16 v[140:143], v[52:55], v[84:87], v[140:143]
	v_mfma_f32_16x16x32_bf16 v[136:139], v[68:71], v[84:87], v[136:139]
	v_mfma_f32_16x16x32_bf16 v[124:127], v[52:55], v[164:167], v[124:127]
	v_mfma_f32_16x16x32_bf16 v[120:123], v[68:71], v[164:167], v[120:123]
	v_mfma_f32_16x16x32_bf16 v[108:111], v[52:55], v[196:199], v[108:111]
	v_mfma_f32_16x16x32_bf16 v[104:107], v[68:71], v[196:199], v[104:107]
	s_setprio 0
	s_barrier
	s_add_i32 s62, 0, 0x14000
	s_add_i32 s59, s59, s40
	v_add_u32_e32 v168, s62, v206
	v_lshl_add_u64 v[240:241], s[2:3], 0, v[182:183]
	s_mov_b32 m0, s59
	ds_read_b128 v[200:203], v168
	ds_read_b128 v[208:211], v168 offset:1024
	ds_read_b128 v[212:215], v168 offset:2048
	ds_read_b128 v[216:219], v168 offset:3072
	global_load_lds_dwordx4 v[240:241], off
	s_add_i32 m0, s59, 0x2000
	v_lshl_add_u64 v[242:243], s[2:3], 0, v[186:187]
	global_load_lds_dwordx4 v[242:243], off
	s_barrier
	s_waitcnt lgkmcnt(0)
	s_setprio 1
	v_mfma_f32_16x16x32_bf16 v[148:151], v[200:203], v[72:75], 0
	v_mfma_f32_16x16x32_bf16 v[72:75], v[212:215], v[72:75], 0
	v_mfma_f32_16x16x32_bf16 v[148:151], v[208:211], v[76:79], v[148:151]
	v_mfma_f32_16x16x32_bf16 v[72:75], v[216:219], v[76:79], v[72:75]
	v_mfma_f32_16x16x32_bf16 v[76:79], v[200:203], v[80:83], 0
	v_mfma_f32_16x16x32_bf16 v[80:83], v[212:215], v[80:83], 0
	v_mfma_f32_16x16x32_bf16 v[112:115], v[212:215], v[160:163], 0
	v_mfma_f32_16x16x32_bf16 v[100:103], v[200:203], v[192:195], 0
	v_mfma_f32_16x16x32_bf16 v[96:99], v[212:215], v[192:195], 0
	v_mfma_f32_16x16x32_bf16 v[76:79], v[208:211], v[84:87], v[76:79]
	v_mfma_f32_16x16x32_bf16 v[80:83], v[216:219], v[84:87], v[80:83]
	v_mfma_f32_16x16x32_bf16 v[84:87], v[200:203], v[160:163], 0
	v_mfma_f32_16x16x32_bf16 v[112:115], v[216:219], v[164:167], v[112:115]
	v_mfma_f32_16x16x32_bf16 v[100:103], v[208:211], v[196:199], v[100:103]
	v_mfma_f32_16x16x32_bf16 v[96:99], v[216:219], v[196:199], v[96:99]
	v_mfma_f32_16x16x32_bf16 v[84:87], v[208:211], v[164:167], v[84:87]
	s_setprio 0
	s_mov_b32 m0, s41
	v_lshl_add_u64 v[244:245], s[28:29], 0, v[180:181]
	s_barrier
	ds_read_b128 v[116:119], v207 offset:16384
	ds_read_b128 v[128:131], v207 offset:17408
	ds_read_b128 v[132:135], v207 offset:18432
	ds_read_b128 v[144:147], v207 offset:19456
	ds_read_b128 v[160:163], v207 offset:20480
	ds_read_b128 v[164:167], v207 offset:21504
	ds_read_b128 v[192:195], v207 offset:22528
	ds_read_b128 v[196:199], v207 offset:23552
	global_load_lds_dwordx4 v[244:245], off
	s_mov_b32 m0, s42
	v_lshl_add_u64 v[246:247], s[28:29], 0, v[184:185]
	global_load_lds_dwordx4 v[246:247], off
	s_barrier
	s_waitcnt lgkmcnt(0)
	s_setprio 1
	v_mfma_f32_16x16x32_bf16 v[92:95], v[48:51], v[116:119], 0
	v_mfma_f32_16x16x32_bf16 v[88:91], v[60:63], v[116:119], 0
	v_mfma_f32_16x16x32_bf16 v[44:47], v[48:51], v[132:135], 0
	v_mfma_f32_16x16x32_bf16 v[40:43], v[60:63], v[132:135], 0
	v_mfma_f32_16x16x32_bf16 v[28:31], v[48:51], v[160:163], 0
	v_mfma_f32_16x16x32_bf16 v[24:27], v[60:63], v[160:163], 0
	v_mfma_f32_16x16x32_bf16 v[12:15], v[48:51], v[192:195], 0
	v_mfma_f32_16x16x32_bf16 v[8:11], v[60:63], v[192:195], 0
	v_mfma_f32_16x16x32_bf16 v[92:95], v[52:55], v[128:131], v[92:95]
	v_mfma_f32_16x16x32_bf16 v[88:91], v[68:71], v[128:131], v[88:91]
	v_mfma_f32_16x16x32_bf16 v[44:47], v[52:55], v[144:147], v[44:47]
	v_mfma_f32_16x16x32_bf16 v[40:43], v[68:71], v[144:147], v[40:43]
	v_mfma_f32_16x16x32_bf16 v[28:31], v[52:55], v[164:167], v[28:31]
	v_mfma_f32_16x16x32_bf16 v[24:27], v[68:71], v[164:167], v[24:27]
	v_mfma_f32_16x16x32_bf16 v[12:15], v[52:55], v[196:199], v[12:15]
	v_mfma_f32_16x16x32_bf16 v[8:11], v[68:71], v[196:199], v[8:11]
	s_setprio 0
	s_barrier
	s_add_u32 s60, s2, 0x40000
	s_addc_u32 s61, s3, 0
	s_add_i32 s59, s62, s40
	s_mov_b32 m0, s59
	v_lshl_add_u64 v[48:49], s[60:61], 0, v[182:183]
	global_load_lds_dwordx4 v[48:49], off
	s_add_i32 m0, s59, 0x2000
	v_lshl_add_u64 v[48:49], s[60:61], 0, v[186:187]
	global_load_lds_dwordx4 v[48:49], off
	s_waitcnt vmcnt(6)
	s_barrier
	s_setprio 1
	v_mfma_f32_16x16x32_bf16 v[36:39], v[200:203], v[132:135], 0
	v_mfma_f32_16x16x32_bf16 v[32:35], v[212:215], v[132:135], 0
	v_mfma_f32_16x16x32_bf16 v[20:23], v[200:203], v[160:163], 0
	v_mfma_f32_16x16x32_bf16 v[16:19], v[212:215], v[160:163], 0
	v_mfma_f32_16x16x32_bf16 v[4:7], v[200:203], v[192:195], 0
	v_mfma_f32_16x16x32_bf16 v[0:3], v[212:215], v[192:195], 0
	v_mfma_f32_16x16x32_bf16 v[48:51], v[200:203], v[116:119], 0
	v_mfma_f32_16x16x32_bf16 v[52:55], v[212:215], v[116:119], 0
	v_mfma_f32_16x16x32_bf16 v[36:39], v[208:211], v[144:147], v[36:39]
	v_mfma_f32_16x16x32_bf16 v[32:35], v[216:219], v[144:147], v[32:35]
	v_mfma_f32_16x16x32_bf16 v[20:23], v[208:211], v[164:167], v[20:23]
	v_mfma_f32_16x16x32_bf16 v[16:19], v[216:219], v[164:167], v[16:19]
	v_mfma_f32_16x16x32_bf16 v[4:7], v[208:211], v[196:199], v[4:7]
	v_mfma_f32_16x16x32_bf16 v[0:3], v[216:219], v[196:199], v[0:3]
	v_mfma_f32_16x16x32_bf16 v[48:51], v[208:211], v[128:131], v[48:51]
	v_mfma_f32_16x16x32_bf16 v[52:55], v[216:219], v[128:131], v[52:55]
	s_setprio 0
	s_add_i32 s59, 0, 0x18000
	v_add_u32_e32 v68, s59, v206
	s_barrier
	ds_read_b128 v[56:59], v68
	ds_read_b128 v[60:63], v68 offset:1024
	ds_read_b128 v[64:67], v68 offset:2048
	ds_read_b128 v[68:71], v68 offset:3072
	s_add_u32 s28, s28, 0x40000
	s_addc_u32 s29, s29, 0
	s_mov_b32 m0, s43
	v_lshl_add_u64 v[132:133], s[28:29], 0, v[180:181]
	ds_read_b128 v[116:119], v207 offset:32768
	ds_read_b128 v[128:131], v207 offset:33792
	ds_read_b128 v[160:163], v207 offset:34816
	ds_read_b128 v[164:167], v207 offset:35840
	ds_read_b128 v[192:195], v207 offset:36864
	ds_read_b128 v[196:199], v207 offset:37888
	ds_read_b128 v[200:203], v207 offset:38912
	ds_read_b128 v[208:211], v207 offset:39936
	global_load_lds_dwordx4 v[132:133], off
	s_mov_b32 m0, s44
	v_lshl_add_u64 v[132:133], s[28:29], 0, v[184:185]
	global_load_lds_dwordx4 v[132:133], off
	s_waitcnt lgkmcnt(8)
	s_barrier
	s_waitcnt lgkmcnt(0)
	s_setprio 1
	v_mfma_f32_16x16x32_bf16 v[132:135], v[56:59], v[116:119], v[156:159]
	v_mfma_f32_16x16x32_bf16 v[156:159], v[60:63], v[128:131], v[132:135]
	v_mfma_f32_16x16x32_bf16 v[132:135], v[64:67], v[116:119], v[152:155]
	v_mfma_f32_16x16x32_bf16 v[152:155], v[68:71], v[128:131], v[132:135]
	v_mfma_f32_16x16x32_bf16 v[132:135], v[56:59], v[160:163], v[140:143]
	v_mfma_f32_16x16x32_bf16 v[140:143], v[60:63], v[164:167], v[132:135]
	v_mfma_f32_16x16x32_bf16 v[132:135], v[64:67], v[160:163], v[136:139]
	v_mfma_f32_16x16x32_bf16 v[124:127], v[56:59], v[192:195], v[124:127]
	v_mfma_f32_16x16x32_bf16 v[120:123], v[64:67], v[192:195], v[120:123]
	v_mfma_f32_16x16x32_bf16 v[108:111], v[56:59], v[200:203], v[108:111]
	v_mfma_f32_16x16x32_bf16 v[104:107], v[64:67], v[200:203], v[104:107]
	v_mfma_f32_16x16x32_bf16 v[136:139], v[68:71], v[164:167], v[132:135]
	v_mfma_f32_16x16x32_bf16 v[124:127], v[60:63], v[196:199], v[124:127]
	v_mfma_f32_16x16x32_bf16 v[120:123], v[68:71], v[196:199], v[120:123]
	v_mfma_f32_16x16x32_bf16 v[108:111], v[60:63], v[208:211], v[108:111]
	v_mfma_f32_16x16x32_bf16 v[104:107], v[68:71], v[208:211], v[104:107]
	s_setprio 0
	s_barrier
	s_add_i32 s28, 0, 0x1c000
	v_add_u32_e32 v132, s28, v206
	s_add_i32 s29, s59, s40
	ds_read_b128 v[212:215], v132
	ds_read_b128 v[216:219], v132 offset:1024
	ds_read_b128 v[220:223], v132 offset:2048
	ds_read_b128 v[236:239], v132 offset:3072
	s_mov_b32 m0, s29
	v_lshl_add_u64 v[132:133], v[240:241], 0, s[78:79]
	global_load_lds_dwordx4 v[132:133], off
	s_add_i32 m0, s29, 0x2000
	v_lshl_add_u64 v[132:133], v[242:243], 0, s[78:79]
	global_load_lds_dwordx4 v[132:133], off
	s_barrier
	s_waitcnt lgkmcnt(0)
	s_setprio 1
	v_mfma_f32_16x16x32_bf16 v[72:75], v[220:223], v[116:119], v[72:75]
	v_mfma_f32_16x16x32_bf16 v[132:135], v[212:215], v[116:119], v[148:151]
	v_mfma_f32_16x16x32_bf16 v[144:147], v[236:239], v[128:131], v[72:75]
	v_mfma_f32_16x16x32_bf16 v[72:75], v[212:215], v[160:163], v[76:79]
	v_mfma_f32_16x16x32_bf16 v[148:151], v[216:219], v[128:131], v[132:135]
	v_mfma_f32_16x16x32_bf16 v[132:135], v[216:219], v[164:167], v[72:75]
	v_mfma_f32_16x16x32_bf16 v[72:75], v[220:223], v[160:163], v[80:83]
	v_mfma_f32_16x16x32_bf16 v[128:131], v[236:239], v[164:167], v[72:75]
	v_mfma_f32_16x16x32_bf16 v[72:75], v[212:215], v[192:195], v[84:87]
	v_mfma_f32_16x16x32_bf16 v[116:119], v[216:219], v[196:199], v[72:75]
	v_mfma_f32_16x16x32_bf16 v[72:75], v[220:223], v[192:195], v[112:115]
	v_mfma_f32_16x16x32_bf16 v[112:115], v[236:239], v[196:199], v[72:75]
	v_mfma_f32_16x16x32_bf16 v[72:75], v[212:215], v[200:203], v[100:103]
	v_mfma_f32_16x16x32_bf16 v[100:103], v[216:219], v[208:211], v[72:75]
	v_mfma_f32_16x16x32_bf16 v[72:75], v[220:223], v[200:203], v[96:99]
	v_mfma_f32_16x16x32_bf16 v[96:99], v[236:239], v[208:211], v[72:75]
	s_setprio 0
	s_mov_b32 m0, s53
	v_lshl_add_u64 v[200:201], v[244:245], 0, s[78:79]
	s_barrier
	s_nop 2
	ds_read_b128 v[72:75], v207 offset:49152
	ds_read_b128 v[76:79], v207 offset:50176
	ds_read_b128 v[80:83], v207 offset:51200
	ds_read_b128 v[84:87], v207 offset:52224
	ds_read_b128 v[160:163], v207 offset:53248
	ds_read_b128 v[164:167], v207 offset:54272
	ds_read_b128 v[192:195], v207 offset:55296
	ds_read_b128 v[196:199], v207 offset:56320
	global_load_lds_dwordx4 v[200:201], off
	s_mov_b32 m0, s54
	v_lshl_add_u64 v[200:201], v[246:247], 0, s[78:79]
	global_load_lds_dwordx4 v[200:201], off
	s_barrier
	s_waitcnt lgkmcnt(0)
	s_setprio 1
	v_mfma_f32_16x16x32_bf16 v[92:95], v[56:59], v[72:75], v[92:95]
	v_mfma_f32_16x16x32_bf16 v[88:91], v[64:67], v[72:75], v[88:91]
	v_mfma_f32_16x16x32_bf16 v[44:47], v[56:59], v[80:83], v[44:47]
	v_mfma_f32_16x16x32_bf16 v[40:43], v[64:67], v[80:83], v[40:43]
	v_mfma_f32_16x16x32_bf16 v[28:31], v[56:59], v[160:163], v[28:31]
	v_mfma_f32_16x16x32_bf16 v[24:27], v[64:67], v[160:163], v[24:27]
	v_mfma_f32_16x16x32_bf16 v[12:15], v[56:59], v[192:195], v[12:15]
	v_mfma_f32_16x16x32_bf16 v[8:11], v[64:67], v[192:195], v[8:11]
	v_mfma_f32_16x16x32_bf16 v[92:95], v[60:63], v[76:79], v[92:95]
	v_mfma_f32_16x16x32_bf16 v[88:91], v[68:71], v[76:79], v[88:91]
	v_mfma_f32_16x16x32_bf16 v[44:47], v[60:63], v[84:87], v[44:47]
	v_mfma_f32_16x16x32_bf16 v[40:43], v[68:71], v[84:87], v[40:43]
	v_mfma_f32_16x16x32_bf16 v[28:31], v[60:63], v[164:167], v[28:31]
	v_mfma_f32_16x16x32_bf16 v[24:27], v[68:71], v[164:167], v[24:27]
	v_mfma_f32_16x16x32_bf16 v[12:15], v[60:63], v[196:199], v[12:15]
	v_mfma_f32_16x16x32_bf16 v[8:11], v[68:71], v[196:199], v[8:11]
	s_setprio 0
	s_barrier
	s_add_u32 s2, s2, 0x40080
	s_addc_u32 s3, s3, 0
	s_add_i32 s28, s28, s40
	s_mov_b32 m0, s28
	v_lshl_add_u64 v[56:57], s[2:3], 0, v[182:183]
	global_load_lds_dwordx4 v[56:57], off
	s_add_i32 m0, s28, 0x2000
	v_lshl_add_u64 v[56:57], s[2:3], 0, v[186:187]
	global_load_lds_dwordx4 v[56:57], off
	s_waitcnt vmcnt(6)
	s_barrier
	s_setprio 1
	v_mfma_f32_16x16x32_bf16 v[48:51], v[212:215], v[72:75], v[48:51]
	v_mfma_f32_16x16x32_bf16 v[64:67], v[216:219], v[76:79], v[48:51]
	v_mfma_f32_16x16x32_bf16 v[48:51], v[220:223], v[72:75], v[52:55]
	v_mfma_f32_16x16x32_bf16 v[36:39], v[212:215], v[80:83], v[36:39]
	v_mfma_f32_16x16x32_bf16 v[32:35], v[220:223], v[80:83], v[32:35]
	v_mfma_f32_16x16x32_bf16 v[20:23], v[212:215], v[160:163], v[20:23]
	v_mfma_f32_16x16x32_bf16 v[16:19], v[220:223], v[160:163], v[16:19]
	v_mfma_f32_16x16x32_bf16 v[4:7], v[212:215], v[192:195], v[4:7]
	v_mfma_f32_16x16x32_bf16 v[0:3], v[220:223], v[192:195], v[0:3]
	v_mfma_f32_16x16x32_bf16 v[56:59], v[236:239], v[76:79], v[48:51]
	v_mfma_f32_16x16x32_bf16 v[36:39], v[216:219], v[84:87], v[36:39]
	v_mfma_f32_16x16x32_bf16 v[32:35], v[236:239], v[84:87], v[32:35]
	v_mfma_f32_16x16x32_bf16 v[20:23], v[216:219], v[164:167], v[20:23]
	v_mfma_f32_16x16x32_bf16 v[16:19], v[236:239], v[164:167], v[16:19]
	v_mfma_f32_16x16x32_bf16 v[4:7], v[216:219], v[196:199], v[4:7]
	v_mfma_f32_16x16x32_bf16 v[0:3], v[236:239], v[196:199], v[0:3]
	s_setprio 0
	s_add_i32 s58, s58, 2
	s_add_u32 s8, s8, 0x100
	s_addc_u32 s9, s9, 0
	s_add_u32 s56, s56, 0x100
	s_addc_u32 s57, s57, 0
	s_cmp_gt_u32 s58, 13
	s_barrier
.LBB0_678:
	s_add_u32 s2, s8, 0xfffc0080
	s_addc_u32 s3, s9, -1
	s_add_i32 s59, 0, 0x10000
	v_add_u32_e32 v68, s59, v206
	ds_read_b128 v[48:51], v68
	ds_read_b128 v[52:55], v68 offset:1024
	ds_read_b128 v[60:63], v68 offset:2048
	ds_read_b128 v[68:71], v68 offset:3072
	s_cmp_eq_u32 s58, 12
	s_cselect_b32 s29, s1, s3
	s_cselect_b32 s28, s7, s2
	s_cselect_b32 s3, s21, s57
	s_cselect_b32 s2, s23, s56
	v_lshl_add_u64 v[200:201], s[8:9], 0, v[188:189]
	s_add_i32 m0, s41, 0xc000
	ds_read_b128 v[72:75], v207
	ds_read_b128 v[76:79], v207 offset:1024
	ds_read_b128 v[80:83], v207 offset:2048
	ds_read_b128 v[84:87], v207 offset:3072
	ds_read_b128 v[160:163], v207 offset:4096
	ds_read_b128 v[164:167], v207 offset:5120
	ds_read_b128 v[192:195], v207 offset:6144
	ds_read_b128 v[196:199], v207 offset:7168
	global_load_lds_dwordx4 v[200:201], off
	s_add_i32 m0, s41, 0xe000
	v_lshl_add_u64 v[200:201], s[8:9], 0, v[190:191]
	global_load_lds_dwordx4 v[200:201], off
	s_waitcnt lgkmcnt(8)
	s_barrier
	s_waitcnt lgkmcnt(0)
	s_setprio 1
	v_mfma_f32_16x16x32_bf16 v[156:159], v[48:51], v[72:75], v[156:159]
	v_mfma_f32_16x16x32_bf16 v[152:155], v[60:63], v[72:75], v[152:155]
	v_mfma_f32_16x16x32_bf16 v[140:143], v[48:51], v[80:83], v[140:143]
	v_mfma_f32_16x16x32_bf16 v[136:139], v[60:63], v[80:83], v[136:139]
	v_mfma_f32_16x16x32_bf16 v[124:127], v[48:51], v[160:163], v[124:127]
	v_mfma_f32_16x16x32_bf16 v[120:123], v[60:63], v[160:163], v[120:123]
	v_mfma_f32_16x16x32_bf16 v[108:111], v[48:51], v[192:195], v[108:111]
	v_mfma_f32_16x16x32_bf16 v[104:107], v[60:63], v[192:195], v[104:107]
	v_mfma_f32_16x16x32_bf16 v[156:159], v[52:55], v[76:79], v[156:159]
	v_mfma_f32_16x16x32_bf16 v[152:155], v[68:71], v[76:79], v[152:155]
	v_mfma_f32_16x16x32_bf16 v[140:143], v[52:55], v[84:87], v[140:143]
	v_mfma_f32_16x16x32_bf16 v[136:139], v[68:71], v[84:87], v[136:139]
	v_mfma_f32_16x16x32_bf16 v[124:127], v[52:55], v[164:167], v[124:127]
	v_mfma_f32_16x16x32_bf16 v[120:123], v[68:71], v[164:167], v[120:123]
	v_mfma_f32_16x16x32_bf16 v[108:111], v[52:55], v[196:199], v[108:111]
	v_mfma_f32_16x16x32_bf16 v[104:107], v[68:71], v[196:199], v[104:107]
	s_setprio 0
	s_barrier
	s_add_i32 s62, 0, 0x14000
	s_add_i32 s59, s59, s40
	v_add_u32_e32 v168, s62, v206
	v_lshl_add_u64 v[240:241], s[2:3], 0, v[182:183]
	s_mov_b32 m0, s59
	ds_read_b128 v[200:203], v168
	ds_read_b128 v[208:211], v168 offset:1024
	ds_read_b128 v[212:215], v168 offset:2048
	ds_read_b128 v[216:219], v168 offset:3072
	global_load_lds_dwordx4 v[240:241], off
	s_add_i32 m0, s59, 0x2000
	v_lshl_add_u64 v[242:243], s[2:3], 0, v[186:187]
	global_load_lds_dwordx4 v[242:243], off
	s_barrier
	s_waitcnt lgkmcnt(0)
	s_setprio 1
	v_mfma_f32_16x16x32_bf16 v[148:151], v[200:203], v[72:75], v[148:151]
	v_mfma_f32_16x16x32_bf16 v[72:75], v[212:215], v[72:75], v[144:147]
	v_mfma_f32_16x16x32_bf16 v[148:151], v[208:211], v[76:79], v[148:151]
	v_mfma_f32_16x16x32_bf16 v[72:75], v[216:219], v[76:79], v[72:75]
	v_mfma_f32_16x16x32_bf16 v[76:79], v[200:203], v[80:83], v[132:135]
	v_mfma_f32_16x16x32_bf16 v[80:83], v[212:215], v[80:83], v[128:131]
	v_mfma_f32_16x16x32_bf16 v[112:115], v[212:215], v[160:163], v[112:115]
	v_mfma_f32_16x16x32_bf16 v[100:103], v[200:203], v[192:195], v[100:103]
	v_mfma_f32_16x16x32_bf16 v[96:99], v[212:215], v[192:195], v[96:99]
	v_mfma_f32_16x16x32_bf16 v[76:79], v[208:211], v[84:87], v[76:79]
	v_mfma_f32_16x16x32_bf16 v[80:83], v[216:219], v[84:87], v[80:83]
	v_mfma_f32_16x16x32_bf16 v[84:87], v[200:203], v[160:163], v[116:119]
	v_mfma_f32_16x16x32_bf16 v[112:115], v[216:219], v[164:167], v[112:115]
	v_mfma_f32_16x16x32_bf16 v[100:103], v[208:211], v[196:199], v[100:103]
	v_mfma_f32_16x16x32_bf16 v[96:99], v[216:219], v[196:199], v[96:99]
	v_mfma_f32_16x16x32_bf16 v[84:87], v[208:211], v[164:167], v[84:87]
	s_setprio 0
	s_mov_b32 m0, s41
	v_lshl_add_u64 v[244:245], s[28:29], 0, v[180:181]
	s_barrier
	ds_read_b128 v[116:119], v207 offset:16384
	ds_read_b128 v[128:131], v207 offset:17408
	ds_read_b128 v[132:135], v207 offset:18432
	ds_read_b128 v[144:147], v207 offset:19456
	ds_read_b128 v[160:163], v207 offset:20480
	ds_read_b128 v[164:167], v207 offset:21504
	ds_read_b128 v[192:195], v207 offset:22528
	ds_read_b128 v[196:199], v207 offset:23552
	global_load_lds_dwordx4 v[244:245], off
	s_mov_b32 m0, s42
	v_lshl_add_u64 v[246:247], s[28:29], 0, v[184:185]
	global_load_lds_dwordx4 v[246:247], off
	s_barrier
	s_waitcnt lgkmcnt(0)
	s_setprio 1
	v_mfma_f32_16x16x32_bf16 v[92:95], v[48:51], v[116:119], v[92:95]
	v_mfma_f32_16x16x32_bf16 v[88:91], v[60:63], v[116:119], v[88:91]
	v_mfma_f32_16x16x32_bf16 v[44:47], v[48:51], v[132:135], v[44:47]
	v_mfma_f32_16x16x32_bf16 v[40:43], v[60:63], v[132:135], v[40:43]
	v_mfma_f32_16x16x32_bf16 v[28:31], v[48:51], v[160:163], v[28:31]
	v_mfma_f32_16x16x32_bf16 v[24:27], v[60:63], v[160:163], v[24:27]
	v_mfma_f32_16x16x32_bf16 v[12:15], v[48:51], v[192:195], v[12:15]
	v_mfma_f32_16x16x32_bf16 v[8:11], v[60:63], v[192:195], v[8:11]
	v_mfma_f32_16x16x32_bf16 v[92:95], v[52:55], v[128:131], v[92:95]
	v_mfma_f32_16x16x32_bf16 v[88:91], v[68:71], v[128:131], v[88:91]
	v_mfma_f32_16x16x32_bf16 v[44:47], v[52:55], v[144:147], v[44:47]
	v_mfma_f32_16x16x32_bf16 v[40:43], v[68:71], v[144:147], v[40:43]
	v_mfma_f32_16x16x32_bf16 v[28:31], v[52:55], v[164:167], v[28:31]
	v_mfma_f32_16x16x32_bf16 v[24:27], v[68:71], v[164:167], v[24:27]
	v_mfma_f32_16x16x32_bf16 v[12:15], v[52:55], v[196:199], v[12:15]
	v_mfma_f32_16x16x32_bf16 v[8:11], v[68:71], v[196:199], v[8:11]
	s_setprio 0
	s_barrier
	s_add_u32 s60, s2, 0x40000
	s_addc_u32 s61, s3, 0
	s_add_i32 s59, s62, s40
	s_mov_b32 m0, s59
	v_lshl_add_u64 v[48:49], s[60:61], 0, v[182:183]
	global_load_lds_dwordx4 v[48:49], off
	s_add_i32 m0, s59, 0x2000
	v_lshl_add_u64 v[48:49], s[60:61], 0, v[186:187]
	global_load_lds_dwordx4 v[48:49], off
	s_waitcnt vmcnt(6)
	s_barrier
	s_setprio 1
	v_mfma_f32_16x16x32_bf16 v[36:39], v[200:203], v[132:135], v[36:39]
	v_mfma_f32_16x16x32_bf16 v[32:35], v[212:215], v[132:135], v[32:35]
	v_mfma_f32_16x16x32_bf16 v[20:23], v[200:203], v[160:163], v[20:23]
	v_mfma_f32_16x16x32_bf16 v[16:19], v[212:215], v[160:163], v[16:19]
	v_mfma_f32_16x16x32_bf16 v[4:7], v[200:203], v[192:195], v[4:7]
	v_mfma_f32_16x16x32_bf16 v[0:3], v[212:215], v[192:195], v[0:3]
	v_mfma_f32_16x16x32_bf16 v[48:51], v[200:203], v[116:119], v[64:67]
	v_mfma_f32_16x16x32_bf16 v[52:55], v[212:215], v[116:119], v[56:59]
	v_mfma_f32_16x16x32_bf16 v[36:39], v[208:211], v[144:147], v[36:39]
	v_mfma_f32_16x16x32_bf16 v[32:35], v[216:219], v[144:147], v[32:35]
	v_mfma_f32_16x16x32_bf16 v[20:23], v[208:211], v[164:167], v[20:23]
	v_mfma_f32_16x16x32_bf16 v[16:19], v[216:219], v[164:167], v[16:19]
	v_mfma_f32_16x16x32_bf16 v[4:7], v[208:211], v[196:199], v[4:7]
	v_mfma_f32_16x16x32_bf16 v[0:3], v[216:219], v[196:199], v[0:3]
	v_mfma_f32_16x16x32_bf16 v[48:51], v[208:211], v[128:131], v[48:51]
	v_mfma_f32_16x16x32_bf16 v[52:55], v[216:219], v[128:131], v[52:55]
	s_setprio 0
	s_add_i32 s59, 0, 0x18000
	v_add_u32_e32 v68, s59, v206
	s_barrier
	ds_read_b128 v[56:59], v68
	ds_read_b128 v[60:63], v68 offset:1024
	ds_read_b128 v[64:67], v68 offset:2048
	ds_read_b128 v[68:71], v68 offset:3072
	s_add_u32 s28, s28, 0x40000
	s_addc_u32 s29, s29, 0
	s_mov_b32 m0, s43
	v_lshl_add_u64 v[132:133], s[28:29], 0, v[180:181]
	ds_read_b128 v[116:119], v207 offset:32768
	ds_read_b128 v[128:131], v207 offset:33792
	ds_read_b128 v[160:163], v207 offset:34816
	ds_read_b128 v[164:167], v207 offset:35840
	ds_read_b128 v[192:195], v207 offset:36864
	ds_read_b128 v[196:199], v207 offset:37888
	ds_read_b128 v[200:203], v207 offset:38912
	ds_read_b128 v[208:211], v207 offset:39936
	global_load_lds_dwordx4 v[132:133], off
	s_mov_b32 m0, s44
	v_lshl_add_u64 v[132:133], s[28:29], 0, v[184:185]
	global_load_lds_dwordx4 v[132:133], off
	s_waitcnt lgkmcnt(8)
	s_barrier
	s_waitcnt lgkmcnt(0)
	s_setprio 1
	v_mfma_f32_16x16x32_bf16 v[132:135], v[56:59], v[116:119], v[156:159]
	v_mfma_f32_16x16x32_bf16 v[156:159], v[60:63], v[128:131], v[132:135]
	v_mfma_f32_16x16x32_bf16 v[132:135], v[64:67], v[116:119], v[152:155]
	v_mfma_f32_16x16x32_bf16 v[152:155], v[68:71], v[128:131], v[132:135]
	v_mfma_f32_16x16x32_bf16 v[132:135], v[56:59], v[160:163], v[140:143]
	v_mfma_f32_16x16x32_bf16 v[140:143], v[60:63], v[164:167], v[132:135]
	v_mfma_f32_16x16x32_bf16 v[132:135], v[64:67], v[160:163], v[136:139]
	v_mfma_f32_16x16x32_bf16 v[124:127], v[56:59], v[192:195], v[124:127]
	v_mfma_f32_16x16x32_bf16 v[120:123], v[64:67], v[192:195], v[120:123]
	v_mfma_f32_16x16x32_bf16 v[108:111], v[56:59], v[200:203], v[108:111]
	v_mfma_f32_16x16x32_bf16 v[104:107], v[64:67], v[200:203], v[104:107]
	v_mfma_f32_16x16x32_bf16 v[136:139], v[68:71], v[164:167], v[132:135]
	v_mfma_f32_16x16x32_bf16 v[124:127], v[60:63], v[196:199], v[124:127]
	v_mfma_f32_16x16x32_bf16 v[120:123], v[68:71], v[196:199], v[120:123]
	v_mfma_f32_16x16x32_bf16 v[108:111], v[60:63], v[208:211], v[108:111]
	v_mfma_f32_16x16x32_bf16 v[104:107], v[68:71], v[208:211], v[104:107]
	s_setprio 0
	s_barrier
	s_add_i32 s28, 0, 0x1c000
	v_add_u32_e32 v132, s28, v206
	s_add_i32 s29, s59, s40
	ds_read_b128 v[212:215], v132
	ds_read_b128 v[216:219], v132 offset:1024
	ds_read_b128 v[220:223], v132 offset:2048
	ds_read_b128 v[236:239], v132 offset:3072
	s_mov_b32 m0, s29
	v_lshl_add_u64 v[132:133], v[240:241], 0, s[78:79]
	global_load_lds_dwordx4 v[132:133], off
	s_add_i32 m0, s29, 0x2000
	v_lshl_add_u64 v[132:133], v[242:243], 0, s[78:79]
	global_load_lds_dwordx4 v[132:133], off
	s_barrier
	s_waitcnt lgkmcnt(0)
	s_setprio 1
	v_mfma_f32_16x16x32_bf16 v[72:75], v[220:223], v[116:119], v[72:75]
	v_mfma_f32_16x16x32_bf16 v[132:135], v[212:215], v[116:119], v[148:151]
	v_mfma_f32_16x16x32_bf16 v[144:147], v[236:239], v[128:131], v[72:75]
	v_mfma_f32_16x16x32_bf16 v[72:75], v[212:215], v[160:163], v[76:79]
	v_mfma_f32_16x16x32_bf16 v[148:151], v[216:219], v[128:131], v[132:135]
	v_mfma_f32_16x16x32_bf16 v[132:135], v[216:219], v[164:167], v[72:75]
	v_mfma_f32_16x16x32_bf16 v[72:75], v[220:223], v[160:163], v[80:83]
	v_mfma_f32_16x16x32_bf16 v[128:131], v[236:239], v[164:167], v[72:75]
	v_mfma_f32_16x16x32_bf16 v[72:75], v[212:215], v[192:195], v[84:87]
	v_mfma_f32_16x16x32_bf16 v[116:119], v[216:219], v[196:199], v[72:75]
	v_mfma_f32_16x16x32_bf16 v[72:75], v[220:223], v[192:195], v[112:115]
	v_mfma_f32_16x16x32_bf16 v[112:115], v[236:239], v[196:199], v[72:75]
	v_mfma_f32_16x16x32_bf16 v[72:75], v[212:215], v[200:203], v[100:103]
	v_mfma_f32_16x16x32_bf16 v[100:103], v[216:219], v[208:211], v[72:75]
	v_mfma_f32_16x16x32_bf16 v[72:75], v[220:223], v[200:203], v[96:99]
	v_mfma_f32_16x16x32_bf16 v[96:99], v[236:239], v[208:211], v[72:75]
	s_setprio 0
	s_mov_b32 m0, s53
	v_lshl_add_u64 v[200:201], v[244:245], 0, s[78:79]
	s_barrier
	s_nop 2
	ds_read_b128 v[72:75], v207 offset:49152
	ds_read_b128 v[76:79], v207 offset:50176
	ds_read_b128 v[80:83], v207 offset:51200
	ds_read_b128 v[84:87], v207 offset:52224
	ds_read_b128 v[160:163], v207 offset:53248
	ds_read_b128 v[164:167], v207 offset:54272
	ds_read_b128 v[192:195], v207 offset:55296
	ds_read_b128 v[196:199], v207 offset:56320
	global_load_lds_dwordx4 v[200:201], off
	s_mov_b32 m0, s54
	v_lshl_add_u64 v[200:201], v[246:247], 0, s[78:79]
	global_load_lds_dwordx4 v[200:201], off
	s_barrier
	s_waitcnt lgkmcnt(0)
	s_setprio 1
	v_mfma_f32_16x16x32_bf16 v[92:95], v[56:59], v[72:75], v[92:95]
	v_mfma_f32_16x16x32_bf16 v[88:91], v[64:67], v[72:75], v[88:91]
	v_mfma_f32_16x16x32_bf16 v[44:47], v[56:59], v[80:83], v[44:47]
	v_mfma_f32_16x16x32_bf16 v[40:43], v[64:67], v[80:83], v[40:43]
	v_mfma_f32_16x16x32_bf16 v[28:31], v[56:59], v[160:163], v[28:31]
	v_mfma_f32_16x16x32_bf16 v[24:27], v[64:67], v[160:163], v[24:27]
	v_mfma_f32_16x16x32_bf16 v[12:15], v[56:59], v[192:195], v[12:15]
	v_mfma_f32_16x16x32_bf16 v[8:11], v[64:67], v[192:195], v[8:11]
	v_mfma_f32_16x16x32_bf16 v[92:95], v[60:63], v[76:79], v[92:95]
	v_mfma_f32_16x16x32_bf16 v[88:91], v[68:71], v[76:79], v[88:91]
	v_mfma_f32_16x16x32_bf16 v[44:47], v[60:63], v[84:87], v[44:47]
	v_mfma_f32_16x16x32_bf16 v[40:43], v[68:71], v[84:87], v[40:43]
	v_mfma_f32_16x16x32_bf16 v[28:31], v[60:63], v[164:167], v[28:31]
	v_mfma_f32_16x16x32_bf16 v[24:27], v[68:71], v[164:167], v[24:27]
	v_mfma_f32_16x16x32_bf16 v[12:15], v[60:63], v[196:199], v[12:15]
	v_mfma_f32_16x16x32_bf16 v[8:11], v[68:71], v[196:199], v[8:11]
	s_setprio 0
	s_barrier
	s_add_u32 s2, s2, 0x40080
	s_addc_u32 s3, s3, 0
	s_add_i32 s28, s28, s40
	s_mov_b32 m0, s28
	v_lshl_add_u64 v[56:57], s[2:3], 0, v[182:183]
	global_load_lds_dwordx4 v[56:57], off
	s_add_i32 m0, s28, 0x2000
	v_lshl_add_u64 v[56:57], s[2:3], 0, v[186:187]
	global_load_lds_dwordx4 v[56:57], off
	s_waitcnt vmcnt(6)
	s_barrier
	s_setprio 1
	v_mfma_f32_16x16x32_bf16 v[48:51], v[212:215], v[72:75], v[48:51]
	v_mfma_f32_16x16x32_bf16 v[64:67], v[216:219], v[76:79], v[48:51]
	v_mfma_f32_16x16x32_bf16 v[48:51], v[220:223], v[72:75], v[52:55]
	v_mfma_f32_16x16x32_bf16 v[36:39], v[212:215], v[80:83], v[36:39]
	v_mfma_f32_16x16x32_bf16 v[32:35], v[220:223], v[80:83], v[32:35]
	v_mfma_f32_16x16x32_bf16 v[20:23], v[212:215], v[160:163], v[20:23]
	v_mfma_f32_16x16x32_bf16 v[16:19], v[220:223], v[160:163], v[16:19]
	v_mfma_f32_16x16x32_bf16 v[4:7], v[212:215], v[192:195], v[4:7]
	v_mfma_f32_16x16x32_bf16 v[0:3], v[220:223], v[192:195], v[0:3]
	v_mfma_f32_16x16x32_bf16 v[56:59], v[236:239], v[76:79], v[48:51]
	v_mfma_f32_16x16x32_bf16 v[36:39], v[216:219], v[84:87], v[36:39]
	v_mfma_f32_16x16x32_bf16 v[32:35], v[236:239], v[84:87], v[32:35]
	v_mfma_f32_16x16x32_bf16 v[20:23], v[216:219], v[164:167], v[20:23]
	v_mfma_f32_16x16x32_bf16 v[16:19], v[236:239], v[164:167], v[16:19]
	v_mfma_f32_16x16x32_bf16 v[4:7], v[216:219], v[196:199], v[4:7]
	v_mfma_f32_16x16x32_bf16 v[0:3], v[236:239], v[196:199], v[0:3]
	s_setprio 0
	s_add_i32 s58, s58, 2
	s_add_u32 s8, s8, 0x100
	s_addc_u32 s9, s9, 0
	s_add_u32 s56, s56, 0x100
	s_addc_u32 s57, s57, 0
	s_cmp_gt_u32 s58, 13
	s_barrier
	s_cbranch_scc0 .LBB0_678
	s_lshl_b32 s1, s0, 8
	s_add_i32 s2, s1, s51
	s_lshl_b32 s1, s6, 8
	v_mov_b32_e32 v160, v205
	v_mov_b32_e32 v208, v204
	s_or_b32 s1, s1, s52
	s_nop 0
	v_lshl_add_u32 v192, v208, 3, s1
	s_add_i32 s1, s0, -16
	s_lshr_b32 s1, s1, 3
	s_add_i32 s1, s1, 1
	s_cmp_gt_i32 s0, 15
	s_cselect_b32 s3, s1, 0
	s_mul_i32 s96, s3, 0x1800
	s_lshl_b64 s[0:1], s[96:97], 2
	s_add_u32 s0, s45, s0
	v_ashrrev_i32_e32 v193, 31, v192
	s_addc_u32 s1, s46, s1
	v_lshlrev_b64 v[196:197], 2, v[192:193]
	s_lshl_b32 s96, s3, 10
	v_lshl_add_u64 v[48:49], s[0:1], 0, v[196:197]
	s_lshl_b64 s[0:1], s[96:97], 2
	s_add_u32 s0, s49, s0
	s_addc_u32 s1, s50, s1
	v_lshl_add_u64 v[52:53], s[0:1], 0, v[196:197]
	global_load_dwordx4 v[80:83], v[48:49], off offset:16
	global_load_dwordx4 v[84:87], v[48:49], off
	global_load_dwordx4 v[72:75], v[52:53], off offset:16
	global_load_dwordx4 v[76:79], v[52:53], off
	global_load_dwordx4 v[60:63], v[48:49], off offset:528
	global_load_dwordx4 v[68:71], v[48:49], off offset:512
	s_nop 0
	global_load_dwordx4 v[48:51], v[52:53], off offset:528
	s_nop 0
	global_load_dwordx4 v[52:55], v[52:53], off offset:512
	v_add_u32_e32 v194, s2, v160
	v_ashrrev_i32_e32 v195, 31, v194
	v_lshlrev_b64 v[160:161], 10, v[194:195]
	v_lshl_add_u64 v[198:199], v[160:161], 0, v[192:193]
	v_cndmask_b32_e64 v160, 0, 1, s[74:75]
	v_cmp_gt_i32_e64 s[0:1], s71, v194
	v_cmp_ne_u32_e64 s[6:7], 1, v160
	s_andn2_b64 vcc, exec, s[74:75]
	s_mov_b64 s[2:3], -1
	s_cbranch_vccnz .LBB0_681
	v_lshl_add_u64 v[160:161], v[198:199], 1, s[14:15]
	v_mov_b32_e32 v222, v160
	v_mov_b32_e32 v223, v161
	global_load_dwordx4 v[210:213], v[222:223], off
	global_load_dwordx4 v[214:217], v[222:223], off offset:256
	s_mov_b64 s[80:81], 0x8000
	v_lshl_add_u64 v[222:223], v[222:223], 0, s[80:81]
	global_load_dwordx4 v[218:221], v[222:223], off
	global_load_dwordx4 v[236:239], v[222:223], off offset:256
	s_mov_b64 s[2:3], 0
	s_waitcnt vmcnt(3)
	v_lshlrev_b32_e32 v164, 16, v210
	v_and_b32_e32 v165, 0xffff0000, v210
	v_lshlrev_b32_e32 v166, 16, v211
	v_and_b32_e32 v167, 0xffff0000, v211
	v_lshlrev_b32_e32 v160, 16, v212
	v_and_b32_e32 v161, 0xffff0000, v212
	v_lshlrev_b32_e32 v162, 16, v213
	v_and_b32_e32 v163, 0xffff0000, v213
	s_mov_b64 s[80:81], 0x8000
	v_lshl_add_u64 v[222:223], v[222:223], 0, s[80:81]
	global_load_dwordx4 v[210:213], v[222:223], off

.LBB0_879:
	s_ashr_i32 s39, s38, 31
	v_cmp_lt_i64_e32 vcc, s[12:13], v[178:179]
	s_lshl_b64 s[12:13], s[38:39], 19
	s_add_u32 s40, s49, s12
	s_addc_u32 s41, s50, s13
	s_lshl_b32 s84, s82, 18
	s_add_u32 s40, s40, s84
	s_addc_u32 s41, s41, 0
	s_and_b64 s[12:13], vcc, exec
	s_cselect_b32 s1, s41, s11
	s_cselect_b32 s9, s40, s10
	s_ashr_i32 s37, s36, 31
	s_lshl_b64 s[12:13], s[36:37], 19
	s_add_u32 s42, s51, s12
	s_addc_u32 s43, s52, s13
	s_and_b64 s[12:13], vcc, exec
	s_cselect_b32 s14, s43, s3
	s_cselect_b32 s15, s42, s2
	s_add_u32 s10, s10, 0x40080
	s_addc_u32 s11, s11, 0
	s_add_u32 s37, s2, 0x100
	s_addc_u32 s39, s3, 0
	s_mov_b32 s67, -2
	s_cmp_lg_u32 s83, 0
	s_cbranch_scc1 .Lup_half_peel
	s_add_u32 s2, s10, 0xfffc0080
	s_addc_u32 s3, s11, -1
	s_add_i32 s68, 0, 0x10000
	v_add_u32_e32 v108, s68, v237
	ds_read_b128 v[48:51], v108
	ds_read_b128 v[52:55], v108 offset:1024
	ds_read_b128 v[104:107], v108 offset:2048
	ds_read_b128 v[108:111], v108 offset:3072
	s_cmp_eq_u32 s67, 12
	s_cselect_b32 s13, s1, s3
	s_cselect_b32 s12, s9, s2
	s_cselect_b32 s3, s14, s39
	s_cselect_b32 s2, s15, s37
	v_lshl_add_u64 v[198:199], s[10:11], 0, v[186:187]
	s_add_i32 m0, s54, 0xc000
	ds_read_b128 v[112:115], v238
	ds_read_b128 v[116:119], v238 offset:1024
	ds_read_b128 v[120:123], v238 offset:2048
	ds_read_b128 v[156:159], v238 offset:3072
	ds_read_b128 v[160:163], v238 offset:4096
	ds_read_b128 v[164:167], v238 offset:5120
	ds_read_b128 v[190:193], v238 offset:6144
	ds_read_b128 v[194:197], v238 offset:7168
	global_load_lds_dwordx4 v[198:199], off
	s_add_i32 m0, s54, 0xe000
	v_lshl_add_u64 v[198:199], s[10:11], 0, v[188:189]
	global_load_lds_dwordx4 v[198:199], off
	s_waitcnt lgkmcnt(8)
	s_barrier
	s_waitcnt lgkmcnt(0)
	s_setprio 1
	v_mfma_f32_16x16x32_bf16 v[152:155], v[48:51], v[112:115], 0
	v_mfma_f32_16x16x32_bf16 v[68:71], v[104:107], v[112:115], 0
	v_mfma_f32_16x16x32_bf16 v[148:151], v[48:51], v[120:123], 0
	v_mfma_f32_16x16x32_bf16 v[64:67], v[104:107], v[120:123], 0
	v_mfma_f32_16x16x32_bf16 v[136:139], v[48:51], v[160:163], 0
	v_mfma_f32_16x16x32_bf16 v[44:47], v[104:107], v[160:163], 0
	v_mfma_f32_16x16x32_bf16 v[128:131], v[48:51], v[190:193], 0
	v_mfma_f32_16x16x32_bf16 v[40:43], v[104:107], v[190:193], 0
	v_mfma_f32_16x16x32_bf16 v[152:155], v[52:55], v[116:119], v[152:155]
	v_mfma_f32_16x16x32_bf16 v[68:71], v[108:111], v[116:119], v[68:71]
	v_mfma_f32_16x16x32_bf16 v[148:151], v[52:55], v[156:159], v[148:151]
	v_mfma_f32_16x16x32_bf16 v[64:67], v[108:111], v[156:159], v[64:67]
	v_mfma_f32_16x16x32_bf16 v[136:139], v[52:55], v[164:167], v[136:139]
	v_mfma_f32_16x16x32_bf16 v[44:47], v[108:111], v[164:167], v[44:47]
	v_mfma_f32_16x16x32_bf16 v[128:131], v[52:55], v[194:197], v[128:131]
	v_mfma_f32_16x16x32_bf16 v[40:43], v[108:111], v[194:197], v[40:43]
	s_setprio 0
	s_barrier
	s_add_i32 s70, 0, 0x14000
	s_add_i32 s68, s68, s53
	v_add_u32_e32 v210, s70, v237
	v_lshl_add_u64 v[218:219], s[2:3], 0, v[168:169]
	s_mov_b32 m0, s68
	ds_read_b128 v[198:201], v210
	ds_read_b128 v[202:205], v210 offset:1024
	ds_read_b128 v[206:209], v210 offset:2048
	ds_read_b128 v[210:213], v210 offset:3072
	global_load_lds_dwordx4 v[218:219], off
	s_add_i32 m0, s68, 0x2000
	v_lshl_add_u64 v[220:221], s[2:3], 0, v[184:185]
	global_load_lds_dwordx4 v[220:221], off
	s_barrier
	s_waitcnt lgkmcnt(0)
	s_setprio 1
	v_mfma_f32_16x16x32_bf16 v[144:147], v[198:201], v[112:115], 0
	v_mfma_f32_16x16x32_bf16 v[60:63], v[206:209], v[112:115], 0
	v_mfma_f32_16x16x32_bf16 v[56:59], v[206:209], v[120:123], 0
	v_mfma_f32_16x16x32_bf16 v[36:39], v[206:209], v[160:163], 0
	v_mfma_f32_16x16x32_bf16 v[32:35], v[206:209], v[190:193], 0
	v_mfma_f32_16x16x32_bf16 v[144:147], v[202:205], v[116:119], v[144:147]
	v_mfma_f32_16x16x32_bf16 v[60:63], v[210:213], v[116:119], v[60:63]
	v_mfma_f32_16x16x32_bf16 v[112:115], v[198:201], v[120:123], 0
	v_mfma_f32_16x16x32_bf16 v[56:59], v[210:213], v[156:159], v[56:59]
	v_mfma_f32_16x16x32_bf16 v[116:119], v[198:201], v[160:163], 0
	v_mfma_f32_16x16x32_bf16 v[36:39], v[210:213], v[164:167], v[36:39]
	v_mfma_f32_16x16x32_bf16 v[120:123], v[198:201], v[190:193], 0
	v_mfma_f32_16x16x32_bf16 v[32:35], v[210:213], v[194:197], v[32:35]
	v_mfma_f32_16x16x32_bf16 v[112:115], v[202:205], v[156:159], v[112:115]
	v_mfma_f32_16x16x32_bf16 v[116:119], v[202:205], v[164:167], v[116:119]
	v_mfma_f32_16x16x32_bf16 v[120:123], v[202:205], v[194:197], v[120:123]
	s_setprio 0
	s_mov_b32 m0, s54
	v_lshl_add_u64 v[222:223], s[12:13], 0, v[180:181]
	s_barrier
	ds_read_b128 v[124:127], v238 offset:16384
	ds_read_b128 v[132:135], v238 offset:17408
	ds_read_b128 v[140:143], v238 offset:18432
	ds_read_b128 v[156:159], v238 offset:19456
	ds_read_b128 v[160:163], v238 offset:20480
	ds_read_b128 v[164:167], v238 offset:21504
	ds_read_b128 v[190:193], v238 offset:22528
	ds_read_b128 v[194:197], v238 offset:23552
	global_load_lds_dwordx4 v[222:223], off
	s_mov_b32 m0, s55
	v_lshl_add_u64 v[240:241], s[12:13], 0, v[182:183]
	global_load_lds_dwordx4 v[240:241], off
	s_barrier
	s_waitcnt lgkmcnt(0)
	s_setprio 1
	v_mfma_f32_16x16x32_bf16 v[100:103], v[48:51], v[124:127], 0
	v_mfma_f32_16x16x32_bf16 v[28:31], v[104:107], v[124:127], 0
	v_mfma_f32_16x16x32_bf16 v[96:99], v[48:51], v[140:143], 0
	v_mfma_f32_16x16x32_bf16 v[24:27], v[104:107], v[140:143], 0
	v_mfma_f32_16x16x32_bf16 v[84:87], v[48:51], v[160:163], 0
	v_mfma_f32_16x16x32_bf16 v[12:15], v[104:107], v[160:163], 0
	v_mfma_f32_16x16x32_bf16 v[8:11], v[104:107], v[190:193], 0
	v_mfma_f32_16x16x32_bf16 v[100:103], v[52:55], v[132:135], v[100:103]
	v_mfma_f32_16x16x32_bf16 v[28:31], v[108:111], v[132:135], v[28:31]
	v_mfma_f32_16x16x32_bf16 v[96:99], v[52:55], v[156:159], v[96:99]
	v_mfma_f32_16x16x32_bf16 v[24:27], v[108:111], v[156:159], v[24:27]
	v_mfma_f32_16x16x32_bf16 v[84:87], v[52:55], v[164:167], v[84:87]
	v_mfma_f32_16x16x32_bf16 v[12:15], v[108:111], v[164:167], v[12:15]
	v_mfma_f32_16x16x32_bf16 v[48:51], v[48:51], v[190:193], 0
	v_mfma_f32_16x16x32_bf16 v[8:11], v[108:111], v[194:197], v[8:11]
	v_mfma_f32_16x16x32_bf16 v[48:51], v[52:55], v[194:197], v[48:51]
	s_setprio 0
	s_barrier
	s_add_u32 s68, s2, 0x40000
	s_addc_u32 s69, s3, 0
	s_add_i32 s70, s70, s53
	s_mov_b32 m0, s70
	v_lshl_add_u64 v[52:53], s[68:69], 0, v[168:169]
	global_load_lds_dwordx4 v[52:53], off
	s_add_i32 m0, s70, 0x2000
	v_lshl_add_u64 v[52:53], s[68:69], 0, v[184:185]
	global_load_lds_dwordx4 v[52:53], off
	s_waitcnt vmcnt(6)
	s_barrier
	s_setprio 1
	v_mfma_f32_16x16x32_bf16 v[76:79], v[198:201], v[140:143], 0
	v_mfma_f32_16x16x32_bf16 v[20:23], v[206:209], v[124:127], 0
	v_mfma_f32_16x16x32_bf16 v[88:91], v[202:205], v[156:159], v[76:79]
	v_mfma_f32_16x16x32_bf16 v[16:19], v[206:209], v[140:143], 0
	v_mfma_f32_16x16x32_bf16 v[76:79], v[198:201], v[160:163], 0
	v_mfma_f32_16x16x32_bf16 v[4:7], v[206:209], v[160:163], 0
	v_mfma_f32_16x16x32_bf16 v[72:75], v[198:201], v[190:193], 0
	v_mfma_f32_16x16x32_bf16 v[0:3], v[206:209], v[190:193], 0
	v_mfma_f32_16x16x32_bf16 v[52:55], v[198:201], v[124:127], 0
	v_mfma_f32_16x16x32_bf16 v[20:23], v[210:213], v[132:135], v[20:23]
	v_mfma_f32_16x16x32_bf16 v[16:19], v[210:213], v[156:159], v[16:19]
	v_mfma_f32_16x16x32_bf16 v[80:83], v[202:205], v[164:167], v[76:79]
	v_mfma_f32_16x16x32_bf16 v[4:7], v[210:213], v[164:167], v[4:7]
	v_mfma_f32_16x16x32_bf16 v[72:75], v[202:205], v[194:197], v[72:75]
	v_mfma_f32_16x16x32_bf16 v[0:3], v[210:213], v[194:197], v[0:3]
	v_mfma_f32_16x16x32_bf16 v[52:55], v[202:205], v[132:135], v[52:55]
	s_setprio 0
	s_add_i32 s68, 0, 0x18000
	v_add_u32_e32 v108, s68, v237
	s_barrier
	ds_read_b128 v[76:79], v108
	ds_read_b128 v[92:95], v108 offset:1024
	ds_read_b128 v[104:107], v108 offset:2048
	ds_read_b128 v[108:111], v108 offset:3072
	s_add_u32 s12, s12, 0x40000
	s_addc_u32 s13, s13, 0
	s_mov_b32 m0, s56
	v_lshl_add_u64 v[140:141], s[12:13], 0, v[180:181]
	ds_read_b128 v[124:127], v238 offset:32768
	ds_read_b128 v[132:135], v238 offset:33792
	ds_read_b128 v[156:159], v238 offset:34816
	ds_read_b128 v[160:163], v238 offset:35840
	ds_read_b128 v[164:167], v238 offset:36864
	ds_read_b128 v[190:193], v238 offset:37888
	ds_read_b128 v[194:197], v238 offset:38912
	ds_read_b128 v[198:201], v238 offset:39936
	global_load_lds_dwordx4 v[140:141], off
	s_mov_b32 m0, s57
	v_lshl_add_u64 v[140:141], s[12:13], 0, v[182:183]
	global_load_lds_dwordx4 v[140:141], off
	s_waitcnt lgkmcnt(8)
	s_barrier
	s_waitcnt lgkmcnt(0)
	s_setprio 1
	v_mfma_f32_16x16x32_bf16 v[140:143], v[76:79], v[124:127], v[152:155]
	v_mfma_f32_16x16x32_bf16 v[152:155], v[92:95], v[132:135], v[140:143]
	v_mfma_f32_16x16x32_bf16 v[68:71], v[104:107], v[124:127], v[68:71]
	v_mfma_f32_16x16x32_bf16 v[140:143], v[76:79], v[156:159], v[148:151]
	v_mfma_f32_16x16x32_bf16 v[64:67], v[104:107], v[156:159], v[64:67]
	v_mfma_f32_16x16x32_bf16 v[136:139], v[76:79], v[164:167], v[136:139]
	v_mfma_f32_16x16x32_bf16 v[44:47], v[104:107], v[164:167], v[44:47]
	v_mfma_f32_16x16x32_bf16 v[128:131], v[76:79], v[194:197], v[128:131]
	v_mfma_f32_16x16x32_bf16 v[40:43], v[104:107], v[194:197], v[40:43]
	v_mfma_f32_16x16x32_bf16 v[68:71], v[108:111], v[132:135], v[68:71]
	v_mfma_f32_16x16x32_bf16 v[148:151], v[92:95], v[160:163], v[140:143]
	v_mfma_f32_16x16x32_bf16 v[64:67], v[108:111], v[160:163], v[64:67]
	v_mfma_f32_16x16x32_bf16 v[136:139], v[92:95], v[190:193], v[136:139]
	v_mfma_f32_16x16x32_bf16 v[44:47], v[108:111], v[190:193], v[44:47]
	v_mfma_f32_16x16x32_bf16 v[128:131], v[92:95], v[198:201], v[128:131]
	v_mfma_f32_16x16x32_bf16 v[40:43], v[108:111], v[198:201], v[40:43]
	s_setprio 0
	s_barrier
	s_add_i32 s12, 0, 0x1c000
	v_add_u32_e32 v140, s12, v237
	s_add_i32 s13, s68, s53
	ds_read_b128 v[202:205], v140
	ds_read_b128 v[206:209], v140 offset:1024
	ds_read_b128 v[210:213], v140 offset:2048
	ds_read_b128 v[214:217], v140 offset:3072
	s_mov_b32 m0, s13
	v_lshl_add_u64 v[140:141], v[218:219], 0, s[78:79]
	global_load_lds_dwordx4 v[140:141], off
	s_add_i32 m0, s13, 0x2000
	v_lshl_add_u64 v[140:141], v[220:221], 0, s[78:79]
	global_load_lds_dwordx4 v[140:141], off
	s_barrier
	s_waitcnt lgkmcnt(0)
	s_setprio 1
	v_mfma_f32_16x16x32_bf16 v[140:143], v[202:205], v[124:127], v[144:147]
	v_mfma_f32_16x16x32_bf16 v[112:115], v[202:205], v[156:159], v[112:115]
	v_mfma_f32_16x16x32_bf16 v[144:147], v[206:209], v[132:135], v[140:143]
	v_mfma_f32_16x16x32_bf16 v[60:63], v[210:213], v[124:127], v[60:63]
	v_mfma_f32_16x16x32_bf16 v[140:143], v[206:209], v[160:163], v[112:115]
	v_mfma_f32_16x16x32_bf16 v[112:115], v[202:205], v[164:167], v[116:119]
	v_mfma_f32_16x16x32_bf16 v[60:63], v[214:217], v[132:135], v[60:63]
	v_mfma_f32_16x16x32_bf16 v[56:59], v[210:213], v[156:159], v[56:59]
	v_mfma_f32_16x16x32_bf16 v[132:135], v[206:209], v[190:193], v[112:115]
	v_mfma_f32_16x16x32_bf16 v[36:39], v[210:213], v[164:167], v[36:39]
	v_mfma_f32_16x16x32_bf16 v[112:115], v[202:205], v[194:197], v[120:123]
	v_mfma_f32_16x16x32_bf16 v[32:35], v[210:213], v[194:197], v[32:35]
	v_mfma_f32_16x16x32_bf16 v[56:59], v[214:217], v[160:163], v[56:59]
	v_mfma_f32_16x16x32_bf16 v[36:39], v[214:217], v[190:193], v[36:39]
	v_mfma_f32_16x16x32_bf16 v[124:127], v[206:209], v[198:201], v[112:115]
	v_mfma_f32_16x16x32_bf16 v[32:35], v[214:217], v[198:201], v[32:35]
	s_setprio 0
	s_mov_b32 m0, s62
	v_lshl_add_u64 v[198:199], v[222:223], 0, s[78:79]
	s_barrier
	ds_read_b128 v[112:115], v238 offset:49152
	ds_read_b128 v[116:119], v238 offset:50176
	ds_read_b128 v[120:123], v238 offset:51200
	ds_read_b128 v[156:159], v238 offset:52224
	ds_read_b128 v[160:163], v238 offset:53248
	ds_read_b128 v[164:167], v238 offset:54272
	ds_read_b128 v[190:193], v238 offset:55296
	ds_read_b128 v[194:197], v238 offset:56320
	global_load_lds_dwordx4 v[198:199], off
	s_mov_b32 m0, s63
	v_lshl_add_u64 v[198:199], v[240:241], 0, s[78:79]
	global_load_lds_dwordx4 v[198:199], off
	s_barrier
	s_waitcnt lgkmcnt(0)
	s_setprio 1
	v_mfma_f32_16x16x32_bf16 v[100:103], v[76:79], v[112:115], v[100:103]
	v_mfma_f32_16x16x32_bf16 v[28:31], v[104:107], v[112:115], v[28:31]
	v_mfma_f32_16x16x32_bf16 v[96:99], v[76:79], v[120:123], v[96:99]
	v_mfma_f32_16x16x32_bf16 v[24:27], v[104:107], v[120:123], v[24:27]
	v_mfma_f32_16x16x32_bf16 v[84:87], v[76:79], v[160:163], v[84:87]
	v_mfma_f32_16x16x32_bf16 v[12:15], v[104:107], v[160:163], v[12:15]
	v_mfma_f32_16x16x32_bf16 v[48:51], v[76:79], v[190:193], v[48:51]
	v_mfma_f32_16x16x32_bf16 v[8:11], v[104:107], v[190:193], v[8:11]
	v_mfma_f32_16x16x32_bf16 v[100:103], v[92:95], v[116:119], v[100:103]
	v_mfma_f32_16x16x32_bf16 v[28:31], v[108:111], v[116:119], v[28:31]
	v_mfma_f32_16x16x32_bf16 v[96:99], v[92:95], v[156:159], v[96:99]
	v_mfma_f32_16x16x32_bf16 v[24:27], v[108:111], v[156:159], v[24:27]
	v_mfma_f32_16x16x32_bf16 v[84:87], v[92:95], v[164:167], v[84:87]
	v_mfma_f32_16x16x32_bf16 v[12:15], v[108:111], v[164:167], v[12:15]
	v_mfma_f32_16x16x32_bf16 v[76:79], v[92:95], v[194:197], v[48:51]
	v_mfma_f32_16x16x32_bf16 v[8:11], v[108:111], v[194:197], v[8:11]
	s_setprio 0
	s_barrier
	s_add_u32 s2, s2, 0x40080
	s_addc_u32 s3, s3, 0
	s_add_i32 s12, s12, s53
	s_mov_b32 m0, s12
	v_lshl_add_u64 v[48:49], s[2:3], 0, v[168:169]
	global_load_lds_dwordx4 v[48:49], off
	s_add_i32 m0, s12, 0x2000
	v_lshl_add_u64 v[48:49], s[2:3], 0, v[184:185]
	global_load_lds_dwordx4 v[48:49], off
	s_waitcnt vmcnt(6)
	s_barrier
	s_setprio 1
	v_mfma_f32_16x16x32_bf16 v[48:51], v[202:205], v[112:115], v[52:55]
	v_mfma_f32_16x16x32_bf16 v[92:95], v[206:209], v[116:119], v[48:51]
	v_mfma_f32_16x16x32_bf16 v[48:51], v[202:205], v[120:123], v[88:91]
	v_mfma_f32_16x16x32_bf16 v[88:91], v[206:209], v[156:159], v[48:51]
	v_mfma_f32_16x16x32_bf16 v[48:51], v[202:205], v[160:163], v[80:83]
	v_mfma_f32_16x16x32_bf16 v[20:23], v[210:213], v[112:115], v[20:23]
	v_mfma_f32_16x16x32_bf16 v[16:19], v[210:213], v[120:123], v[16:19]
	v_mfma_f32_16x16x32_bf16 v[80:83], v[206:209], v[164:167], v[48:51]
	v_mfma_f32_16x16x32_bf16 v[4:7], v[210:213], v[160:163], v[4:7]
	v_mfma_f32_16x16x32_bf16 v[48:51], v[202:205], v[190:193], v[72:75]
	v_mfma_f32_16x16x32_bf16 v[0:3], v[210:213], v[190:193], v[0:3]
	v_mfma_f32_16x16x32_bf16 v[20:23], v[214:217], v[116:119], v[20:23]
	v_mfma_f32_16x16x32_bf16 v[16:19], v[214:217], v[156:159], v[16:19]
	v_mfma_f32_16x16x32_bf16 v[4:7], v[214:217], v[164:167], v[4:7]
	v_mfma_f32_16x16x32_bf16 v[72:75], v[206:209], v[194:197], v[48:51]
	v_mfma_f32_16x16x32_bf16 v[0:3], v[214:217], v[194:197], v[0:3]
	s_setprio 0
	s_add_i32 s67, s67, 2
	s_add_u32 s10, s10, 0x100
	s_addc_u32 s11, s11, 0
	s_add_u32 s37, s37, 0x100
	s_addc_u32 s39, s39, 0
	s_cmp_gt_u32 s67, 13
	s_barrier
.LBB0_880:
	s_add_u32 s2, s10, 0xfffc0080
	s_addc_u32 s3, s11, -1
	s_add_i32 s68, 0, 0x10000
	v_add_u32_e32 v108, s68, v237
	ds_read_b128 v[48:51], v108
	ds_read_b128 v[52:55], v108 offset:1024
	ds_read_b128 v[104:107], v108 offset:2048
	ds_read_b128 v[108:111], v108 offset:3072
	s_cmp_eq_u32 s67, 12
	s_cselect_b32 s13, s1, s3
	s_cselect_b32 s12, s9, s2
	s_cselect_b32 s3, s14, s39
	s_cselect_b32 s2, s15, s37
	v_lshl_add_u64 v[198:199], s[10:11], 0, v[186:187]
	s_add_i32 m0, s54, 0xc000
	ds_read_b128 v[112:115], v238
	ds_read_b128 v[116:119], v238 offset:1024
	ds_read_b128 v[120:123], v238 offset:2048
	ds_read_b128 v[156:159], v238 offset:3072
	ds_read_b128 v[160:163], v238 offset:4096
	ds_read_b128 v[164:167], v238 offset:5120
	ds_read_b128 v[190:193], v238 offset:6144
	ds_read_b128 v[194:197], v238 offset:7168
	global_load_lds_dwordx4 v[198:199], off
	s_add_i32 m0, s54, 0xe000
	v_lshl_add_u64 v[198:199], s[10:11], 0, v[188:189]
	global_load_lds_dwordx4 v[198:199], off
	s_waitcnt lgkmcnt(8)
	s_barrier
	s_waitcnt lgkmcnt(0)
	s_setprio 1
	v_mfma_f32_16x16x32_bf16 v[152:155], v[48:51], v[112:115], v[152:155]
	v_mfma_f32_16x16x32_bf16 v[68:71], v[104:107], v[112:115], v[68:71]
	v_mfma_f32_16x16x32_bf16 v[148:151], v[48:51], v[120:123], v[148:151]
	v_mfma_f32_16x16x32_bf16 v[64:67], v[104:107], v[120:123], v[64:67]
	v_mfma_f32_16x16x32_bf16 v[136:139], v[48:51], v[160:163], v[136:139]
	v_mfma_f32_16x16x32_bf16 v[44:47], v[104:107], v[160:163], v[44:47]
	v_mfma_f32_16x16x32_bf16 v[128:131], v[48:51], v[190:193], v[128:131]
	v_mfma_f32_16x16x32_bf16 v[40:43], v[104:107], v[190:193], v[40:43]
	v_mfma_f32_16x16x32_bf16 v[152:155], v[52:55], v[116:119], v[152:155]
	v_mfma_f32_16x16x32_bf16 v[68:71], v[108:111], v[116:119], v[68:71]
	v_mfma_f32_16x16x32_bf16 v[148:151], v[52:55], v[156:159], v[148:151]
	v_mfma_f32_16x16x32_bf16 v[64:67], v[108:111], v[156:159], v[64:67]
	v_mfma_f32_16x16x32_bf16 v[136:139], v[52:55], v[164:167], v[136:139]
	v_mfma_f32_16x16x32_bf16 v[44:47], v[108:111], v[164:167], v[44:47]
	v_mfma_f32_16x16x32_bf16 v[128:131], v[52:55], v[194:197], v[128:131]
	v_mfma_f32_16x16x32_bf16 v[40:43], v[108:111], v[194:197], v[40:43]
	s_setprio 0
	s_barrier
	s_add_i32 s70, 0, 0x14000
	s_add_i32 s68, s68, s53
	v_add_u32_e32 v210, s70, v237
	v_lshl_add_u64 v[218:219], s[2:3], 0, v[168:169]
	s_mov_b32 m0, s68
	ds_read_b128 v[198:201], v210
	ds_read_b128 v[202:205], v210 offset:1024
	ds_read_b128 v[206:209], v210 offset:2048
	ds_read_b128 v[210:213], v210 offset:3072
	global_load_lds_dwordx4 v[218:219], off
	s_add_i32 m0, s68, 0x2000
	v_lshl_add_u64 v[220:221], s[2:3], 0, v[184:185]
	global_load_lds_dwordx4 v[220:221], off
	s_barrier
	s_waitcnt lgkmcnt(0)
	s_setprio 1
	v_mfma_f32_16x16x32_bf16 v[144:147], v[198:201], v[112:115], v[144:147]
	v_mfma_f32_16x16x32_bf16 v[60:63], v[206:209], v[112:115], v[60:63]
	v_mfma_f32_16x16x32_bf16 v[56:59], v[206:209], v[120:123], v[56:59]
	v_mfma_f32_16x16x32_bf16 v[36:39], v[206:209], v[160:163], v[36:39]
	v_mfma_f32_16x16x32_bf16 v[32:35], v[206:209], v[190:193], v[32:35]
	v_mfma_f32_16x16x32_bf16 v[144:147], v[202:205], v[116:119], v[144:147]
	v_mfma_f32_16x16x32_bf16 v[60:63], v[210:213], v[116:119], v[60:63]
	v_mfma_f32_16x16x32_bf16 v[112:115], v[198:201], v[120:123], v[140:143]
	v_mfma_f32_16x16x32_bf16 v[56:59], v[210:213], v[156:159], v[56:59]
	v_mfma_f32_16x16x32_bf16 v[116:119], v[198:201], v[160:163], v[132:135]
	v_mfma_f32_16x16x32_bf16 v[36:39], v[210:213], v[164:167], v[36:39]
	v_mfma_f32_16x16x32_bf16 v[120:123], v[198:201], v[190:193], v[124:127]
	v_mfma_f32_16x16x32_bf16 v[32:35], v[210:213], v[194:197], v[32:35]
	v_mfma_f32_16x16x32_bf16 v[112:115], v[202:205], v[156:159], v[112:115]
	v_mfma_f32_16x16x32_bf16 v[116:119], v[202:205], v[164:167], v[116:119]
	v_mfma_f32_16x16x32_bf16 v[120:123], v[202:205], v[194:197], v[120:123]
	s_setprio 0
	s_mov_b32 m0, s54
	v_lshl_add_u64 v[222:223], s[12:13], 0, v[180:181]
	s_barrier
	ds_read_b128 v[124:127], v238 offset:16384
	ds_read_b128 v[132:135], v238 offset:17408
	ds_read_b128 v[140:143], v238 offset:18432
	ds_read_b128 v[156:159], v238 offset:19456
	ds_read_b128 v[160:163], v238 offset:20480
	ds_read_b128 v[164:167], v238 offset:21504
	ds_read_b128 v[190:193], v238 offset:22528
	ds_read_b128 v[194:197], v238 offset:23552
	global_load_lds_dwordx4 v[222:223], off
	s_mov_b32 m0, s55
	v_lshl_add_u64 v[240:241], s[12:13], 0, v[182:183]
	global_load_lds_dwordx4 v[240:241], off
	s_barrier
	s_waitcnt lgkmcnt(0)
	s_setprio 1
	v_mfma_f32_16x16x32_bf16 v[100:103], v[48:51], v[124:127], v[100:103]
	v_mfma_f32_16x16x32_bf16 v[28:31], v[104:107], v[124:127], v[28:31]
	v_mfma_f32_16x16x32_bf16 v[96:99], v[48:51], v[140:143], v[96:99]
	v_mfma_f32_16x16x32_bf16 v[24:27], v[104:107], v[140:143], v[24:27]
	v_mfma_f32_16x16x32_bf16 v[84:87], v[48:51], v[160:163], v[84:87]
	v_mfma_f32_16x16x32_bf16 v[12:15], v[104:107], v[160:163], v[12:15]
	v_mfma_f32_16x16x32_bf16 v[8:11], v[104:107], v[190:193], v[8:11]
	v_mfma_f32_16x16x32_bf16 v[100:103], v[52:55], v[132:135], v[100:103]
	v_mfma_f32_16x16x32_bf16 v[28:31], v[108:111], v[132:135], v[28:31]
	v_mfma_f32_16x16x32_bf16 v[96:99], v[52:55], v[156:159], v[96:99]
	v_mfma_f32_16x16x32_bf16 v[24:27], v[108:111], v[156:159], v[24:27]
	v_mfma_f32_16x16x32_bf16 v[84:87], v[52:55], v[164:167], v[84:87]
	v_mfma_f32_16x16x32_bf16 v[12:15], v[108:111], v[164:167], v[12:15]
	v_mfma_f32_16x16x32_bf16 v[48:51], v[48:51], v[190:193], v[76:79]
	v_mfma_f32_16x16x32_bf16 v[8:11], v[108:111], v[194:197], v[8:11]
	v_mfma_f32_16x16x32_bf16 v[48:51], v[52:55], v[194:197], v[48:51]
	s_setprio 0
	s_barrier
	s_add_u32 s68, s2, 0x40000
	s_addc_u32 s69, s3, 0
	s_add_i32 s70, s70, s53
	s_mov_b32 m0, s70
	v_lshl_add_u64 v[52:53], s[68:69], 0, v[168:169]
	global_load_lds_dwordx4 v[52:53], off
	s_add_i32 m0, s70, 0x2000
	v_lshl_add_u64 v[52:53], s[68:69], 0, v[184:185]
	global_load_lds_dwordx4 v[52:53], off
	s_waitcnt vmcnt(6)
	s_barrier
	s_setprio 1
	v_mfma_f32_16x16x32_bf16 v[76:79], v[198:201], v[140:143], v[88:91]
	v_mfma_f32_16x16x32_bf16 v[20:23], v[206:209], v[124:127], v[20:23]
	v_mfma_f32_16x16x32_bf16 v[88:91], v[202:205], v[156:159], v[76:79]
	v_mfma_f32_16x16x32_bf16 v[16:19], v[206:209], v[140:143], v[16:19]
	v_mfma_f32_16x16x32_bf16 v[76:79], v[198:201], v[160:163], v[80:83]
	v_mfma_f32_16x16x32_bf16 v[4:7], v[206:209], v[160:163], v[4:7]
	v_mfma_f32_16x16x32_bf16 v[72:75], v[198:201], v[190:193], v[72:75]
	v_mfma_f32_16x16x32_bf16 v[0:3], v[206:209], v[190:193], v[0:3]
	v_mfma_f32_16x16x32_bf16 v[52:55], v[198:201], v[124:127], v[92:95]
	v_mfma_f32_16x16x32_bf16 v[20:23], v[210:213], v[132:135], v[20:23]
	v_mfma_f32_16x16x32_bf16 v[16:19], v[210:213], v[156:159], v[16:19]
	v_mfma_f32_16x16x32_bf16 v[80:83], v[202:205], v[164:167], v[76:79]
	v_mfma_f32_16x16x32_bf16 v[4:7], v[210:213], v[164:167], v[4:7]
	v_mfma_f32_16x16x32_bf16 v[72:75], v[202:205], v[194:197], v[72:75]
	v_mfma_f32_16x16x32_bf16 v[0:3], v[210:213], v[194:197], v[0:3]
	v_mfma_f32_16x16x32_bf16 v[52:55], v[202:205], v[132:135], v[52:55]
	s_setprio 0
	s_add_i32 s68, 0, 0x18000
	v_add_u32_e32 v108, s68, v237
	s_barrier
	ds_read_b128 v[76:79], v108
	ds_read_b128 v[92:95], v108 offset:1024
	ds_read_b128 v[104:107], v108 offset:2048
	ds_read_b128 v[108:111], v108 offset:3072
	s_add_u32 s12, s12, 0x40000
	s_addc_u32 s13, s13, 0
	s_mov_b32 m0, s56
	v_lshl_add_u64 v[140:141], s[12:13], 0, v[180:181]
	ds_read_b128 v[124:127], v238 offset:32768
	ds_read_b128 v[132:135], v238 offset:33792
	ds_read_b128 v[156:159], v238 offset:34816
	ds_read_b128 v[160:163], v238 offset:35840
	ds_read_b128 v[164:167], v238 offset:36864
	ds_read_b128 v[190:193], v238 offset:37888
	ds_read_b128 v[194:197], v238 offset:38912
	ds_read_b128 v[198:201], v238 offset:39936
	global_load_lds_dwordx4 v[140:141], off
	s_mov_b32 m0, s57
	v_lshl_add_u64 v[140:141], s[12:13], 0, v[182:183]
	global_load_lds_dwordx4 v[140:141], off
	s_waitcnt lgkmcnt(8)
	s_barrier
	s_waitcnt lgkmcnt(0)
	s_setprio 1
	v_mfma_f32_16x16x32_bf16 v[140:143], v[76:79], v[124:127], v[152:155]
	v_mfma_f32_16x16x32_bf16 v[152:155], v[92:95], v[132:135], v[140:143]
	v_mfma_f32_16x16x32_bf16 v[68:71], v[104:107], v[124:127], v[68:71]
	v_mfma_f32_16x16x32_bf16 v[140:143], v[76:79], v[156:159], v[148:151]
	v_mfma_f32_16x16x32_bf16 v[64:67], v[104:107], v[156:159], v[64:67]
	v_mfma_f32_16x16x32_bf16 v[136:139], v[76:79], v[164:167], v[136:139]
	v_mfma_f32_16x16x32_bf16 v[44:47], v[104:107], v[164:167], v[44:47]
	v_mfma_f32_16x16x32_bf16 v[128:131], v[76:79], v[194:197], v[128:131]
	v_mfma_f32_16x16x32_bf16 v[40:43], v[104:107], v[194:197], v[40:43]
	v_mfma_f32_16x16x32_bf16 v[68:71], v[108:111], v[132:135], v[68:71]
	v_mfma_f32_16x16x32_bf16 v[148:151], v[92:95], v[160:163], v[140:143]
	v_mfma_f32_16x16x32_bf16 v[64:67], v[108:111], v[160:163], v[64:67]
	v_mfma_f32_16x16x32_bf16 v[136:139], v[92:95], v[190:193], v[136:139]
	v_mfma_f32_16x16x32_bf16 v[44:47], v[108:111], v[190:193], v[44:47]
	v_mfma_f32_16x16x32_bf16 v[128:131], v[92:95], v[198:201], v[128:131]
	v_mfma_f32_16x16x32_bf16 v[40:43], v[108:111], v[198:201], v[40:43]
	s_setprio 0
	s_barrier
	s_add_i32 s12, 0, 0x1c000
	v_add_u32_e32 v140, s12, v237
	s_add_i32 s13, s68, s53
	ds_read_b128 v[202:205], v140
	ds_read_b128 v[206:209], v140 offset:1024
	ds_read_b128 v[210:213], v140 offset:2048
	ds_read_b128 v[214:217], v140 offset:3072
	s_mov_b32 m0, s13
	v_lshl_add_u64 v[140:141], v[218:219], 0, s[78:79]
	global_load_lds_dwordx4 v[140:141], off
	s_add_i32 m0, s13, 0x2000
	v_lshl_add_u64 v[140:141], v[220:221], 0, s[78:79]
	global_load_lds_dwordx4 v[140:141], off
	s_barrier
	s_waitcnt lgkmcnt(0)
	s_setprio 1
	v_mfma_f32_16x16x32_bf16 v[140:143], v[202:205], v[124:127], v[144:147]
	v_mfma_f32_16x16x32_bf16 v[112:115], v[202:205], v[156:159], v[112:115]
	v_mfma_f32_16x16x32_bf16 v[144:147], v[206:209], v[132:135], v[140:143]
	v_mfma_f32_16x16x32_bf16 v[60:63], v[210:213], v[124:127], v[60:63]
	v_mfma_f32_16x16x32_bf16 v[140:143], v[206:209], v[160:163], v[112:115]
	v_mfma_f32_16x16x32_bf16 v[112:115], v[202:205], v[164:167], v[116:119]
	v_mfma_f32_16x16x32_bf16 v[60:63], v[214:217], v[132:135], v[60:63]
	v_mfma_f32_16x16x32_bf16 v[56:59], v[210:213], v[156:159], v[56:59]
	v_mfma_f32_16x16x32_bf16 v[132:135], v[206:209], v[190:193], v[112:115]
	v_mfma_f32_16x16x32_bf16 v[36:39], v[210:213], v[164:167], v[36:39]
	v_mfma_f32_16x16x32_bf16 v[112:115], v[202:205], v[194:197], v[120:123]
	v_mfma_f32_16x16x32_bf16 v[32:35], v[210:213], v[194:197], v[32:35]
	v_mfma_f32_16x16x32_bf16 v[56:59], v[214:217], v[160:163], v[56:59]
	v_mfma_f32_16x16x32_bf16 v[36:39], v[214:217], v[190:193], v[36:39]
	v_mfma_f32_16x16x32_bf16 v[124:127], v[206:209], v[198:201], v[112:115]
	v_mfma_f32_16x16x32_bf16 v[32:35], v[214:217], v[198:201], v[32:35]
	s_setprio 0
	s_mov_b32 m0, s62
	v_lshl_add_u64 v[198:199], v[222:223], 0, s[78:79]
	s_barrier
	ds_read_b128 v[112:115], v238 offset:49152
	ds_read_b128 v[116:119], v238 offset:50176
	ds_read_b128 v[120:123], v238 offset:51200
	ds_read_b128 v[156:159], v238 offset:52224
	ds_read_b128 v[160:163], v238 offset:53248
	ds_read_b128 v[164:167], v238 offset:54272
	ds_read_b128 v[190:193], v238 offset:55296
	ds_read_b128 v[194:197], v238 offset:56320
	global_load_lds_dwordx4 v[198:199], off
	s_mov_b32 m0, s63
	v_lshl_add_u64 v[198:199], v[240:241], 0, s[78:79]
	global_load_lds_dwordx4 v[198:199], off
	s_barrier
	s_waitcnt lgkmcnt(0)
	s_setprio 1
	v_mfma_f32_16x16x32_bf16 v[100:103], v[76:79], v[112:115], v[100:103]
	v_mfma_f32_16x16x32_bf16 v[28:31], v[104:107], v[112:115], v[28:31]
	v_mfma_f32_16x16x32_bf16 v[96:99], v[76:79], v[120:123], v[96:99]
	v_mfma_f32_16x16x32_bf16 v[24:27], v[104:107], v[120:123], v[24:27]
	v_mfma_f32_16x16x32_bf16 v[84:87], v[76:79], v[160:163], v[84:87]
	v_mfma_f32_16x16x32_bf16 v[12:15], v[104:107], v[160:163], v[12:15]
	v_mfma_f32_16x16x32_bf16 v[48:51], v[76:79], v[190:193], v[48:51]
	v_mfma_f32_16x16x32_bf16 v[8:11], v[104:107], v[190:193], v[8:11]
	v_mfma_f32_16x16x32_bf16 v[100:103], v[92:95], v[116:119], v[100:103]
	v_mfma_f32_16x16x32_bf16 v[28:31], v[108:111], v[116:119], v[28:31]
	v_mfma_f32_16x16x32_bf16 v[96:99], v[92:95], v[156:159], v[96:99]
	v_mfma_f32_16x16x32_bf16 v[24:27], v[108:111], v[156:159], v[24:27]
	v_mfma_f32_16x16x32_bf16 v[84:87], v[92:95], v[164:167], v[84:87]
	v_mfma_f32_16x16x32_bf16 v[12:15], v[108:111], v[164:167], v[12:15]
	v_mfma_f32_16x16x32_bf16 v[76:79], v[92:95], v[194:197], v[48:51]
	v_mfma_f32_16x16x32_bf16 v[8:11], v[108:111], v[194:197], v[8:11]
	s_setprio 0
	s_barrier
	s_add_u32 s2, s2, 0x40080
	s_addc_u32 s3, s3, 0
	s_add_i32 s12, s12, s53
	s_mov_b32 m0, s12
	v_lshl_add_u64 v[48:49], s[2:3], 0, v[168:169]
	global_load_lds_dwordx4 v[48:49], off
	s_add_i32 m0, s12, 0x2000
	v_lshl_add_u64 v[48:49], s[2:3], 0, v[184:185]
	global_load_lds_dwordx4 v[48:49], off
	s_waitcnt vmcnt(6)
	s_barrier
	s_setprio 1
	v_mfma_f32_16x16x32_bf16 v[48:51], v[202:205], v[112:115], v[52:55]
	v_mfma_f32_16x16x32_bf16 v[92:95], v[206:209], v[116:119], v[48:51]
	v_mfma_f32_16x16x32_bf16 v[48:51], v[202:205], v[120:123], v[88:91]
	v_mfma_f32_16x16x32_bf16 v[88:91], v[206:209], v[156:159], v[48:51]
	v_mfma_f32_16x16x32_bf16 v[48:51], v[202:205], v[160:163], v[80:83]
	v_mfma_f32_16x16x32_bf16 v[20:23], v[210:213], v[112:115], v[20:23]
	v_mfma_f32_16x16x32_bf16 v[16:19], v[210:213], v[120:123], v[16:19]
	v_mfma_f32_16x16x32_bf16 v[80:83], v[206:209], v[164:167], v[48:51]
	v_mfma_f32_16x16x32_bf16 v[4:7], v[210:213], v[160:163], v[4:7]
	v_mfma_f32_16x16x32_bf16 v[48:51], v[202:205], v[190:193], v[72:75]
	v_mfma_f32_16x16x32_bf16 v[0:3], v[210:213], v[190:193], v[0:3]
	v_mfma_f32_16x16x32_bf16 v[20:23], v[214:217], v[116:119], v[20:23]
	v_mfma_f32_16x16x32_bf16 v[16:19], v[214:217], v[156:159], v[16:19]
	v_mfma_f32_16x16x32_bf16 v[4:7], v[214:217], v[164:167], v[4:7]
	v_mfma_f32_16x16x32_bf16 v[72:75], v[206:209], v[194:197], v[48:51]
	v_mfma_f32_16x16x32_bf16 v[0:3], v[214:217], v[194:197], v[0:3]
	s_setprio 0
	s_add_i32 s67, s67, 2
	s_add_u32 s10, s10, 0x100
	s_addc_u32 s11, s11, 0
	s_add_u32 s37, s37, 0x100
	s_addc_u32 s39, s39, 0
	s_cmp_gt_u32 s67, 13
	s_barrier
	s_cbranch_scc0 .LBB0_880

.Lup_half_peel:
	s_add_u32 s2, s10, 0xfffc0080
	s_addc_u32 s3, s11, -1
	s_add_i32 s68, 0, 0x10000
	v_add_u32_e32 v108, s68, v237
	ds_read_b128 v[48:51], v108
	ds_read_b128 v[52:55], v108 offset:1024
	ds_read_b128 v[104:107], v108 offset:2048
	ds_read_b128 v[108:111], v108 offset:3072
	s_cmp_eq_u32 s67, 12
	s_cselect_b32 s13, s1, s3
	s_cselect_b32 s12, s9, s2
	s_cselect_b32 s3, s14, s39
	s_cselect_b32 s2, s15, s37
	v_lshl_add_u64 v[198:199], s[10:11], 0, v[186:187]
	s_add_i32 m0, s54, 0xc000
	ds_read_b128 v[112:115], v238
	ds_read_b128 v[116:119], v238 offset:1024
	ds_read_b128 v[120:123], v238 offset:2048
	ds_read_b128 v[156:159], v238 offset:3072
	ds_read_b128 v[160:163], v238 offset:4096
	ds_read_b128 v[164:167], v238 offset:5120
	ds_read_b128 v[190:193], v238 offset:6144
	ds_read_b128 v[194:197], v238 offset:7168
	global_load_lds_dwordx4 v[198:199], off
	s_add_i32 m0, s54, 0xe000
	v_lshl_add_u64 v[198:199], s[10:11], 0, v[188:189]
	global_load_lds_dwordx4 v[198:199], off
	s_waitcnt lgkmcnt(8)
	s_barrier
	s_waitcnt lgkmcnt(0)
	s_setprio 1
	v_mfma_f32_16x16x32_bf16 v[152:155], v[48:51], v[112:115], 0
	v_mfma_f32_16x16x32_bf16 v[68:71], v[104:107], v[112:115], 0
	v_mfma_f32_16x16x32_bf16 v[148:151], v[48:51], v[120:123], 0
	v_mfma_f32_16x16x32_bf16 v[64:67], v[104:107], v[120:123], 0
	v_mfma_f32_16x16x32_bf16 v[136:139], v[48:51], v[160:163], 0
	v_mfma_f32_16x16x32_bf16 v[44:47], v[104:107], v[160:163], 0
	v_mfma_f32_16x16x32_bf16 v[128:131], v[48:51], v[190:193], 0
	v_mfma_f32_16x16x32_bf16 v[40:43], v[104:107], v[190:193], 0
	v_mfma_f32_16x16x32_bf16 v[152:155], v[52:55], v[116:119], v[152:155]
	v_mfma_f32_16x16x32_bf16 v[68:71], v[108:111], v[116:119], v[68:71]
	v_mfma_f32_16x16x32_bf16 v[148:151], v[52:55], v[156:159], v[148:151]
	v_mfma_f32_16x16x32_bf16 v[64:67], v[108:111], v[156:159], v[64:67]
	v_mfma_f32_16x16x32_bf16 v[136:139], v[52:55], v[164:167], v[136:139]
	v_mfma_f32_16x16x32_bf16 v[44:47], v[108:111], v[164:167], v[44:47]
	v_mfma_f32_16x16x32_bf16 v[128:131], v[52:55], v[194:197], v[128:131]
	v_mfma_f32_16x16x32_bf16 v[40:43], v[108:111], v[194:197], v[40:43]
	s_setprio 0
	s_barrier
	s_add_i32 s70, 0, 0x14000
	s_add_i32 s68, s68, s53
	v_add_u32_e32 v210, s70, v237
	v_lshl_add_u64 v[218:219], s[2:3], 0, v[168:169]
	s_mov_b32 m0, s68
	ds_read_b128 v[198:201], v210
	ds_read_b128 v[202:205], v210 offset:1024
	ds_read_b128 v[206:209], v210 offset:2048
	ds_read_b128 v[210:213], v210 offset:3072
	global_load_lds_dwordx4 v[218:219], off
	s_add_i32 m0, s68, 0x2000
	v_lshl_add_u64 v[220:221], s[2:3], 0, v[184:185]
	global_load_lds_dwordx4 v[220:221], off
	s_barrier
	s_waitcnt lgkmcnt(0)
	s_setprio 1
	v_mfma_f32_16x16x32_bf16 v[144:147], v[198:201], v[112:115], 0
	v_mfma_f32_16x16x32_bf16 v[60:63], v[206:209], v[112:115], 0
	v_mfma_f32_16x16x32_bf16 v[56:59], v[206:209], v[120:123], 0
	v_mfma_f32_16x16x32_bf16 v[36:39], v[206:209], v[160:163], 0
	v_mfma_f32_16x16x32_bf16 v[32:35], v[206:209], v[190:193], 0
	v_mfma_f32_16x16x32_bf16 v[144:147], v[202:205], v[116:119], v[144:147]
	v_mfma_f32_16x16x32_bf16 v[60:63], v[210:213], v[116:119], v[60:63]
	v_mfma_f32_16x16x32_bf16 v[112:115], v[198:201], v[120:123], 0
	v_mfma_f32_16x16x32_bf16 v[56:59], v[210:213], v[156:159], v[56:59]
	v_mfma_f32_16x16x32_bf16 v[116:119], v[198:201], v[160:163], 0
	v_mfma_f32_16x16x32_bf16 v[36:39], v[210:213], v[164:167], v[36:39]
	v_mfma_f32_16x16x32_bf16 v[120:123], v[198:201], v[190:193], 0
	v_mfma_f32_16x16x32_bf16 v[32:35], v[210:213], v[194:197], v[32:35]
	v_mfma_f32_16x16x32_bf16 v[112:115], v[202:205], v[156:159], v[112:115]
	v_mfma_f32_16x16x32_bf16 v[116:119], v[202:205], v[164:167], v[116:119]
	v_mfma_f32_16x16x32_bf16 v[120:123], v[202:205], v[194:197], v[120:123]
	s_setprio 0
	s_mov_b32 m0, s54
	v_lshl_add_u64 v[222:223], s[12:13], 0, v[180:181]
	s_barrier
	ds_read_b128 v[124:127], v238 offset:16384
	ds_read_b128 v[132:135], v238 offset:17408
	ds_read_b128 v[140:143], v238 offset:18432
	ds_read_b128 v[156:159], v238 offset:19456
	ds_read_b128 v[160:163], v238 offset:20480
	ds_read_b128 v[164:167], v238 offset:21504
	ds_read_b128 v[190:193], v238 offset:22528
	ds_read_b128 v[194:197], v238 offset:23552
	global_load_lds_dwordx4 v[222:223], off
	s_mov_b32 m0, s55
	v_lshl_add_u64 v[240:241], s[12:13], 0, v[182:183]
	global_load_lds_dwordx4 v[240:241], off
	s_barrier
	s_waitcnt lgkmcnt(0)
	s_setprio 1
	s_setprio 0
	s_barrier
	s_add_u32 s68, s2, 0x40000
	s_addc_u32 s69, s3, 0
	s_add_i32 s70, s70, s53
	s_mov_b32 m0, s70
	v_lshl_add_u64 v[52:53], s[68:69], 0, v[168:169]
	global_load_lds_dwordx4 v[52:53], off
	s_add_i32 m0, s70, 0x2000
	v_lshl_add_u64 v[52:53], s[68:69], 0, v[184:185]
	global_load_lds_dwordx4 v[52:53], off
	s_waitcnt vmcnt(6)
	s_barrier
	s_setprio 1
	s_setprio 0
	s_add_i32 s68, 0, 0x18000
	v_add_u32_e32 v108, s68, v237
	s_barrier
	ds_read_b128 v[76:79], v108
	ds_read_b128 v[92:95], v108 offset:1024
	ds_read_b128 v[104:107], v108 offset:2048
	ds_read_b128 v[108:111], v108 offset:3072
	s_add_u32 s12, s12, 0x40000
	s_addc_u32 s13, s13, 0
	s_mov_b32 m0, s56
	v_lshl_add_u64 v[140:141], s[12:13], 0, v[180:181]
	ds_read_b128 v[124:127], v238 offset:32768
	ds_read_b128 v[132:135], v238 offset:33792
	ds_read_b128 v[156:159], v238 offset:34816
	ds_read_b128 v[160:163], v238 offset:35840
	ds_read_b128 v[164:167], v238 offset:36864
	ds_read_b128 v[190:193], v238 offset:37888
	ds_read_b128 v[194:197], v238 offset:38912
	ds_read_b128 v[198:201], v238 offset:39936
	global_load_lds_dwordx4 v[140:141], off
	s_mov_b32 m0, s57
	v_lshl_add_u64 v[140:141], s[12:13], 0, v[182:183]
	global_load_lds_dwordx4 v[140:141], off
	s_waitcnt lgkmcnt(8)
	s_barrier
	s_waitcnt lgkmcnt(0)
	s_setprio 1
	v_mfma_f32_16x16x32_bf16 v[140:143], v[76:79], v[124:127], v[152:155]
	v_mfma_f32_16x16x32_bf16 v[152:155], v[92:95], v[132:135], v[140:143]
	v_mfma_f32_16x16x32_bf16 v[68:71], v[104:107], v[124:127], v[68:71]
	v_mfma_f32_16x16x32_bf16 v[140:143], v[76:79], v[156:159], v[148:151]
	v_mfma_f32_16x16x32_bf16 v[64:67], v[104:107], v[156:159], v[64:67]
	v_mfma_f32_16x16x32_bf16 v[136:139], v[76:79], v[164:167], v[136:139]
	v_mfma_f32_16x16x32_bf16 v[44:47], v[104:107], v[164:167], v[44:47]
	v_mfma_f32_16x16x32_bf16 v[128:131], v[76:79], v[194:197], v[128:131]
	v_mfma_f32_16x16x32_bf16 v[40:43], v[104:107], v[194:197], v[40:43]
	v_mfma_f32_16x16x32_bf16 v[68:71], v[108:111], v[132:135], v[68:71]
	v_mfma_f32_16x16x32_bf16 v[148:151], v[92:95], v[160:163], v[140:143]
	v_mfma_f32_16x16x32_bf16 v[64:67], v[108:111], v[160:163], v[64:67]
	v_mfma_f32_16x16x32_bf16 v[136:139], v[92:95], v[190:193], v[136:139]
	v_mfma_f32_16x16x32_bf16 v[44:47], v[108:111], v[190:193], v[44:47]
	v_mfma_f32_16x16x32_bf16 v[128:131], v[92:95], v[198:201], v[128:131]
	v_mfma_f32_16x16x32_bf16 v[40:43], v[108:111], v[198:201], v[40:43]
	s_setprio 0
	s_barrier
	s_add_i32 s12, 0, 0x1c000
	v_add_u32_e32 v140, s12, v237
	s_add_i32 s13, s68, s53
	ds_read_b128 v[202:205], v140
	ds_read_b128 v[206:209], v140 offset:1024
	ds_read_b128 v[210:213], v140 offset:2048
	ds_read_b128 v[214:217], v140 offset:3072
	s_mov_b32 m0, s13
	v_lshl_add_u64 v[140:141], v[218:219], 0, s[78:79]
	global_load_lds_dwordx4 v[140:141], off
	s_add_i32 m0, s13, 0x2000
	v_lshl_add_u64 v[140:141], v[220:221], 0, s[78:79]
	global_load_lds_dwordx4 v[140:141], off
	s_barrier
	s_waitcnt lgkmcnt(0)
	s_setprio 1
	v_mfma_f32_16x16x32_bf16 v[140:143], v[202:205], v[124:127], v[144:147]
	v_mfma_f32_16x16x32_bf16 v[112:115], v[202:205], v[156:159], v[112:115]
	v_mfma_f32_16x16x32_bf16 v[144:147], v[206:209], v[132:135], v[140:143]
	v_mfma_f32_16x16x32_bf16 v[60:63], v[210:213], v[124:127], v[60:63]
	v_mfma_f32_16x16x32_bf16 v[140:143], v[206:209], v[160:163], v[112:115]
	v_mfma_f32_16x16x32_bf16 v[112:115], v[202:205], v[164:167], v[116:119]
	v_mfma_f32_16x16x32_bf16 v[60:63], v[214:217], v[132:135], v[60:63]
	v_mfma_f32_16x16x32_bf16 v[56:59], v[210:213], v[156:159], v[56:59]
	v_mfma_f32_16x16x32_bf16 v[132:135], v[206:209], v[190:193], v[112:115]
	v_mfma_f32_16x16x32_bf16 v[36:39], v[210:213], v[164:167], v[36:39]
	v_mfma_f32_16x16x32_bf16 v[112:115], v[202:205], v[194:197], v[120:123]
	v_mfma_f32_16x16x32_bf16 v[32:35], v[210:213], v[194:197], v[32:35]
	v_mfma_f32_16x16x32_bf16 v[56:59], v[214:217], v[160:163], v[56:59]
	v_mfma_f32_16x16x32_bf16 v[36:39], v[214:217], v[190:193], v[36:39]
	v_mfma_f32_16x16x32_bf16 v[124:127], v[206:209], v[198:201], v[112:115]
	v_mfma_f32_16x16x32_bf16 v[32:35], v[214:217], v[198:201], v[32:35]
	s_setprio 0
	s_mov_b32 m0, s62
	v_lshl_add_u64 v[198:199], v[222:223], 0, s[78:79]
	s_barrier
	ds_read_b128 v[112:115], v238 offset:49152
	ds_read_b128 v[116:119], v238 offset:50176
	ds_read_b128 v[120:123], v238 offset:51200
	ds_read_b128 v[156:159], v238 offset:52224
	ds_read_b128 v[160:163], v238 offset:53248
	ds_read_b128 v[164:167], v238 offset:54272
	ds_read_b128 v[190:193], v238 offset:55296
	ds_read_b128 v[194:197], v238 offset:56320
	global_load_lds_dwordx4 v[198:199], off
	s_mov_b32 m0, s63
	v_lshl_add_u64 v[198:199], v[240:241], 0, s[78:79]
	global_load_lds_dwordx4 v[198:199], off
	s_barrier
	s_waitcnt lgkmcnt(0)
	s_setprio 1
	s_setprio 0
	s_barrier
	s_add_u32 s2, s2, 0x40080
	s_addc_u32 s3, s3, 0
	s_add_i32 s12, s12, s53
	s_mov_b32 m0, s12
	v_lshl_add_u64 v[48:49], s[2:3], 0, v[168:169]
	global_load_lds_dwordx4 v[48:49], off
	s_add_i32 m0, s12, 0x2000
	v_lshl_add_u64 v[48:49], s[2:3], 0, v[184:185]
	global_load_lds_dwordx4 v[48:49], off
	s_waitcnt vmcnt(6)
	s_barrier
	s_setprio 1
	s_setprio 0
	s_add_i32 s67, s67, 2
	s_add_u32 s10, s10, 0x100
	s_addc_u32 s11, s11, 0
	s_add_u32 s37, s37, 0x100
	s_addc_u32 s39, s39, 0
	s_cmp_gt_u32 s67, 13
	s_barrier
.Lup_half_loop:
	s_add_u32 s2, s10, 0xfffc0080
	s_addc_u32 s3, s11, -1
	s_add_i32 s68, 0, 0x10000
	v_add_u32_e32 v108, s68, v237
	ds_read_b128 v[48:51], v108
	ds_read_b128 v[52:55], v108 offset:1024
	ds_read_b128 v[104:107], v108 offset:2048
	ds_read_b128 v[108:111], v108 offset:3072
	s_cmp_eq_u32 s67, 12
	s_cselect_b32 s13, s1, s3
	s_cselect_b32 s12, s9, s2
	s_cselect_b32 s3, s14, s39
	s_cselect_b32 s2, s15, s37
	v_lshl_add_u64 v[198:199], s[10:11], 0, v[186:187]
	s_add_i32 m0, s54, 0xc000
	ds_read_b128 v[112:115], v238
	ds_read_b128 v[116:119], v238 offset:1024
	ds_read_b128 v[120:123], v238 offset:2048
	ds_read_b128 v[156:159], v238 offset:3072
	ds_read_b128 v[160:163], v238 offset:4096
	ds_read_b128 v[164:167], v238 offset:5120
	ds_read_b128 v[190:193], v238 offset:6144
	ds_read_b128 v[194:197], v238 offset:7168
	global_load_lds_dwordx4 v[198:199], off
	s_add_i32 m0, s54, 0xe000
	v_lshl_add_u64 v[198:199], s[10:11], 0, v[188:189]
	global_load_lds_dwordx4 v[198:199], off
	s_waitcnt lgkmcnt(8)
	s_barrier
	s_waitcnt lgkmcnt(0)
	s_setprio 1
	v_mfma_f32_16x16x32_bf16 v[152:155], v[48:51], v[112:115], v[152:155]
	v_mfma_f32_16x16x32_bf16 v[68:71], v[104:107], v[112:115], v[68:71]
	v_mfma_f32_16x16x32_bf16 v[148:151], v[48:51], v[120:123], v[148:151]
	v_mfma_f32_16x16x32_bf16 v[64:67], v[104:107], v[120:123], v[64:67]
	v_mfma_f32_16x16x32_bf16 v[136:139], v[48:51], v[160:163], v[136:139]
	v_mfma_f32_16x16x32_bf16 v[44:47], v[104:107], v[160:163], v[44:47]
	v_mfma_f32_16x16x32_bf16 v[128:131], v[48:51], v[190:193], v[128:131]
	v_mfma_f32_16x16x32_bf16 v[40:43], v[104:107], v[190:193], v[40:43]
	v_mfma_f32_16x16x32_bf16 v[152:155], v[52:55], v[116:119], v[152:155]
	v_mfma_f32_16x16x32_bf16 v[68:71], v[108:111], v[116:119], v[68:71]
	v_mfma_f32_16x16x32_bf16 v[148:151], v[52:55], v[156:159], v[148:151]
	v_mfma_f32_16x16x32_bf16 v[64:67], v[108:111], v[156:159], v[64:67]
	v_mfma_f32_16x16x32_bf16 v[136:139], v[52:55], v[164:167], v[136:139]
	v_mfma_f32_16x16x32_bf16 v[44:47], v[108:111], v[164:167], v[44:47]
	v_mfma_f32_16x16x32_bf16 v[128:131], v[52:55], v[194:197], v[128:131]
	v_mfma_f32_16x16x32_bf16 v[40:43], v[108:111], v[194:197], v[40:43]
	s_setprio 0
	s_barrier
	s_add_i32 s70, 0, 0x14000
	s_add_i32 s68, s68, s53
	v_add_u32_e32 v210, s70, v237
	v_lshl_add_u64 v[218:219], s[2:3], 0, v[168:169]
	s_mov_b32 m0, s68
	ds_read_b128 v[198:201], v210
	ds_read_b128 v[202:205], v210 offset:1024
	ds_read_b128 v[206:209], v210 offset:2048
	ds_read_b128 v[210:213], v210 offset:3072
	global_load_lds_dwordx4 v[218:219], off
	s_add_i32 m0, s68, 0x2000
	v_lshl_add_u64 v[220:221], s[2:3], 0, v[184:185]
	global_load_lds_dwordx4 v[220:221], off
	s_barrier
	s_waitcnt lgkmcnt(0)
	s_setprio 1
	v_mfma_f32_16x16x32_bf16 v[144:147], v[198:201], v[112:115], v[144:147]
	v_mfma_f32_16x16x32_bf16 v[60:63], v[206:209], v[112:115], v[60:63]
	v_mfma_f32_16x16x32_bf16 v[56:59], v[206:209], v[120:123], v[56:59]
	v_mfma_f32_16x16x32_bf16 v[36:39], v[206:209], v[160:163], v[36:39]
	v_mfma_f32_16x16x32_bf16 v[32:35], v[206:209], v[190:193], v[32:35]
	v_mfma_f32_16x16x32_bf16 v[144:147], v[202:205], v[116:119], v[144:147]
	v_mfma_f32_16x16x32_bf16 v[60:63], v[210:213], v[116:119], v[60:63]
	v_mfma_f32_16x16x32_bf16 v[112:115], v[198:201], v[120:123], v[140:143]
	v_mfma_f32_16x16x32_bf16 v[56:59], v[210:213], v[156:159], v[56:59]
	v_mfma_f32_16x16x32_bf16 v[116:119], v[198:201], v[160:163], v[132:135]
	v_mfma_f32_16x16x32_bf16 v[36:39], v[210:213], v[164:167], v[36:39]
	v_mfma_f32_16x16x32_bf16 v[120:123], v[198:201], v[190:193], v[124:127]
	v_mfma_f32_16x16x32_bf16 v[32:35], v[210:213], v[194:197], v[32:35]
	v_mfma_f32_16x16x32_bf16 v[112:115], v[202:205], v[156:159], v[112:115]
	v_mfma_f32_16x16x32_bf16 v[116:119], v[202:205], v[164:167], v[116:119]
	v_mfma_f32_16x16x32_bf16 v[120:123], v[202:205], v[194:197], v[120:123]
	s_setprio 0
	s_mov_b32 m0, s54
	v_lshl_add_u64 v[222:223], s[12:13], 0, v[180:181]
	s_barrier
	ds_read_b128 v[124:127], v238 offset:16384
	ds_read_b128 v[132:135], v238 offset:17408
	ds_read_b128 v[140:143], v238 offset:18432
	ds_read_b128 v[156:159], v238 offset:19456
	ds_read_b128 v[160:163], v238 offset:20480
	ds_read_b128 v[164:167], v238 offset:21504
	ds_read_b128 v[190:193], v238 offset:22528
	ds_read_b128 v[194:197], v238 offset:23552
	global_load_lds_dwordx4 v[222:223], off
	s_mov_b32 m0, s55
	v_lshl_add_u64 v[240:241], s[12:13], 0, v[182:183]
	global_load_lds_dwordx4 v[240:241], off
	s_barrier
	s_waitcnt lgkmcnt(0)
	s_setprio 1
	s_setprio 0
	s_barrier
	s_add_u32 s68, s2, 0x40000
	s_addc_u32 s69, s3, 0
	s_add_i32 s70, s70, s53
	s_mov_b32 m0, s70
	v_lshl_add_u64 v[52:53], s[68:69], 0, v[168:169]
	global_load_lds_dwordx4 v[52:53], off
	s_add_i32 m0, s70, 0x2000
	v_lshl_add_u64 v[52:53], s[68:69], 0, v[184:185]
	global_load_lds_dwordx4 v[52:53], off
	s_waitcnt vmcnt(6)
	s_barrier
	s_setprio 1
	s_setprio 0
	s_add_i32 s68, 0, 0x18000
	v_add_u32_e32 v108, s68, v237
	s_barrier
	ds_read_b128 v[76:79], v108
	ds_read_b128 v[92:95], v108 offset:1024
	ds_read_b128 v[104:107], v108 offset:2048
	ds_read_b128 v[108:111], v108 offset:3072
	s_add_u32 s12, s12, 0x40000
	s_addc_u32 s13, s13, 0
	s_mov_b32 m0, s56
	v_lshl_add_u64 v[140:141], s[12:13], 0, v[180:181]
	ds_read_b128 v[124:127], v238 offset:32768
	ds_read_b128 v[132:135], v238 offset:33792
	ds_read_b128 v[156:159], v238 offset:34816
	ds_read_b128 v[160:163], v238 offset:35840
	ds_read_b128 v[164:167], v238 offset:36864
	ds_read_b128 v[190:193], v238 offset:37888
	ds_read_b128 v[194:197], v238 offset:38912
	ds_read_b128 v[198:201], v238 offset:39936
	global_load_lds_dwordx4 v[140:141], off
	s_mov_b32 m0, s57
	v_lshl_add_u64 v[140:141], s[12:13], 0, v[182:183]
	global_load_lds_dwordx4 v[140:141], off
	s_waitcnt lgkmcnt(8)
	s_barrier
	s_waitcnt lgkmcnt(0)
	s_setprio 1
	v_mfma_f32_16x16x32_bf16 v[140:143], v[76:79], v[124:127], v[152:155]
	v_mfma_f32_16x16x32_bf16 v[152:155], v[92:95], v[132:135], v[140:143]
	v_mfma_f32_16x16x32_bf16 v[68:71], v[104:107], v[124:127], v[68:71]
	v_mfma_f32_16x16x32_bf16 v[140:143], v[76:79], v[156:159], v[148:151]
	v_mfma_f32_16x16x32_bf16 v[64:67], v[104:107], v[156:159], v[64:67]
	v_mfma_f32_16x16x32_bf16 v[136:139], v[76:79], v[164:167], v[136:139]
	v_mfma_f32_16x16x32_bf16 v[44:47], v[104:107], v[164:167], v[44:47]
	v_mfma_f32_16x16x32_bf16 v[128:131], v[76:79], v[194:197], v[128:131]
	v_mfma_f32_16x16x32_bf16 v[40:43], v[104:107], v[194:197], v[40:43]
	v_mfma_f32_16x16x32_bf16 v[68:71], v[108:111], v[132:135], v[68:71]
	v_mfma_f32_16x16x32_bf16 v[148:151], v[92:95], v[160:163], v[140:143]
	v_mfma_f32_16x16x32_bf16 v[64:67], v[108:111], v[160:163], v[64:67]
	v_mfma_f32_16x16x32_bf16 v[136:139], v[92:95], v[190:193], v[136:139]
	v_mfma_f32_16x16x32_bf16 v[44:47], v[108:111], v[190:193], v[44:47]
	v_mfma_f32_16x16x32_bf16 v[128:131], v[92:95], v[198:201], v[128:131]
	v_mfma_f32_16x16x32_bf16 v[40:43], v[108:111], v[198:201], v[40:43]
	s_setprio 0
	s_barrier
	s_add_i32 s12, 0, 0x1c000
	v_add_u32_e32 v140, s12, v237
	s_add_i32 s13, s68, s53
	ds_read_b128 v[202:205], v140
	ds_read_b128 v[206:209], v140 offset:1024
	ds_read_b128 v[210:213], v140 offset:2048
	ds_read_b128 v[214:217], v140 offset:3072
	s_mov_b32 m0, s13
	v_lshl_add_u64 v[140:141], v[218:219], 0, s[78:79]
	global_load_lds_dwordx4 v[140:141], off
	s_add_i32 m0, s13, 0x2000
	v_lshl_add_u64 v[140:141], v[220:221], 0, s[78:79]
	global_load_lds_dwordx4 v[140:141], off
	s_barrier
	s_waitcnt lgkmcnt(0)
	s_setprio 1
	v_mfma_f32_16x16x32_bf16 v[140:143], v[202:205], v[124:127], v[144:147]
	v_mfma_f32_16x16x32_bf16 v[112:115], v[202:205], v[156:159], v[112:115]
	v_mfma_f32_16x16x32_bf16 v[144:147], v[206:209], v[132:135], v[140:143]
	v_mfma_f32_16x16x32_bf16 v[60:63], v[210:213], v[124:127], v[60:63]
	v_mfma_f32_16x16x32_bf16 v[140:143], v[206:209], v[160:163], v[112:115]
	v_mfma_f32_16x16x32_bf16 v[112:115], v[202:205], v[164:167], v[116:119]
	v_mfma_f32_16x16x32_bf16 v[60:63], v[214:217], v[132:135], v[60:63]
	v_mfma_f32_16x16x32_bf16 v[56:59], v[210:213], v[156:159], v[56:59]
	v_mfma_f32_16x16x32_bf16 v[132:135], v[206:209], v[190:193], v[112:115]
	v_mfma_f32_16x16x32_bf16 v[36:39], v[210:213], v[164:167], v[36:39]
	v_mfma_f32_16x16x32_bf16 v[112:115], v[202:205], v[194:197], v[120:123]
	v_mfma_f32_16x16x32_bf16 v[32:35], v[210:213], v[194:197], v[32:35]
	v_mfma_f32_16x16x32_bf16 v[56:59], v[214:217], v[160:163], v[56:59]
	v_mfma_f32_16x16x32_bf16 v[36:39], v[214:217], v[190:193], v[36:39]
	v_mfma_f32_16x16x32_bf16 v[124:127], v[206:209], v[198:201], v[112:115]
	v_mfma_f32_16x16x32_bf16 v[32:35], v[214:217], v[198:201], v[32:35]
	s_setprio 0
	s_mov_b32 m0, s62
	v_lshl_add_u64 v[198:199], v[222:223], 0, s[78:79]
	s_barrier
	ds_read_b128 v[112:115], v238 offset:49152
	ds_read_b128 v[116:119], v238 offset:50176
	ds_read_b128 v[120:123], v238 offset:51200
	ds_read_b128 v[156:159], v238 offset:52224
	ds_read_b128 v[160:163], v238 offset:53248
	ds_read_b128 v[164:167], v238 offset:54272
	ds_read_b128 v[190:193], v238 offset:55296
	ds_read_b128 v[194:197], v238 offset:56320
	global_load_lds_dwordx4 v[198:199], off
	s_mov_b32 m0, s63
	v_lshl_add_u64 v[198:199], v[240:241], 0, s[78:79]
	global_load_lds_dwordx4 v[198:199], off
	s_barrier
	s_waitcnt lgkmcnt(0)
	s_setprio 1
	s_setprio 0
	s_barrier
	s_add_u32 s2, s2, 0x40080
	s_addc_u32 s3, s3, 0
	s_add_i32 s12, s12, s53
	s_mov_b32 m0, s12
	v_lshl_add_u64 v[48:49], s[2:3], 0, v[168:169]
	global_load_lds_dwordx4 v[48:49], off
	s_add_i32 m0, s12, 0x2000
	v_lshl_add_u64 v[48:49], s[2:3], 0, v[184:185]
	global_load_lds_dwordx4 v[48:49], off
	s_waitcnt vmcnt(6)
	s_barrier
	s_setprio 1
	s_setprio 0
	s_add_i32 s67, s67, 2
	s_add_u32 s10, s10, 0x100
	s_addc_u32 s11, s11, 0
	s_add_u32 s37, s37, 0x100
	s_addc_u32 s39, s39, 0
	s_cmp_gt_u32 s67, 13
	s_barrier
	s_cbranch_scc0 .Lup_half_loop
	s_branch .Lup_epi

.LBB0_1048:
	s_add_u32 s56, s2, 0x100
	s_addc_u32 s57, s3, 0
	s_mov_b32 s58, -2
	s_add_u32 s2, s24, 0x100
	s_addc_u32 s3, s25, 0
	s_add_i32 s59, 0, 0x10000
	v_add_u32_e32 v52, s59, v194
	ds_read_b128 v[40:43], v52
	ds_read_b128 v[44:47], v52 offset:1024
	ds_read_b128 v[48:51], v52 offset:2048
	ds_read_b128 v[52:55], v52 offset:3072
	s_cmp_eq_u32 s58, 40
	s_cselect_b32 s27, s1, s3
	s_cselect_b32 s26, s0, s2
	s_cselect_b32 s9, s23, s57
	s_cselect_b32 s8, s22, s56
	v_lshl_add_u64 v[190:191], s[24:25], 0, v[166:167]
	s_add_i32 m0, s37, 0xc000
	ds_read_b128 v[56:59], v195
	ds_read_b128 v[60:63], v195 offset:1024
	ds_read_b128 v[72:75], v195 offset:2048
	ds_read_b128 v[84:87], v195 offset:3072
	ds_read_b128 v[182:185], v195 offset:4096
	ds_read_b128 v[186:189], v195 offset:5120
	ds_read_b128 v[196:199], v195 offset:6144
	ds_read_b128 v[200:203], v195 offset:7168
	global_load_lds_dwordx4 v[190:191], off
	s_add_i32 m0, s37, 0xe000
	v_lshl_add_u64 v[190:191], s[24:25], 0, v[180:181]
	global_load_lds_dwordx4 v[190:191], off
	s_waitcnt lgkmcnt(8)
	s_barrier
	s_waitcnt lgkmcnt(0)
	s_setprio 1
	v_mfma_f32_16x16x32_bf16 v[156:159], v[40:43], v[56:59], 0
	v_mfma_f32_16x16x32_bf16 v[152:155], v[48:51], v[56:59], 0
	v_mfma_f32_16x16x32_bf16 v[140:143], v[40:43], v[72:75], 0
	v_mfma_f32_16x16x32_bf16 v[136:139], v[48:51], v[72:75], 0
	v_mfma_f32_16x16x32_bf16 v[124:127], v[40:43], v[182:185], 0
	v_mfma_f32_16x16x32_bf16 v[120:123], v[48:51], v[182:185], 0
	v_mfma_f32_16x16x32_bf16 v[108:111], v[40:43], v[196:199], 0
	v_mfma_f32_16x16x32_bf16 v[104:107], v[48:51], v[196:199], 0
	v_mfma_f32_16x16x32_bf16 v[156:159], v[44:47], v[60:63], v[156:159]
	v_mfma_f32_16x16x32_bf16 v[152:155], v[52:55], v[60:63], v[152:155]
	v_mfma_f32_16x16x32_bf16 v[140:143], v[44:47], v[84:87], v[140:143]
	v_mfma_f32_16x16x32_bf16 v[136:139], v[52:55], v[84:87], v[136:139]
	v_mfma_f32_16x16x32_bf16 v[124:127], v[44:47], v[186:189], v[124:127]
	v_mfma_f32_16x16x32_bf16 v[120:123], v[52:55], v[186:189], v[120:123]
	v_mfma_f32_16x16x32_bf16 v[108:111], v[44:47], v[200:203], v[108:111]
	v_mfma_f32_16x16x32_bf16 v[104:107], v[52:55], v[200:203], v[104:107]
	s_setprio 0
	s_barrier
	s_add_i32 s60, 0, 0x14000
	v_add_u32_e32 v190, s60, v194
	s_add_i32 s24, s59, s36
	ds_read_b128 v[204:207], v190
	ds_read_b128 v[208:211], v190 offset:1024
	ds_read_b128 v[212:215], v190 offset:2048
	ds_read_b128 v[216:219], v190 offset:3072
	v_lshl_add_u64 v[190:191], s[8:9], 0, v[168:169]
	s_mov_b32 m0, s24
	v_lshl_add_u64 v[240:241], s[8:9], 0, v[164:165]
	global_load_lds_dwordx4 v[190:191], off
	s_add_i32 m0, s24, 0x2000
	s_nop 0
	global_load_lds_dwordx4 v[240:241], off
	s_barrier
	s_waitcnt lgkmcnt(0)
	s_setprio 1
	v_mfma_f32_16x16x32_bf16 v[148:151], v[204:207], v[56:59], 0
	v_mfma_f32_16x16x32_bf16 v[56:59], v[212:215], v[56:59], 0
	v_mfma_f32_16x16x32_bf16 v[148:151], v[208:211], v[60:63], v[148:151]
	v_mfma_f32_16x16x32_bf16 v[56:59], v[216:219], v[60:63], v[56:59]
	v_mfma_f32_16x16x32_bf16 v[60:63], v[204:207], v[72:75], 0
	v_mfma_f32_16x16x32_bf16 v[72:75], v[212:215], v[72:75], 0
	v_mfma_f32_16x16x32_bf16 v[112:115], v[212:215], v[182:185], 0
	v_mfma_f32_16x16x32_bf16 v[100:103], v[204:207], v[196:199], 0
	v_mfma_f32_16x16x32_bf16 v[96:99], v[212:215], v[196:199], 0
	v_mfma_f32_16x16x32_bf16 v[60:63], v[208:211], v[84:87], v[60:63]
	v_mfma_f32_16x16x32_bf16 v[72:75], v[216:219], v[84:87], v[72:75]
	v_mfma_f32_16x16x32_bf16 v[84:87], v[204:207], v[182:185], 0
	v_mfma_f32_16x16x32_bf16 v[112:115], v[216:219], v[186:189], v[112:115]
	v_mfma_f32_16x16x32_bf16 v[100:103], v[208:211], v[200:203], v[100:103]
	v_mfma_f32_16x16x32_bf16 v[96:99], v[216:219], v[200:203], v[96:99]
	v_mfma_f32_16x16x32_bf16 v[84:87], v[208:211], v[186:189], v[84:87]
	s_setprio 0
	s_mov_b32 m0, s37
	v_lshl_add_u64 v[242:243], s[26:27], 0, v[160:161]
	s_barrier
	ds_read_b128 v[116:119], v195 offset:16384
	ds_read_b128 v[128:131], v195 offset:17408
	ds_read_b128 v[132:135], v195 offset:18432
	ds_read_b128 v[144:147], v195 offset:19456
	ds_read_b128 v[182:185], v195 offset:20480
	ds_read_b128 v[186:189], v195 offset:21504
	ds_read_b128 v[196:199], v195 offset:22528
	ds_read_b128 v[200:203], v195 offset:23552
	global_load_lds_dwordx4 v[242:243], off
	s_mov_b32 m0, s38
	v_lshl_add_u64 v[244:245], s[26:27], 0, v[162:163]
	global_load_lds_dwordx4 v[244:245], off
	s_barrier
	s_waitcnt lgkmcnt(0)
	s_setprio 1
	v_mfma_f32_16x16x32_bf16 v[92:95], v[40:43], v[116:119], 0
	v_mfma_f32_16x16x32_bf16 v[88:91], v[48:51], v[116:119], 0
	v_mfma_f32_16x16x32_bf16 v[68:71], v[40:43], v[132:135], 0
	v_mfma_f32_16x16x32_bf16 v[64:67], v[48:51], v[132:135], 0
	v_mfma_f32_16x16x32_bf16 v[28:31], v[40:43], v[182:185], 0
	v_mfma_f32_16x16x32_bf16 v[24:27], v[48:51], v[182:185], 0
	v_mfma_f32_16x16x32_bf16 v[12:15], v[40:43], v[196:199], 0
	v_mfma_f32_16x16x32_bf16 v[8:11], v[48:51], v[196:199], 0
	v_mfma_f32_16x16x32_bf16 v[92:95], v[44:47], v[128:131], v[92:95]
	v_mfma_f32_16x16x32_bf16 v[88:91], v[52:55], v[128:131], v[88:91]
	v_mfma_f32_16x16x32_bf16 v[68:71], v[44:47], v[144:147], v[68:71]
	v_mfma_f32_16x16x32_bf16 v[64:67], v[52:55], v[144:147], v[64:67]
	v_mfma_f32_16x16x32_bf16 v[28:31], v[44:47], v[186:189], v[28:31]
	v_mfma_f32_16x16x32_bf16 v[24:27], v[52:55], v[186:189], v[24:27]
	v_mfma_f32_16x16x32_bf16 v[12:15], v[44:47], v[200:203], v[12:15]
	v_mfma_f32_16x16x32_bf16 v[8:11], v[52:55], v[200:203], v[8:11]
	s_setprio 0
	s_barrier
	s_add_u32 s24, s8, 0xb0000
	s_addc_u32 s25, s9, 0
	s_add_i32 s59, s60, s36
	s_mov_b32 m0, s59
	v_lshl_add_u64 v[40:41], s[24:25], 0, v[168:169]
	global_load_lds_dwordx4 v[40:41], off
	s_add_i32 m0, s59, 0x2000
	v_lshl_add_u64 v[40:41], s[24:25], 0, v[164:165]
	global_load_lds_dwordx4 v[40:41], off
	s_waitcnt vmcnt(6)
	s_barrier
	s_setprio 1
	v_mfma_f32_16x16x32_bf16 v[36:39], v[204:207], v[132:135], 0
	v_mfma_f32_16x16x32_bf16 v[32:35], v[212:215], v[132:135], 0
	v_mfma_f32_16x16x32_bf16 v[20:23], v[204:207], v[182:185], 0
	v_mfma_f32_16x16x32_bf16 v[16:19], v[212:215], v[182:185], 0
	v_mfma_f32_16x16x32_bf16 v[4:7], v[204:207], v[196:199], 0
	v_mfma_f32_16x16x32_bf16 v[0:3], v[212:215], v[196:199], 0
	v_mfma_f32_16x16x32_bf16 v[40:43], v[204:207], v[116:119], 0
	v_mfma_f32_16x16x32_bf16 v[44:47], v[212:215], v[116:119], 0
	v_mfma_f32_16x16x32_bf16 v[36:39], v[208:211], v[144:147], v[36:39]
	v_mfma_f32_16x16x32_bf16 v[32:35], v[216:219], v[144:147], v[32:35]
	v_mfma_f32_16x16x32_bf16 v[20:23], v[208:211], v[186:189], v[20:23]
	v_mfma_f32_16x16x32_bf16 v[16:19], v[216:219], v[186:189], v[16:19]
	v_mfma_f32_16x16x32_bf16 v[4:7], v[208:211], v[200:203], v[4:7]
	v_mfma_f32_16x16x32_bf16 v[0:3], v[216:219], v[200:203], v[0:3]
	v_mfma_f32_16x16x32_bf16 v[40:43], v[208:211], v[128:131], v[40:43]
	v_mfma_f32_16x16x32_bf16 v[44:47], v[216:219], v[128:131], v[44:47]
	s_setprio 0
	s_add_i32 s59, 0, 0x18000
	v_add_u32_e32 v80, s59, v194
	s_barrier
	ds_read_b128 v[48:51], v80
	ds_read_b128 v[52:55], v80 offset:1024
	ds_read_b128 v[76:79], v80 offset:2048
	ds_read_b128 v[80:83], v80 offset:3072
	s_add_u32 s24, s26, 0xb0000
	s_addc_u32 s25, s27, 0
	s_mov_b32 m0, s39
	v_lshl_add_u64 v[132:133], s[24:25], 0, v[160:161]
	ds_read_b128 v[116:119], v195 offset:32768
	ds_read_b128 v[128:131], v195 offset:33792
	ds_read_b128 v[182:185], v195 offset:34816
	ds_read_b128 v[186:189], v195 offset:35840
	ds_read_b128 v[196:199], v195 offset:36864
	ds_read_b128 v[200:203], v195 offset:37888
	ds_read_b128 v[204:207], v195 offset:38912
	ds_read_b128 v[208:211], v195 offset:39936
	global_load_lds_dwordx4 v[132:133], off
	s_mov_b32 m0, s40
	v_lshl_add_u64 v[132:133], s[24:25], 0, v[162:163]
	global_load_lds_dwordx4 v[132:133], off
	s_waitcnt lgkmcnt(8)
	s_barrier
	s_waitcnt lgkmcnt(0)
	s_setprio 1
	v_mfma_f32_16x16x32_bf16 v[132:135], v[48:51], v[116:119], v[156:159]
	v_mfma_f32_16x16x32_bf16 v[156:159], v[52:55], v[128:131], v[132:135]
	v_mfma_f32_16x16x32_bf16 v[132:135], v[76:79], v[116:119], v[152:155]
	v_mfma_f32_16x16x32_bf16 v[152:155], v[80:83], v[128:131], v[132:135]
	v_mfma_f32_16x16x32_bf16 v[132:135], v[48:51], v[182:185], v[140:143]
	v_mfma_f32_16x16x32_bf16 v[140:143], v[52:55], v[186:189], v[132:135]
	v_mfma_f32_16x16x32_bf16 v[132:135], v[76:79], v[182:185], v[136:139]
	v_mfma_f32_16x16x32_bf16 v[124:127], v[48:51], v[196:199], v[124:127]
	v_mfma_f32_16x16x32_bf16 v[120:123], v[76:79], v[196:199], v[120:123]
	v_mfma_f32_16x16x32_bf16 v[108:111], v[48:51], v[204:207], v[108:111]
	v_mfma_f32_16x16x32_bf16 v[104:107], v[76:79], v[204:207], v[104:107]
	v_mfma_f32_16x16x32_bf16 v[136:139], v[80:83], v[186:189], v[132:135]
	v_mfma_f32_16x16x32_bf16 v[124:127], v[52:55], v[200:203], v[124:127]
	v_mfma_f32_16x16x32_bf16 v[120:123], v[80:83], v[200:203], v[120:123]
	v_mfma_f32_16x16x32_bf16 v[108:111], v[52:55], v[208:211], v[108:111]
	v_mfma_f32_16x16x32_bf16 v[104:107], v[80:83], v[208:211], v[104:107]
	s_setprio 0
	s_barrier
	s_add_i32 s24, 0, 0x1c000
	v_add_u32_e32 v132, s24, v194
	s_add_i32 s25, s59, s36
	ds_read_b128 v[212:215], v132
	ds_read_b128 v[216:219], v132 offset:1024
	ds_read_b128 v[220:223], v132 offset:2048
	ds_read_b128 v[236:239], v132 offset:3072
	s_mov_b32 m0, s25
	v_lshl_add_u64 v[132:133], v[190:191], 0, s[78:79]
	global_load_lds_dwordx4 v[132:133], off
	s_add_i32 m0, s25, 0x2000
	v_lshl_add_u64 v[132:133], v[240:241], 0, s[78:79]
	global_load_lds_dwordx4 v[132:133], off
	s_barrier
	s_waitcnt lgkmcnt(0)
	s_setprio 1
	v_mfma_f32_16x16x32_bf16 v[56:59], v[220:223], v[116:119], v[56:59]
	v_mfma_f32_16x16x32_bf16 v[132:135], v[212:215], v[116:119], v[148:151]
	v_mfma_f32_16x16x32_bf16 v[144:147], v[236:239], v[128:131], v[56:59]
	v_mfma_f32_16x16x32_bf16 v[56:59], v[212:215], v[182:185], v[60:63]
	v_mfma_f32_16x16x32_bf16 v[148:151], v[216:219], v[128:131], v[132:135]
	v_mfma_f32_16x16x32_bf16 v[132:135], v[216:219], v[186:189], v[56:59]
	v_mfma_f32_16x16x32_bf16 v[56:59], v[220:223], v[182:185], v[72:75]
	v_mfma_f32_16x16x32_bf16 v[128:131], v[236:239], v[186:189], v[56:59]
	v_mfma_f32_16x16x32_bf16 v[56:59], v[212:215], v[196:199], v[84:87]
	v_mfma_f32_16x16x32_bf16 v[116:119], v[216:219], v[200:203], v[56:59]
	v_mfma_f32_16x16x32_bf16 v[56:59], v[220:223], v[196:199], v[112:115]
	v_mfma_f32_16x16x32_bf16 v[112:115], v[236:239], v[200:203], v[56:59]
	v_mfma_f32_16x16x32_bf16 v[56:59], v[212:215], v[204:207], v[100:103]
	v_mfma_f32_16x16x32_bf16 v[100:103], v[216:219], v[208:211], v[56:59]
	v_mfma_f32_16x16x32_bf16 v[56:59], v[220:223], v[204:207], v[96:99]
	v_mfma_f32_16x16x32_bf16 v[96:99], v[236:239], v[208:211], v[56:59]
	s_setprio 0
	s_mov_b32 m0, s47
	v_lshl_add_u64 v[190:191], v[242:243], 0, s[78:79]
	s_barrier
	s_nop 2
	ds_read_b128 v[56:59], v195 offset:49152
	ds_read_b128 v[60:63], v195 offset:50176
	ds_read_b128 v[72:75], v195 offset:51200
	ds_read_b128 v[84:87], v195 offset:52224
	ds_read_b128 v[182:185], v195 offset:53248
	ds_read_b128 v[186:189], v195 offset:54272
	ds_read_b128 v[196:199], v195 offset:55296
	ds_read_b128 v[200:203], v195 offset:56320
	global_load_lds_dwordx4 v[190:191], off
	s_mov_b32 m0, s49
	v_lshl_add_u64 v[190:191], v[244:245], 0, s[78:79]
	global_load_lds_dwordx4 v[190:191], off
	s_barrier
	s_waitcnt lgkmcnt(0)
	s_setprio 1
	v_mfma_f32_16x16x32_bf16 v[92:95], v[48:51], v[56:59], v[92:95]
	v_mfma_f32_16x16x32_bf16 v[88:91], v[76:79], v[56:59], v[88:91]
	v_mfma_f32_16x16x32_bf16 v[68:71], v[48:51], v[72:75], v[68:71]
	v_mfma_f32_16x16x32_bf16 v[64:67], v[76:79], v[72:75], v[64:67]
	v_mfma_f32_16x16x32_bf16 v[28:31], v[48:51], v[182:185], v[28:31]
	v_mfma_f32_16x16x32_bf16 v[24:27], v[76:79], v[182:185], v[24:27]
	v_mfma_f32_16x16x32_bf16 v[12:15], v[48:51], v[196:199], v[12:15]
	v_mfma_f32_16x16x32_bf16 v[8:11], v[76:79], v[196:199], v[8:11]
	v_mfma_f32_16x16x32_bf16 v[92:95], v[52:55], v[60:63], v[92:95]
	v_mfma_f32_16x16x32_bf16 v[88:91], v[80:83], v[60:63], v[88:91]
	v_mfma_f32_16x16x32_bf16 v[68:71], v[52:55], v[84:87], v[68:71]
	v_mfma_f32_16x16x32_bf16 v[64:67], v[80:83], v[84:87], v[64:67]
	v_mfma_f32_16x16x32_bf16 v[28:31], v[52:55], v[186:189], v[28:31]
	v_mfma_f32_16x16x32_bf16 v[24:27], v[80:83], v[186:189], v[24:27]
	v_mfma_f32_16x16x32_bf16 v[12:15], v[52:55], v[200:203], v[12:15]
	v_mfma_f32_16x16x32_bf16 v[8:11], v[80:83], v[200:203], v[8:11]
	s_setprio 0
	s_barrier
	s_add_u32 s8, s8, 0xb0080
	s_addc_u32 s9, s9, 0
	s_add_i32 s24, s24, s36
	s_mov_b32 m0, s24
	v_lshl_add_u64 v[48:49], s[8:9], 0, v[168:169]
	global_load_lds_dwordx4 v[48:49], off
	s_add_i32 m0, s24, 0x2000
	v_lshl_add_u64 v[48:49], s[8:9], 0, v[164:165]
	global_load_lds_dwordx4 v[48:49], off
	s_waitcnt vmcnt(6)
	s_barrier
	s_setprio 1
	v_mfma_f32_16x16x32_bf16 v[40:43], v[212:215], v[56:59], v[40:43]
	v_mfma_f32_16x16x32_bf16 v[80:83], v[216:219], v[60:63], v[40:43]
	v_mfma_f32_16x16x32_bf16 v[40:43], v[220:223], v[56:59], v[44:47]
	v_mfma_f32_16x16x32_bf16 v[36:39], v[212:215], v[72:75], v[36:39]
	v_mfma_f32_16x16x32_bf16 v[32:35], v[220:223], v[72:75], v[32:35]
	v_mfma_f32_16x16x32_bf16 v[20:23], v[212:215], v[182:185], v[20:23]
	v_mfma_f32_16x16x32_bf16 v[16:19], v[220:223], v[182:185], v[16:19]
	v_mfma_f32_16x16x32_bf16 v[4:7], v[212:215], v[196:199], v[4:7]
	v_mfma_f32_16x16x32_bf16 v[0:3], v[220:223], v[196:199], v[0:3]
	v_mfma_f32_16x16x32_bf16 v[76:79], v[236:239], v[60:63], v[40:43]
	v_mfma_f32_16x16x32_bf16 v[36:39], v[216:219], v[84:87], v[36:39]
	v_mfma_f32_16x16x32_bf16 v[32:35], v[236:239], v[84:87], v[32:35]
	v_mfma_f32_16x16x32_bf16 v[20:23], v[216:219], v[186:189], v[20:23]
	v_mfma_f32_16x16x32_bf16 v[16:19], v[236:239], v[186:189], v[16:19]
	v_mfma_f32_16x16x32_bf16 v[4:7], v[216:219], v[200:203], v[4:7]
	v_mfma_f32_16x16x32_bf16 v[0:3], v[236:239], v[200:203], v[0:3]
	s_setprio 0
	s_add_i32 s58, s58, 2
	s_add_u32 s56, s56, 0x100
	s_addc_u32 s57, s57, 0
	s_cmp_gt_u32 s58, 41
	s_mov_b64 s[24:25], s[2:3]
	s_barrier
.LBB0_1049:
	s_add_u32 s2, s24, 0x100
	s_addc_u32 s3, s25, 0
	s_add_i32 s59, 0, 0x10000
	v_add_u32_e32 v52, s59, v194
	ds_read_b128 v[40:43], v52
	ds_read_b128 v[44:47], v52 offset:1024
	ds_read_b128 v[48:51], v52 offset:2048
	ds_read_b128 v[52:55], v52 offset:3072
	s_cmp_eq_u32 s58, 40
	s_cselect_b32 s27, s1, s3
	s_cselect_b32 s26, s0, s2
	s_cselect_b32 s9, s23, s57
	s_cselect_b32 s8, s22, s56
	v_lshl_add_u64 v[190:191], s[24:25], 0, v[166:167]
	s_add_i32 m0, s37, 0xc000
	ds_read_b128 v[56:59], v195
	ds_read_b128 v[60:63], v195 offset:1024
	ds_read_b128 v[72:75], v195 offset:2048
	ds_read_b128 v[84:87], v195 offset:3072
	ds_read_b128 v[182:185], v195 offset:4096
	ds_read_b128 v[186:189], v195 offset:5120
	ds_read_b128 v[196:199], v195 offset:6144
	ds_read_b128 v[200:203], v195 offset:7168
	global_load_lds_dwordx4 v[190:191], off
	s_add_i32 m0, s37, 0xe000
	v_lshl_add_u64 v[190:191], s[24:25], 0, v[180:181]
	global_load_lds_dwordx4 v[190:191], off
	s_waitcnt lgkmcnt(8)
	s_barrier
	s_waitcnt lgkmcnt(0)
	s_setprio 1
	v_mfma_f32_16x16x32_bf16 v[156:159], v[40:43], v[56:59], v[156:159]
	v_mfma_f32_16x16x32_bf16 v[152:155], v[48:51], v[56:59], v[152:155]
	v_mfma_f32_16x16x32_bf16 v[140:143], v[40:43], v[72:75], v[140:143]
	v_mfma_f32_16x16x32_bf16 v[136:139], v[48:51], v[72:75], v[136:139]
	v_mfma_f32_16x16x32_bf16 v[124:127], v[40:43], v[182:185], v[124:127]
	v_mfma_f32_16x16x32_bf16 v[120:123], v[48:51], v[182:185], v[120:123]
	v_mfma_f32_16x16x32_bf16 v[108:111], v[40:43], v[196:199], v[108:111]
	v_mfma_f32_16x16x32_bf16 v[104:107], v[48:51], v[196:199], v[104:107]
	v_mfma_f32_16x16x32_bf16 v[156:159], v[44:47], v[60:63], v[156:159]
	v_mfma_f32_16x16x32_bf16 v[152:155], v[52:55], v[60:63], v[152:155]
	v_mfma_f32_16x16x32_bf16 v[140:143], v[44:47], v[84:87], v[140:143]
	v_mfma_f32_16x16x32_bf16 v[136:139], v[52:55], v[84:87], v[136:139]
	v_mfma_f32_16x16x32_bf16 v[124:127], v[44:47], v[186:189], v[124:127]
	v_mfma_f32_16x16x32_bf16 v[120:123], v[52:55], v[186:189], v[120:123]
	v_mfma_f32_16x16x32_bf16 v[108:111], v[44:47], v[200:203], v[108:111]
	v_mfma_f32_16x16x32_bf16 v[104:107], v[52:55], v[200:203], v[104:107]
	s_setprio 0
	s_barrier
	s_add_i32 s60, 0, 0x14000
	v_add_u32_e32 v190, s60, v194
	s_add_i32 s24, s59, s36
	ds_read_b128 v[204:207], v190
	ds_read_b128 v[208:211], v190 offset:1024
	ds_read_b128 v[212:215], v190 offset:2048
	ds_read_b128 v[216:219], v190 offset:3072
	v_lshl_add_u64 v[190:191], s[8:9], 0, v[168:169]
	s_mov_b32 m0, s24
	v_lshl_add_u64 v[240:241], s[8:9], 0, v[164:165]
	global_load_lds_dwordx4 v[190:191], off
	s_add_i32 m0, s24, 0x2000
	s_nop 0
	global_load_lds_dwordx4 v[240:241], off
	s_barrier
	s_waitcnt lgkmcnt(0)
	s_setprio 1
	v_mfma_f32_16x16x32_bf16 v[148:151], v[204:207], v[56:59], v[148:151]
	v_mfma_f32_16x16x32_bf16 v[56:59], v[212:215], v[56:59], v[144:147]
	v_mfma_f32_16x16x32_bf16 v[148:151], v[208:211], v[60:63], v[148:151]
	v_mfma_f32_16x16x32_bf16 v[56:59], v[216:219], v[60:63], v[56:59]
	v_mfma_f32_16x16x32_bf16 v[60:63], v[204:207], v[72:75], v[132:135]
	v_mfma_f32_16x16x32_bf16 v[72:75], v[212:215], v[72:75], v[128:131]
	v_mfma_f32_16x16x32_bf16 v[112:115], v[212:215], v[182:185], v[112:115]
	v_mfma_f32_16x16x32_bf16 v[100:103], v[204:207], v[196:199], v[100:103]
	v_mfma_f32_16x16x32_bf16 v[96:99], v[212:215], v[196:199], v[96:99]
	v_mfma_f32_16x16x32_bf16 v[60:63], v[208:211], v[84:87], v[60:63]
	v_mfma_f32_16x16x32_bf16 v[72:75], v[216:219], v[84:87], v[72:75]
	v_mfma_f32_16x16x32_bf16 v[84:87], v[204:207], v[182:185], v[116:119]
	v_mfma_f32_16x16x32_bf16 v[112:115], v[216:219], v[186:189], v[112:115]
	v_mfma_f32_16x16x32_bf16 v[100:103], v[208:211], v[200:203], v[100:103]
	v_mfma_f32_16x16x32_bf16 v[96:99], v[216:219], v[200:203], v[96:99]
	v_mfma_f32_16x16x32_bf16 v[84:87], v[208:211], v[186:189], v[84:87]
	s_setprio 0
	s_mov_b32 m0, s37
	v_lshl_add_u64 v[242:243], s[26:27], 0, v[160:161]
	s_barrier
	ds_read_b128 v[116:119], v195 offset:16384
	ds_read_b128 v[128:131], v195 offset:17408
	ds_read_b128 v[132:135], v195 offset:18432
	ds_read_b128 v[144:147], v195 offset:19456
	ds_read_b128 v[182:185], v195 offset:20480
	ds_read_b128 v[186:189], v195 offset:21504
	ds_read_b128 v[196:199], v195 offset:22528
	ds_read_b128 v[200:203], v195 offset:23552
	global_load_lds_dwordx4 v[242:243], off
	s_mov_b32 m0, s38
	v_lshl_add_u64 v[244:245], s[26:27], 0, v[162:163]
	global_load_lds_dwordx4 v[244:245], off
	s_barrier
	s_waitcnt lgkmcnt(0)
	s_setprio 1
	v_mfma_f32_16x16x32_bf16 v[92:95], v[40:43], v[116:119], v[92:95]
	v_mfma_f32_16x16x32_bf16 v[88:91], v[48:51], v[116:119], v[88:91]
	v_mfma_f32_16x16x32_bf16 v[68:71], v[40:43], v[132:135], v[68:71]
	v_mfma_f32_16x16x32_bf16 v[64:67], v[48:51], v[132:135], v[64:67]
	v_mfma_f32_16x16x32_bf16 v[28:31], v[40:43], v[182:185], v[28:31]
	v_mfma_f32_16x16x32_bf16 v[24:27], v[48:51], v[182:185], v[24:27]
	v_mfma_f32_16x16x32_bf16 v[12:15], v[40:43], v[196:199], v[12:15]
	v_mfma_f32_16x16x32_bf16 v[8:11], v[48:51], v[196:199], v[8:11]
	v_mfma_f32_16x16x32_bf16 v[92:95], v[44:47], v[128:131], v[92:95]
	v_mfma_f32_16x16x32_bf16 v[88:91], v[52:55], v[128:131], v[88:91]
	v_mfma_f32_16x16x32_bf16 v[68:71], v[44:47], v[144:147], v[68:71]
	v_mfma_f32_16x16x32_bf16 v[64:67], v[52:55], v[144:147], v[64:67]
	v_mfma_f32_16x16x32_bf16 v[28:31], v[44:47], v[186:189], v[28:31]
	v_mfma_f32_16x16x32_bf16 v[24:27], v[52:55], v[186:189], v[24:27]
	v_mfma_f32_16x16x32_bf16 v[12:15], v[44:47], v[200:203], v[12:15]
	v_mfma_f32_16x16x32_bf16 v[8:11], v[52:55], v[200:203], v[8:11]
	s_setprio 0
	s_barrier
	s_add_u32 s24, s8, 0xb0000
	s_addc_u32 s25, s9, 0
	s_add_i32 s59, s60, s36
	s_mov_b32 m0, s59
	v_lshl_add_u64 v[40:41], s[24:25], 0, v[168:169]
	global_load_lds_dwordx4 v[40:41], off
	s_add_i32 m0, s59, 0x2000
	v_lshl_add_u64 v[40:41], s[24:25], 0, v[164:165]
	global_load_lds_dwordx4 v[40:41], off
	s_waitcnt vmcnt(6)
	s_barrier
	s_setprio 1
	v_mfma_f32_16x16x32_bf16 v[36:39], v[204:207], v[132:135], v[36:39]
	v_mfma_f32_16x16x32_bf16 v[32:35], v[212:215], v[132:135], v[32:35]
	v_mfma_f32_16x16x32_bf16 v[20:23], v[204:207], v[182:185], v[20:23]
	v_mfma_f32_16x16x32_bf16 v[16:19], v[212:215], v[182:185], v[16:19]
	v_mfma_f32_16x16x32_bf16 v[4:7], v[204:207], v[196:199], v[4:7]
	v_mfma_f32_16x16x32_bf16 v[0:3], v[212:215], v[196:199], v[0:3]
	v_mfma_f32_16x16x32_bf16 v[40:43], v[204:207], v[116:119], v[80:83]
	v_mfma_f32_16x16x32_bf16 v[44:47], v[212:215], v[116:119], v[76:79]
	v_mfma_f32_16x16x32_bf16 v[36:39], v[208:211], v[144:147], v[36:39]
	v_mfma_f32_16x16x32_bf16 v[32:35], v[216:219], v[144:147], v[32:35]
	v_mfma_f32_16x16x32_bf16 v[20:23], v[208:211], v[186:189], v[20:23]
	v_mfma_f32_16x16x32_bf16 v[16:19], v[216:219], v[186:189], v[16:19]
	v_mfma_f32_16x16x32_bf16 v[4:7], v[208:211], v[200:203], v[4:7]
	v_mfma_f32_16x16x32_bf16 v[0:3], v[216:219], v[200:203], v[0:3]
	v_mfma_f32_16x16x32_bf16 v[40:43], v[208:211], v[128:131], v[40:43]
	v_mfma_f32_16x16x32_bf16 v[44:47], v[216:219], v[128:131], v[44:47]
	s_setprio 0
	s_add_i32 s59, 0, 0x18000
	v_add_u32_e32 v80, s59, v194
	s_barrier
	ds_read_b128 v[48:51], v80
	ds_read_b128 v[52:55], v80 offset:1024
	ds_read_b128 v[76:79], v80 offset:2048
	ds_read_b128 v[80:83], v80 offset:3072
	s_add_u32 s24, s26, 0xb0000
	s_addc_u32 s25, s27, 0
	s_mov_b32 m0, s39
	v_lshl_add_u64 v[132:133], s[24:25], 0, v[160:161]
	ds_read_b128 v[116:119], v195 offset:32768
	ds_read_b128 v[128:131], v195 offset:33792
	ds_read_b128 v[182:185], v195 offset:34816
	ds_read_b128 v[186:189], v195 offset:35840
	ds_read_b128 v[196:199], v195 offset:36864
	ds_read_b128 v[200:203], v195 offset:37888
	ds_read_b128 v[204:207], v195 offset:38912
	ds_read_b128 v[208:211], v195 offset:39936
	global_load_lds_dwordx4 v[132:133], off
	s_mov_b32 m0, s40
	v_lshl_add_u64 v[132:133], s[24:25], 0, v[162:163]
	global_load_lds_dwordx4 v[132:133], off
	s_waitcnt lgkmcnt(8)
	s_barrier
	s_waitcnt lgkmcnt(0)
	s_setprio 1
	v_mfma_f32_16x16x32_bf16 v[132:135], v[48:51], v[116:119], v[156:159]
	v_mfma_f32_16x16x32_bf16 v[156:159], v[52:55], v[128:131], v[132:135]
	v_mfma_f32_16x16x32_bf16 v[132:135], v[76:79], v[116:119], v[152:155]
	v_mfma_f32_16x16x32_bf16 v[152:155], v[80:83], v[128:131], v[132:135]
	v_mfma_f32_16x16x32_bf16 v[132:135], v[48:51], v[182:185], v[140:143]
	v_mfma_f32_16x16x32_bf16 v[140:143], v[52:55], v[186:189], v[132:135]
	v_mfma_f32_16x16x32_bf16 v[132:135], v[76:79], v[182:185], v[136:139]
	v_mfma_f32_16x16x32_bf16 v[124:127], v[48:51], v[196:199], v[124:127]
	v_mfma_f32_16x16x32_bf16 v[120:123], v[76:79], v[196:199], v[120:123]
	v_mfma_f32_16x16x32_bf16 v[108:111], v[48:51], v[204:207], v[108:111]
	v_mfma_f32_16x16x32_bf16 v[104:107], v[76:79], v[204:207], v[104:107]
	v_mfma_f32_16x16x32_bf16 v[136:139], v[80:83], v[186:189], v[132:135]
	v_mfma_f32_16x16x32_bf16 v[124:127], v[52:55], v[200:203], v[124:127]
	v_mfma_f32_16x16x32_bf16 v[120:123], v[80:83], v[200:203], v[120:123]
	v_mfma_f32_16x16x32_bf16 v[108:111], v[52:55], v[208:211], v[108:111]
	v_mfma_f32_16x16x32_bf16 v[104:107], v[80:83], v[208:211], v[104:107]
	s_setprio 0
	s_barrier
	s_add_i32 s24, 0, 0x1c000
	v_add_u32_e32 v132, s24, v194
	s_add_i32 s25, s59, s36
	ds_read_b128 v[212:215], v132
	ds_read_b128 v[216:219], v132 offset:1024
	ds_read_b128 v[220:223], v132 offset:2048
	ds_read_b128 v[236:239], v132 offset:3072
	s_mov_b32 m0, s25
	v_lshl_add_u64 v[132:133], v[190:191], 0, s[78:79]
	global_load_lds_dwordx4 v[132:133], off
	s_add_i32 m0, s25, 0x2000
	v_lshl_add_u64 v[132:133], v[240:241], 0, s[78:79]
	global_load_lds_dwordx4 v[132:133], off
	s_barrier
	s_waitcnt lgkmcnt(0)
	s_setprio 1
	v_mfma_f32_16x16x32_bf16 v[56:59], v[220:223], v[116:119], v[56:59]
	v_mfma_f32_16x16x32_bf16 v[132:135], v[212:215], v[116:119], v[148:151]
	v_mfma_f32_16x16x32_bf16 v[144:147], v[236:239], v[128:131], v[56:59]
	v_mfma_f32_16x16x32_bf16 v[56:59], v[212:215], v[182:185], v[60:63]
	v_mfma_f32_16x16x32_bf16 v[148:151], v[216:219], v[128:131], v[132:135]
	v_mfma_f32_16x16x32_bf16 v[132:135], v[216:219], v[186:189], v[56:59]
	v_mfma_f32_16x16x32_bf16 v[56:59], v[220:223], v[182:185], v[72:75]
	v_mfma_f32_16x16x32_bf16 v[128:131], v[236:239], v[186:189], v[56:59]
	v_mfma_f32_16x16x32_bf16 v[56:59], v[212:215], v[196:199], v[84:87]
	v_mfma_f32_16x16x32_bf16 v[116:119], v[216:219], v[200:203], v[56:59]
	v_mfma_f32_16x16x32_bf16 v[56:59], v[220:223], v[196:199], v[112:115]
	v_mfma_f32_16x16x32_bf16 v[112:115], v[236:239], v[200:203], v[56:59]
	v_mfma_f32_16x16x32_bf16 v[56:59], v[212:215], v[204:207], v[100:103]
	v_mfma_f32_16x16x32_bf16 v[100:103], v[216:219], v[208:211], v[56:59]
	v_mfma_f32_16x16x32_bf16 v[56:59], v[220:223], v[204:207], v[96:99]
	v_mfma_f32_16x16x32_bf16 v[96:99], v[236:239], v[208:211], v[56:59]
	s_setprio 0
	s_mov_b32 m0, s47
	v_lshl_add_u64 v[190:191], v[242:243], 0, s[78:79]
	s_barrier
	s_nop 2
	ds_read_b128 v[56:59], v195 offset:49152
	ds_read_b128 v[60:63], v195 offset:50176
	ds_read_b128 v[72:75], v195 offset:51200
	ds_read_b128 v[84:87], v195 offset:52224
	ds_read_b128 v[182:185], v195 offset:53248
	ds_read_b128 v[186:189], v195 offset:54272
	ds_read_b128 v[196:199], v195 offset:55296
	ds_read_b128 v[200:203], v195 offset:56320
	global_load_lds_dwordx4 v[190:191], off
	s_mov_b32 m0, s49
	v_lshl_add_u64 v[190:191], v[244:245], 0, s[78:79]
	global_load_lds_dwordx4 v[190:191], off
	s_barrier
	s_waitcnt lgkmcnt(0)
	s_setprio 1
	v_mfma_f32_16x16x32_bf16 v[92:95], v[48:51], v[56:59], v[92:95]
	v_mfma_f32_16x16x32_bf16 v[88:91], v[76:79], v[56:59], v[88:91]
	v_mfma_f32_16x16x32_bf16 v[68:71], v[48:51], v[72:75], v[68:71]
	v_mfma_f32_16x16x32_bf16 v[64:67], v[76:79], v[72:75], v[64:67]
	v_mfma_f32_16x16x32_bf16 v[28:31], v[48:51], v[182:185], v[28:31]
	v_mfma_f32_16x16x32_bf16 v[24:27], v[76:79], v[182:185], v[24:27]
	v_mfma_f32_16x16x32_bf16 v[12:15], v[48:51], v[196:199], v[12:15]
	v_mfma_f32_16x16x32_bf16 v[8:11], v[76:79], v[196:199], v[8:11]
	v_mfma_f32_16x16x32_bf16 v[92:95], v[52:55], v[60:63], v[92:95]
	v_mfma_f32_16x16x32_bf16 v[88:91], v[80:83], v[60:63], v[88:91]
	v_mfma_f32_16x16x32_bf16 v[68:71], v[52:55], v[84:87], v[68:71]
	v_mfma_f32_16x16x32_bf16 v[64:67], v[80:83], v[84:87], v[64:67]
	v_mfma_f32_16x16x32_bf16 v[28:31], v[52:55], v[186:189], v[28:31]
	v_mfma_f32_16x16x32_bf16 v[24:27], v[80:83], v[186:189], v[24:27]
	v_mfma_f32_16x16x32_bf16 v[12:15], v[52:55], v[200:203], v[12:15]
	v_mfma_f32_16x16x32_bf16 v[8:11], v[80:83], v[200:203], v[8:11]
	s_setprio 0
	s_barrier
	s_add_u32 s8, s8, 0xb0080
	s_addc_u32 s9, s9, 0
	s_add_i32 s24, s24, s36
	s_mov_b32 m0, s24
	v_lshl_add_u64 v[48:49], s[8:9], 0, v[168:169]
	global_load_lds_dwordx4 v[48:49], off
	s_add_i32 m0, s24, 0x2000
	v_lshl_add_u64 v[48:49], s[8:9], 0, v[164:165]
	global_load_lds_dwordx4 v[48:49], off
	s_waitcnt vmcnt(6)
	s_barrier
	s_setprio 1
	v_mfma_f32_16x16x32_bf16 v[40:43], v[212:215], v[56:59], v[40:43]
	v_mfma_f32_16x16x32_bf16 v[80:83], v[216:219], v[60:63], v[40:43]
	v_mfma_f32_16x16x32_bf16 v[40:43], v[220:223], v[56:59], v[44:47]
	v_mfma_f32_16x16x32_bf16 v[36:39], v[212:215], v[72:75], v[36:39]
	v_mfma_f32_16x16x32_bf16 v[32:35], v[220:223], v[72:75], v[32:35]
	v_mfma_f32_16x16x32_bf16 v[20:23], v[212:215], v[182:185], v[20:23]
	v_mfma_f32_16x16x32_bf16 v[16:19], v[220:223], v[182:185], v[16:19]
	v_mfma_f32_16x16x32_bf16 v[4:7], v[212:215], v[196:199], v[4:7]
	v_mfma_f32_16x16x32_bf16 v[0:3], v[220:223], v[196:199], v[0:3]
	v_mfma_f32_16x16x32_bf16 v[76:79], v[236:239], v[60:63], v[40:43]
	v_mfma_f32_16x16x32_bf16 v[36:39], v[216:219], v[84:87], v[36:39]
	v_mfma_f32_16x16x32_bf16 v[32:35], v[236:239], v[84:87], v[32:35]
	v_mfma_f32_16x16x32_bf16 v[20:23], v[216:219], v[186:189], v[20:23]
	v_mfma_f32_16x16x32_bf16 v[16:19], v[236:239], v[186:189], v[16:19]
	v_mfma_f32_16x16x32_bf16 v[4:7], v[216:219], v[200:203], v[4:7]
	v_mfma_f32_16x16x32_bf16 v[0:3], v[236:239], v[200:203], v[0:3]
	s_setprio 0
	s_add_i32 s58, s58, 2
	s_add_u32 s56, s56, 0x100
	s_addc_u32 s57, s57, 0
	s_cmp_gt_u32 s58, 41
	s_mov_b64 s[24:25], s[2:3]
	s_barrier
	s_cbranch_scc0 .LBB0_1049
	s_lshl_b32 s2, s55, 8
	v_mov_b32_e32 v186, v193
	v_mov_b32_e32 v196, v192
	s_or_b32 s2, s2, s46
	v_mov_b32_e32 v52, 0
	v_lshl_add_u32 v182, v196, 3, s2
	s_add_i32 s2, s54, -16
	s_lshr_b32 s2, s2, 3
	s_add_i32 s2, s2, 1
	s_cmp_gt_i32 s54, 15
	s_cselect_b32 s8, s2, 0
	s_mul_i32 s96, s8, 0x1800
	s_lshl_b64 s[2:3], s[96:97], 2
	s_add_u32 s2, s41, s2
	v_ashrrev_i32_e32 v183, 31, v182
	s_addc_u32 s3, s42, s3
	v_lshlrev_b64 v[40:41], 2, v[182:183]
	v_lshl_add_u64 v[42:43], s[2:3], 0, v[40:41]
	global_load_dwordx4 v[72:75], v[42:43], off
	s_lshl_b32 s96, s8, 10
	s_lshl_b64 s[2:3], s[96:97], 2
	s_add_u32 s2, s43, s2
	s_addc_u32 s3, s44, s3
	v_lshl_add_u64 v[184:185], s[2:3], 0, v[40:41]
	s_and_b64 vcc, exec, s[4:5]
	v_mov_b32_e32 v60, 0
	v_mov_b32_e32 v61, v52
	v_mov_b32_e32 v62, 0
	v_mov_b32_e32 v63, 0
	s_cbranch_vccnz .LBB0_1052
	global_load_dwordx4 v[60:63], v[184:185], off
